# v36 + section 7.11 back-edge rotation: K-loop counter/pointer SALU block hoisted from after the bottom barrier into the last MFMA block (8 loops)
# baseline (speedup 1.0000x reference)
; #define PG8_STAGE(bufoff, gbase, voff) do { _Pragma("unroll") for (int _i = 0; _i < 2; ++_i) { unsigned keep_; \
;         asm volatile("s_mov_b32 %0, m0\n\ts_mov_b32 m0, %3\n\ts_nop 0\n\tglobal_load_lds_dwordx4 %1, %2\n\ts_mov_b32 m0, %0" \
;             : "=&s"(keep_) : "v"((voff)[_i]), "s"((const void*)(gbase)), "s"(ldsb0 + (unsigned)(bufoff) + (unsigned)(_i * 8192)) : "memory"); } } while (0)
; #define PG8_LDA(dst, b, h) do { _Pragma("unroll") for (int m = 0; m < 4; ++m) _Pragma("unroll") for (int k = 0; k < 2; ++k) dst[m][k] = *(const LAS bf16x8*)(lds + PG8_SA(b, h) + aoff + m * 2048 + k * 1024); } while (0)
; #define PG8_LDB(dst, b, h) do { _Pragma("unroll") for (int n = 0; n < 2; ++n) _Pragma("unroll") for (int k = 0; k < 2; ++k) dst[n][k] = *(const LAS bf16x8*)(lds + PG8_SB(b, h) + boff + n * 2048 + k * 1024); } while (0)
; template <class Epi, class Sched, bool ALIGN_EPI>
; __device__ __forceinline__ void gemm_phase(LAS unsigned char* lds, const Gemm g, const Sched& S, const Epi& E) {
;     ...
;         for (int t = 0; t < nt; t += 2) {
;             const bool last = (t == nt - 2);
;             const char* a1 = cA + (size_t)(t + 1) * kstep;
;             const char* a2 = last ? nA : cA + (size_t)(t + 2) * kstep; const char* b2 = last ? nB : cB + (size_t)(t + 2) * kstep;
;             const char* a3 = a2 + kstep; const char* b3 = b2 + kstep;
;             PG8_LDB(B0, 0, 0); PG8_LDB(B1, 0, 1); PG8_SCHED; PG8_LDA(At, 0, 0); PG8_STAGE(PG8_SA(1, 1), a1 + hstepA, voffA);
;             PG8_WAIT_V(8); PG8_WAIT_L(0); PG8_BAR; PG8_MMA(0, 0, At, B0); PG8_MMA(0, 1, At, B1); PG8_BAR; PG8_SCHED;
;             PG8_LDA(At, 0, 1); PG8_STAGE(PG8_SB(0, 0), b2, voffB); PG8_STAGE(PG8_SB(0, 1), b2 + hstepB, voffB); PG8_STAGE(PG8_SA(0, 0), a2, voffA);
;             PG8_WAIT_V(8); PG8_WAIT_L(0); PG8_BAR; PG8_MMA(1, 0, At, B0); PG8_MMA(1, 1, At, B1); PG8_BAR; PG8_SCHED;
;             PG8_LDB(B0, 1, 0); PG8_LDB(B1, 1, 1); PG8_SCHED; PG8_LDA(At, 1, 0); PG8_STAGE(PG8_SA(0, 1), a2 + hstepA, voffA);
;             PG8_WAIT_V(8); PG8_WAIT_L(0); PG8_BAR; PG8_MMA(0, 0, At, B0); PG8_MMA(0, 1, At, B1); PG8_BAR; PG8_SCHED;
;             PG8_LDA(At, 1, 1); PG8_STAGE(PG8_SB(1, 0), b3, voffB); PG8_STAGE(PG8_SB(1, 1), b3 + hstepB, voffB); PG8_STAGE(PG8_SA(1, 0), a3, voffA);
;             PG8_WAIT_V(8); PG8_WAIT_L(0); PG8_BAR; PG8_MMA(1, 0, At, B0); PG8_MMA(1, 1, At, B1); PG8_BAR; PG8_SCHED;
.LBB0_113:
	ds_read_b128 v[136:139], v157
	ds_read_b128 v[140:143], v157 offset:1024
	ds_read_b128 v[144:147], v157 offset:2048
	ds_read_b128 v[172:175], v157 offset:3072
	ds_read_b128 v[180:183], v158
	ds_read_b128 v[184:187], v158 offset:1024
	ds_read_b128 v[188:191], v158 offset:2048
	ds_read_b128 v[192:195], v158 offset:3072
	s_add_u32 s6, s4, 0x100
	s_addc_u32 s7, s5, 0
	s_cmp_eq_u32 s81, 28
	s_cselect_b32 s50, s39, s6
	s_cselect_b32 s51, s24, s7
	s_cselect_b32 s48, s58, s59
	s_cselect_b32 s49, s41, s80
	s_add_u32 s8, s50, 0x80
	s_addc_u32 s9, s51, 0
	ds_read_b128 v[196:199], v159
	ds_read_b128 v[206:209], v159 offset:1024
	ds_read_b128 v[210:213], v159 offset:2048
	ds_read_b128 v[214:217], v159 offset:3072
	ds_read_b128 v[218:221], v159 offset:4096
	ds_read_b128 v[222:225], v159 offset:5120
	ds_read_b128 v[226:229], v159 offset:6144
	ds_read_b128 v[230:233], v159 offset:7168
	s_add_u32 s4, s4, 0x80080
	s_addc_u32 s5, s5, 0
	s_mov_b32 m0, s75
	s_nop 0
	global_load_lds_dwordx4 v151, s[4:5]
	s_nop 0
	s_mov_b32 m0, s77
	s_nop 0
	global_load_lds_dwordx4 v153, s[4:5]
	s_waitcnt vmcnt(8)
	s_waitcnt lgkmcnt(0)
	s_barrier
	s_setprio 1
	v_mfma_f32_16x16x32_bf16 v[126:129], v[136:139], v[196:199], v[126:129]
	v_mfma_f32_16x16x32_bf16 v[122:125], v[144:147], v[196:199], v[122:125]
	v_mfma_f32_16x16x32_bf16 v[110:113], v[136:139], v[210:213], v[110:113]
	v_mfma_f32_16x16x32_bf16 v[106:109], v[144:147], v[210:213], v[106:109]
	v_mfma_f32_16x16x32_bf16 v[94:97], v[136:139], v[218:221], v[94:97]
	v_mfma_f32_16x16x32_bf16 v[90:93], v[144:147], v[218:221], v[90:93]
	v_mfma_f32_16x16x32_bf16 v[78:81], v[136:139], v[226:229], v[78:81]
	v_mfma_f32_16x16x32_bf16 v[74:77], v[144:147], v[226:229], v[74:77]
	v_mfma_f32_16x16x32_bf16 v[126:129], v[140:143], v[206:209], v[126:129]
	v_mfma_f32_16x16x32_bf16 v[122:125], v[172:175], v[206:209], v[122:125]
	v_mfma_f32_16x16x32_bf16 v[110:113], v[140:143], v[214:217], v[110:113]
	v_mfma_f32_16x16x32_bf16 v[106:109], v[172:175], v[214:217], v[106:109]
	v_mfma_f32_16x16x32_bf16 v[94:97], v[140:143], v[222:225], v[94:97]
	v_mfma_f32_16x16x32_bf16 v[90:93], v[172:175], v[222:225], v[90:93]
	v_mfma_f32_16x16x32_bf16 v[78:81], v[140:143], v[230:233], v[78:81]
	v_mfma_f32_16x16x32_bf16 v[74:77], v[172:175], v[230:233], v[74:77]
	v_mfma_f32_16x16x32_bf16 v[118:121], v[180:183], v[196:199], v[118:121]
	v_mfma_f32_16x16x32_bf16 v[114:117], v[188:191], v[196:199], v[114:117]
	v_mfma_f32_16x16x32_bf16 v[102:105], v[180:183], v[210:213], v[102:105]
	v_mfma_f32_16x16x32_bf16 v[98:101], v[188:191], v[210:213], v[98:101]
	v_mfma_f32_16x16x32_bf16 v[86:89], v[180:183], v[218:221], v[86:89]
	v_mfma_f32_16x16x32_bf16 v[82:85], v[188:191], v[218:221], v[82:85]
	v_mfma_f32_16x16x32_bf16 v[70:73], v[180:183], v[226:229], v[70:73]
	v_mfma_f32_16x16x32_bf16 v[66:69], v[188:191], v[226:229], v[66:69]
	v_mfma_f32_16x16x32_bf16 v[118:121], v[184:187], v[206:209], v[118:121]
	v_mfma_f32_16x16x32_bf16 v[114:117], v[192:195], v[206:209], v[114:117]
	v_mfma_f32_16x16x32_bf16 v[102:105], v[184:187], v[214:217], v[102:105]
	v_mfma_f32_16x16x32_bf16 v[98:101], v[192:195], v[214:217], v[98:101]
	v_mfma_f32_16x16x32_bf16 v[86:89], v[184:187], v[222:225], v[86:89]
	v_mfma_f32_16x16x32_bf16 v[82:85], v[192:195], v[222:225], v[82:85]
	v_mfma_f32_16x16x32_bf16 v[70:73], v[184:187], v[230:233], v[70:73]
	v_mfma_f32_16x16x32_bf16 v[66:69], v[192:195], v[230:233], v[66:69]
	s_setprio 0
	s_barrier
	ds_read_b128 v[196:199], v159 offset:16384
	ds_read_b128 v[206:209], v159 offset:17408
	ds_read_b128 v[210:213], v159 offset:18432
	ds_read_b128 v[214:217], v159 offset:19456
	ds_read_b128 v[218:221], v159 offset:20480
	ds_read_b128 v[222:225], v159 offset:21504
	ds_read_b128 v[226:229], v159 offset:22528
	ds_read_b128 v[230:233], v159 offset:23552
	s_mov_b32 m0, s23
	s_nop 0
	global_load_lds_dwordx4 v152, s[48:49]
	s_nop 0
	s_mov_b32 m0, s62
	s_nop 0
	global_load_lds_dwordx4 v154, s[48:49]
	s_add_u32 s4, s48, 0x80000
	s_addc_u32 s5, s49, 0
	s_mov_b32 m0, s63
	s_nop 0
	global_load_lds_dwordx4 v152, s[4:5]
	s_nop 0
	s_mov_b32 m0, s64
	s_nop 0
	global_load_lds_dwordx4 v154, s[4:5]
	s_mov_b32 m0, s61
	s_nop 0
	global_load_lds_dwordx4 v151, s[50:51]
	s_nop 0
	s_mov_b32 m0, s65
	s_nop 0
	global_load_lds_dwordx4 v153, s[50:51]
	s_waitcnt vmcnt(8)
	s_waitcnt lgkmcnt(0)
	s_barrier
	s_setprio 1
	v_mfma_f32_16x16x32_bf16 v[62:65], v[136:139], v[196:199], v[62:65]
	v_mfma_f32_16x16x32_bf16 v[58:61], v[144:147], v[196:199], v[58:61]
	v_mfma_f32_16x16x32_bf16 v[46:49], v[136:139], v[210:213], v[46:49]
	v_mfma_f32_16x16x32_bf16 v[42:45], v[144:147], v[210:213], v[42:45]
	v_mfma_f32_16x16x32_bf16 v[30:33], v[136:139], v[218:221], v[30:33]
	v_mfma_f32_16x16x32_bf16 v[26:29], v[144:147], v[218:221], v[26:29]
	v_mfma_f32_16x16x32_bf16 v[14:17], v[136:139], v[226:229], v[14:17]
	v_mfma_f32_16x16x32_bf16 v[10:13], v[144:147], v[226:229], v[10:13]
	v_mfma_f32_16x16x32_bf16 v[62:65], v[140:143], v[206:209], v[62:65]
	v_mfma_f32_16x16x32_bf16 v[58:61], v[172:175], v[206:209], v[58:61]
	v_mfma_f32_16x16x32_bf16 v[46:49], v[140:143], v[214:217], v[46:49]
	v_mfma_f32_16x16x32_bf16 v[42:45], v[172:175], v[214:217], v[42:45]
	v_mfma_f32_16x16x32_bf16 v[30:33], v[140:143], v[222:225], v[30:33]
	v_mfma_f32_16x16x32_bf16 v[26:29], v[172:175], v[222:225], v[26:29]
	v_mfma_f32_16x16x32_bf16 v[14:17], v[140:143], v[230:233], v[14:17]
	v_mfma_f32_16x16x32_bf16 v[10:13], v[172:175], v[230:233], v[10:13]
	v_mfma_f32_16x16x32_bf16 v[54:57], v[180:183], v[196:199], v[54:57]
	v_mfma_f32_16x16x32_bf16 v[50:53], v[188:191], v[196:199], v[50:53]
	v_mfma_f32_16x16x32_bf16 v[38:41], v[180:183], v[210:213], v[38:41]
	v_mfma_f32_16x16x32_bf16 v[34:37], v[188:191], v[210:213], v[34:37]
	v_mfma_f32_16x16x32_bf16 v[22:25], v[180:183], v[218:221], v[22:25]
	v_mfma_f32_16x16x32_bf16 v[18:21], v[188:191], v[218:221], v[18:21]
	v_mfma_f32_16x16x32_bf16 v[6:9], v[180:183], v[226:229], v[6:9]
	v_mfma_f32_16x16x32_bf16 v[2:5], v[188:191], v[226:229], v[2:5]
	v_mfma_f32_16x16x32_bf16 v[54:57], v[184:187], v[206:209], v[54:57]
	v_mfma_f32_16x16x32_bf16 v[50:53], v[192:195], v[206:209], v[50:53]
	v_mfma_f32_16x16x32_bf16 v[38:41], v[184:187], v[214:217], v[38:41]
	v_mfma_f32_16x16x32_bf16 v[34:37], v[192:195], v[214:217], v[34:37]
	v_mfma_f32_16x16x32_bf16 v[22:25], v[184:187], v[222:225], v[22:25]
	v_mfma_f32_16x16x32_bf16 v[18:21], v[192:195], v[222:225], v[18:21]
	v_mfma_f32_16x16x32_bf16 v[6:9], v[184:187], v[230:233], v[6:9]
	v_mfma_f32_16x16x32_bf16 v[2:5], v[192:195], v[230:233], v[2:5]
	s_setprio 0
	s_barrier
; #define PG8_STAGE(bufoff, gbase, voff) do { _Pragma("unroll") for (int _i = 0; _i < 2; ++_i) { unsigned keep_; \
;         asm volatile("s_mov_b32 %0, m0\n\ts_mov_b32 m0, %3\n\ts_nop 0\n\tglobal_load_lds_dwordx4 %1, %2\n\ts_mov_b32 m0, %0" \
;             : "=&s"(keep_) : "v"((voff)[_i]), "s"((const void*)(gbase)), "s"(ldsb0 + (unsigned)(bufoff) + (unsigned)(_i * 8192)) : "memory"); } } while (0)
; #define PG8_LDA(dst, b, h) do { _Pragma("unroll") for (int m = 0; m < 4; ++m) _Pragma("unroll") for (int k = 0; k < 2; ++k) dst[m][k] = *(const LAS bf16x8*)(lds + PG8_SA(b, h) + aoff + m * 2048 + k * 1024); } while (0)
; #define PG8_LDB(dst, b, h) do { _Pragma("unroll") for (int n = 0; n < 2; ++n) _Pragma("unroll") for (int k = 0; k < 2; ++k) dst[n][k] = *(const LAS bf16x8*)(lds + PG8_SB(b, h) + boff + n * 2048 + k * 1024); } while (0)
; template <class Epi, class Sched, bool ALIGN_EPI>
; __device__ __forceinline__ void gemm_phase(LAS unsigned char* lds, const Gemm g, const Sched& S, const Epi& E) {
;     ...
;         for (int t = 0; t < nt; t += 2) {
;             const bool last = (t == nt - 2);
;             const char* a1 = cA + (size_t)(t + 1) * kstep;
;             const char* a2 = last ? nA : cA + (size_t)(t + 2) * kstep; const char* b2 = last ? nB : cB + (size_t)(t + 2) * kstep;
;             const char* a3 = a2 + kstep; const char* b3 = b2 + kstep;
;             PG8_LDB(B0, 0, 0); PG8_LDB(B1, 0, 1); PG8_SCHED; PG8_LDA(At, 0, 0); PG8_STAGE(PG8_SA(1, 1), a1 + hstepA, voffA);
;             PG8_WAIT_V(8); PG8_WAIT_L(0); PG8_BAR; PG8_MMA(0, 0, At, B0); PG8_MMA(0, 1, At, B1); PG8_BAR; PG8_SCHED;
;             PG8_LDA(At, 0, 1); PG8_STAGE(PG8_SB(0, 0), b2, voffB); PG8_STAGE(PG8_SB(0, 1), b2 + hstepB, voffB); PG8_STAGE(PG8_SA(0, 0), a2, voffA);
;             PG8_WAIT_V(8); PG8_WAIT_L(0); PG8_BAR; PG8_MMA(1, 0, At, B0); PG8_MMA(1, 1, At, B1); PG8_BAR; PG8_SCHED;
;             PG8_LDB(B0, 1, 0); PG8_LDB(B1, 1, 1); PG8_SCHED; PG8_LDA(At, 1, 0); PG8_STAGE(PG8_SA(0, 1), a2 + hstepA, voffA);
;             PG8_WAIT_V(8); PG8_WAIT_L(0); PG8_BAR; PG8_MMA(0, 0, At, B0); PG8_MMA(0, 1, At, B1); PG8_BAR; PG8_SCHED;
;             PG8_LDA(At, 1, 1); PG8_STAGE(PG8_SB(1, 0), b3, voffB); PG8_STAGE(PG8_SB(1, 1), b3 + hstepB, voffB); PG8_STAGE(PG8_SA(1, 0), a3, voffA);
;             PG8_WAIT_V(8); PG8_WAIT_L(0); PG8_BAR; PG8_MMA(1, 0, At, B0); PG8_MMA(1, 1, At, B1); PG8_BAR; PG8_SCHED;
	ds_read_b128 v[136:139], v160
	ds_read_b128 v[140:143], v160 offset:1024
	ds_read_b128 v[144:147], v160 offset:2048
	ds_read_b128 v[172:175], v160 offset:3072
	ds_read_b128 v[180:183], v161
	ds_read_b128 v[184:187], v161 offset:1024
	ds_read_b128 v[188:191], v161 offset:2048
	ds_read_b128 v[192:195], v161 offset:3072
	ds_read_b128 v[196:199], v159 offset:32768
	ds_read_b128 v[206:209], v159 offset:33792
	ds_read_b128 v[210:213], v159 offset:34816
	ds_read_b128 v[214:217], v159 offset:35840
	ds_read_b128 v[218:221], v159 offset:36864
	ds_read_b128 v[222:225], v159 offset:37888
	ds_read_b128 v[226:229], v159 offset:38912
	ds_read_b128 v[230:233], v159 offset:39936
	s_add_u32 s4, s50, 0x80000
	s_addc_u32 s5, s51, 0
	s_mov_b32 m0, s66
	s_nop 0
	global_load_lds_dwordx4 v151, s[4:5]
	s_nop 0
	s_mov_b32 m0, s67
	s_nop 0
	global_load_lds_dwordx4 v153, s[4:5]
	s_waitcnt vmcnt(8)
	s_waitcnt lgkmcnt(0)
	s_barrier
	s_setprio 1
	v_mfma_f32_16x16x32_bf16 v[126:129], v[136:139], v[196:199], v[126:129]
	v_mfma_f32_16x16x32_bf16 v[122:125], v[144:147], v[196:199], v[122:125]
	v_mfma_f32_16x16x32_bf16 v[110:113], v[136:139], v[210:213], v[110:113]
	v_mfma_f32_16x16x32_bf16 v[106:109], v[144:147], v[210:213], v[106:109]
	v_mfma_f32_16x16x32_bf16 v[94:97], v[136:139], v[218:221], v[94:97]
	v_mfma_f32_16x16x32_bf16 v[90:93], v[144:147], v[218:221], v[90:93]
	v_mfma_f32_16x16x32_bf16 v[78:81], v[136:139], v[226:229], v[78:81]
	v_mfma_f32_16x16x32_bf16 v[74:77], v[144:147], v[226:229], v[74:77]
	v_mfma_f32_16x16x32_bf16 v[126:129], v[140:143], v[206:209], v[126:129]
	v_mfma_f32_16x16x32_bf16 v[122:125], v[172:175], v[206:209], v[122:125]
	v_mfma_f32_16x16x32_bf16 v[110:113], v[140:143], v[214:217], v[110:113]
	v_mfma_f32_16x16x32_bf16 v[106:109], v[172:175], v[214:217], v[106:109]
	v_mfma_f32_16x16x32_bf16 v[94:97], v[140:143], v[222:225], v[94:97]
	v_mfma_f32_16x16x32_bf16 v[90:93], v[172:175], v[222:225], v[90:93]
	v_mfma_f32_16x16x32_bf16 v[78:81], v[140:143], v[230:233], v[78:81]
	v_mfma_f32_16x16x32_bf16 v[74:77], v[172:175], v[230:233], v[74:77]
	v_mfma_f32_16x16x32_bf16 v[118:121], v[180:183], v[196:199], v[118:121]
	v_mfma_f32_16x16x32_bf16 v[114:117], v[188:191], v[196:199], v[114:117]
	v_mfma_f32_16x16x32_bf16 v[102:105], v[180:183], v[210:213], v[102:105]
	v_mfma_f32_16x16x32_bf16 v[98:101], v[188:191], v[210:213], v[98:101]
	v_mfma_f32_16x16x32_bf16 v[86:89], v[180:183], v[218:221], v[86:89]
	v_mfma_f32_16x16x32_bf16 v[82:85], v[188:191], v[218:221], v[82:85]
	v_mfma_f32_16x16x32_bf16 v[70:73], v[180:183], v[226:229], v[70:73]
	v_mfma_f32_16x16x32_bf16 v[66:69], v[188:191], v[226:229], v[66:69]
	v_mfma_f32_16x16x32_bf16 v[118:121], v[184:187], v[206:209], v[118:121]
	v_mfma_f32_16x16x32_bf16 v[114:117], v[192:195], v[206:209], v[114:117]
	v_mfma_f32_16x16x32_bf16 v[102:105], v[184:187], v[214:217], v[102:105]
	v_mfma_f32_16x16x32_bf16 v[98:101], v[192:195], v[214:217], v[98:101]
	v_mfma_f32_16x16x32_bf16 v[86:89], v[184:187], v[222:225], v[86:89]
	v_mfma_f32_16x16x32_bf16 v[82:85], v[192:195], v[222:225], v[82:85]
	v_mfma_f32_16x16x32_bf16 v[70:73], v[184:187], v[230:233], v[70:73]
	v_mfma_f32_16x16x32_bf16 v[66:69], v[192:195], v[230:233], v[66:69]
	s_setprio 0
	s_barrier
	ds_read_b128 v[196:199], v159 offset:49152
	ds_read_b128 v[206:209], v159 offset:50176
	ds_read_b128 v[210:213], v159 offset:51200
	ds_read_b128 v[214:217], v159 offset:52224
	ds_read_b128 v[218:221], v159 offset:53248
	ds_read_b128 v[222:225], v159 offset:54272
	ds_read_b128 v[226:229], v159 offset:55296
	ds_read_b128 v[230:233], v159 offset:56320
	s_add_u32 s4, s48, 0x80
	s_addc_u32 s5, s49, 0
	s_mov_b32 m0, s69
	s_nop 0
	global_load_lds_dwordx4 v152, s[4:5]
	s_nop 0
	s_mov_b32 m0, s70
	s_nop 0
	global_load_lds_dwordx4 v154, s[4:5]
	s_add_u32 s4, s48, 0x80080
	s_addc_u32 s5, s49, 0
	s_mov_b32 m0, s73
	s_nop 0
	global_load_lds_dwordx4 v152, s[4:5]
	s_nop 0
	s_mov_b32 m0, s74
	s_nop 0
	global_load_lds_dwordx4 v154, s[4:5]
	s_mov_b32 m0, s71
	s_nop 0
	global_load_lds_dwordx4 v151, s[8:9]
	s_nop 0
	s_mov_b32 m0, s72
	s_nop 0
	global_load_lds_dwordx4 v153, s[8:9]
	s_waitcnt vmcnt(8)
	s_waitcnt lgkmcnt(0)
	s_barrier
	s_setprio 1
	v_mfma_f32_16x16x32_bf16 v[62:65], v[136:139], v[196:199], v[62:65]
	v_mfma_f32_16x16x32_bf16 v[58:61], v[144:147], v[196:199], v[58:61]
	v_mfma_f32_16x16x32_bf16 v[46:49], v[136:139], v[210:213], v[46:49]
	v_mfma_f32_16x16x32_bf16 v[42:45], v[144:147], v[210:213], v[42:45]
	s_add_i32 s81, s81, 2
	s_add_u32 s59, s59, 0x100
	s_addc_u32 s80, s80, 0
	s_cmp_gt_u32 s81, 29
	s_mov_b64 s[4:5], s[6:7]
	v_mfma_f32_16x16x32_bf16 v[30:33], v[136:139], v[218:221], v[30:33]
	v_mfma_f32_16x16x32_bf16 v[26:29], v[144:147], v[218:221], v[26:29]
	v_mfma_f32_16x16x32_bf16 v[14:17], v[136:139], v[226:229], v[14:17]
	v_mfma_f32_16x16x32_bf16 v[10:13], v[144:147], v[226:229], v[10:13]
	v_mfma_f32_16x16x32_bf16 v[62:65], v[140:143], v[206:209], v[62:65]
	v_mfma_f32_16x16x32_bf16 v[58:61], v[172:175], v[206:209], v[58:61]
	v_mfma_f32_16x16x32_bf16 v[46:49], v[140:143], v[214:217], v[46:49]
	v_mfma_f32_16x16x32_bf16 v[42:45], v[172:175], v[214:217], v[42:45]
	v_mfma_f32_16x16x32_bf16 v[30:33], v[140:143], v[222:225], v[30:33]
	v_mfma_f32_16x16x32_bf16 v[26:29], v[172:175], v[222:225], v[26:29]
	v_mfma_f32_16x16x32_bf16 v[14:17], v[140:143], v[230:233], v[14:17]
	v_mfma_f32_16x16x32_bf16 v[10:13], v[172:175], v[230:233], v[10:13]
	v_mfma_f32_16x16x32_bf16 v[54:57], v[180:183], v[196:199], v[54:57]
	v_mfma_f32_16x16x32_bf16 v[50:53], v[188:191], v[196:199], v[50:53]
	v_mfma_f32_16x16x32_bf16 v[38:41], v[180:183], v[210:213], v[38:41]
	v_mfma_f32_16x16x32_bf16 v[34:37], v[188:191], v[210:213], v[34:37]
	v_mfma_f32_16x16x32_bf16 v[22:25], v[180:183], v[218:221], v[22:25]
	v_mfma_f32_16x16x32_bf16 v[18:21], v[188:191], v[218:221], v[18:21]
	v_mfma_f32_16x16x32_bf16 v[6:9], v[180:183], v[226:229], v[6:9]
	v_mfma_f32_16x16x32_bf16 v[2:5], v[188:191], v[226:229], v[2:5]
	v_mfma_f32_16x16x32_bf16 v[54:57], v[184:187], v[206:209], v[54:57]
	v_mfma_f32_16x16x32_bf16 v[50:53], v[192:195], v[206:209], v[50:53]
	v_mfma_f32_16x16x32_bf16 v[38:41], v[184:187], v[214:217], v[38:41]
	v_mfma_f32_16x16x32_bf16 v[34:37], v[192:195], v[214:217], v[34:37]
	v_mfma_f32_16x16x32_bf16 v[22:25], v[184:187], v[222:225], v[22:25]
	v_mfma_f32_16x16x32_bf16 v[18:21], v[192:195], v[222:225], v[18:21]
	v_mfma_f32_16x16x32_bf16 v[6:9], v[184:187], v[230:233], v[6:9]
	v_mfma_f32_16x16x32_bf16 v[2:5], v[192:195], v[230:233], v[2:5]
	s_setprio 0
	s_barrier
	s_cbranch_scc0 .LBB0_113
	s_and_b64 vcc, exec, s[36:37]
	s_cbranch_vccz .LBB0_116
	s_barrier

; #define PG8_STAGE(bufoff, gbase, voff) do { _Pragma("unroll") for (int _i = 0; _i < 2; ++_i) { unsigned keep_; \
;         asm volatile("s_mov_b32 %0, m0\n\ts_mov_b32 m0, %3\n\ts_nop 0\n\tglobal_load_lds_dwordx4 %1, %2\n\ts_mov_b32 m0, %0" \
;             : "=&s"(keep_) : "v"((voff)[_i]), "s"((const void*)(gbase)), "s"(ldsb0 + (unsigned)(bufoff) + (unsigned)(_i * 8192)) : "memory"); } } while (0)
; #define PG8_LDA(dst, b, h) do { _Pragma("unroll") for (int m = 0; m < 4; ++m) _Pragma("unroll") for (int k = 0; k < 2; ++k) dst[m][k] = *(const LAS bf16x8*)(lds + PG8_SA(b, h) + aoff + m * 2048 + k * 1024); } while (0)
; #define PG8_LDB(dst, b, h) do { _Pragma("unroll") for (int n = 0; n < 2; ++n) _Pragma("unroll") for (int k = 0; k < 2; ++k) dst[n][k] = *(const LAS bf16x8*)(lds + PG8_SB(b, h) + boff + n * 2048 + k * 1024); } while (0)
; template <class Epi, class Sched, bool ALIGN_EPI>
; __device__ __forceinline__ void gemm_phase(LAS unsigned char* lds, const Gemm g, const Sched& S, const Epi& E) {
;     ...
;         for (int t = 0; t < nt; t += 2) {
;             const bool last = (t == nt - 2);
;             const char* a1 = cA + (size_t)(t + 1) * kstep;
;             const char* a2 = last ? nA : cA + (size_t)(t + 2) * kstep; const char* b2 = last ? nB : cB + (size_t)(t + 2) * kstep;
;             const char* a3 = a2 + kstep; const char* b3 = b2 + kstep;
;             PG8_LDB(B0, 0, 0); PG8_LDB(B1, 0, 1); PG8_SCHED; PG8_LDA(At, 0, 0); PG8_STAGE(PG8_SA(1, 1), a1 + hstepA, voffA);
;             PG8_WAIT_V(8); PG8_WAIT_L(0); PG8_BAR; PG8_MMA(0, 0, At, B0); PG8_MMA(0, 1, At, B1); PG8_BAR; PG8_SCHED;
;             PG8_LDA(At, 0, 1); PG8_STAGE(PG8_SB(0, 0), b2, voffB); PG8_STAGE(PG8_SB(0, 1), b2 + hstepB, voffB); PG8_STAGE(PG8_SA(0, 0), a2, voffA);
;             PG8_WAIT_V(8); PG8_WAIT_L(0); PG8_BAR; PG8_MMA(1, 0, At, B0); PG8_MMA(1, 1, At, B1); PG8_BAR; PG8_SCHED;
;             PG8_LDB(B0, 1, 0); PG8_LDB(B1, 1, 1); PG8_SCHED; PG8_LDA(At, 1, 0); PG8_STAGE(PG8_SA(0, 1), a2 + hstepA, voffA);
;             PG8_WAIT_V(8); PG8_WAIT_L(0); PG8_BAR; PG8_MMA(0, 0, At, B0); PG8_MMA(0, 1, At, B1); PG8_BAR; PG8_SCHED;
;             PG8_LDA(At, 1, 1); PG8_STAGE(PG8_SB(1, 0), b3, voffB); PG8_STAGE(PG8_SB(1, 1), b3 + hstepB, voffB); PG8_STAGE(PG8_SA(1, 0), a3, voffA);
;             PG8_WAIT_V(8); PG8_WAIT_L(0); PG8_BAR; PG8_MMA(1, 0, At, B0); PG8_MMA(1, 1, At, B1); PG8_BAR; PG8_SCHED;
.LBB0_1137:
	ds_read_b128 v[110:113], v206
	ds_read_b128 v[126:129], v206 offset:1024
	ds_read_b128 v[130:133], v206 offset:2048
	ds_read_b128 v[142:145], v206 offset:3072
	ds_read_b128 v[146:149], v207
	ds_read_b128 v[150:153], v207 offset:1024
	ds_read_b128 v[154:157], v207 offset:2048
	ds_read_b128 v[158:161], v207 offset:3072
	s_cmp_eq_u32 s63, 28
	s_cselect_b32 s40, s5, s19
	s_cselect_b32 s41, s3, s27
	s_cselect_b32 s38, s7, s61
	s_cselect_b32 s39, s6, s62
	s_add_u32 s36, s40, 0x80
	s_addc_u32 s37, s41, 0
	ds_read_b128 v[162:165], v208
	ds_read_b128 v[166:169], v208 offset:1024
	ds_read_b128 v[170:173], v208 offset:2048
	ds_read_b128 v[174:177], v208 offset:3072
	ds_read_b128 v[188:191], v208 offset:4096
	ds_read_b128 v[192:195], v208 offset:5120
	ds_read_b128 v[196:199], v208 offset:6144
	ds_read_b128 v[212:215], v208 offset:7168
	s_mov_b32 m0, s58
	s_nop 0
	global_load_lds_dwordx4 v179, s[34:35]
	s_nop 0
	s_mov_b32 m0, s59
	s_nop 0
	global_load_lds_dwordx4 v201, s[34:35]
	s_waitcnt vmcnt(8)
	s_waitcnt lgkmcnt(0)
	s_barrier
	s_setprio 1
	v_mfma_f32_16x16x32_bf16 v[138:141], v[110:113], v[162:165], v[138:141]
	v_mfma_f32_16x16x32_bf16 v[134:137], v[130:133], v[162:165], v[134:137]
	v_mfma_f32_16x16x32_bf16 v[114:117], v[110:113], v[170:173], v[114:117]
	v_mfma_f32_16x16x32_bf16 v[106:109], v[130:133], v[170:173], v[106:109]
	v_mfma_f32_16x16x32_bf16 v[94:97], v[110:113], v[188:191], v[94:97]
	v_mfma_f32_16x16x32_bf16 v[90:93], v[130:133], v[188:191], v[90:93]
	v_mfma_f32_16x16x32_bf16 v[78:81], v[110:113], v[196:199], v[78:81]
	v_mfma_f32_16x16x32_bf16 v[74:77], v[130:133], v[196:199], v[74:77]
	v_mfma_f32_16x16x32_bf16 v[138:141], v[126:129], v[166:169], v[138:141]
	v_mfma_f32_16x16x32_bf16 v[134:137], v[142:145], v[166:169], v[134:137]
	v_mfma_f32_16x16x32_bf16 v[114:117], v[126:129], v[174:177], v[114:117]
	v_mfma_f32_16x16x32_bf16 v[106:109], v[142:145], v[174:177], v[106:109]
	v_mfma_f32_16x16x32_bf16 v[94:97], v[126:129], v[192:195], v[94:97]
	v_mfma_f32_16x16x32_bf16 v[90:93], v[142:145], v[192:195], v[90:93]
	v_mfma_f32_16x16x32_bf16 v[78:81], v[126:129], v[212:215], v[78:81]
	v_mfma_f32_16x16x32_bf16 v[74:77], v[142:145], v[212:215], v[74:77]
	v_mfma_f32_16x16x32_bf16 v[122:125], v[146:149], v[162:165], v[122:125]
	v_mfma_f32_16x16x32_bf16 v[118:121], v[154:157], v[162:165], v[118:121]
	v_mfma_f32_16x16x32_bf16 v[102:105], v[146:149], v[170:173], v[102:105]
	v_mfma_f32_16x16x32_bf16 v[98:101], v[154:157], v[170:173], v[98:101]
	v_mfma_f32_16x16x32_bf16 v[86:89], v[146:149], v[188:191], v[86:89]
	v_mfma_f32_16x16x32_bf16 v[82:85], v[154:157], v[188:191], v[82:85]
	v_mfma_f32_16x16x32_bf16 v[70:73], v[146:149], v[196:199], v[70:73]
	v_mfma_f32_16x16x32_bf16 v[66:69], v[154:157], v[196:199], v[66:69]
	v_mfma_f32_16x16x32_bf16 v[122:125], v[150:153], v[166:169], v[122:125]
	v_mfma_f32_16x16x32_bf16 v[118:121], v[158:161], v[166:169], v[118:121]
	v_mfma_f32_16x16x32_bf16 v[102:105], v[150:153], v[174:177], v[102:105]
	v_mfma_f32_16x16x32_bf16 v[98:101], v[158:161], v[174:177], v[98:101]
	v_mfma_f32_16x16x32_bf16 v[86:89], v[150:153], v[192:195], v[86:89]
	v_mfma_f32_16x16x32_bf16 v[82:85], v[158:161], v[192:195], v[82:85]
	v_mfma_f32_16x16x32_bf16 v[70:73], v[150:153], v[212:215], v[70:73]
	v_mfma_f32_16x16x32_bf16 v[66:69], v[158:161], v[212:215], v[66:69]
	s_setprio 0
	s_barrier
	ds_read_b128 v[162:165], v208 offset:16384
	ds_read_b128 v[166:169], v208 offset:17408
	ds_read_b128 v[170:173], v208 offset:18432
	ds_read_b128 v[174:177], v208 offset:19456
	ds_read_b128 v[188:191], v208 offset:20480
	ds_read_b128 v[192:195], v208 offset:21504
	ds_read_b128 v[196:199], v208 offset:22528
	ds_read_b128 v[212:215], v208 offset:23552
	s_mov_b32 m0, s45
	s_nop 0
	global_load_lds_dwordx4 v200, s[38:39]
	s_nop 0
	s_mov_b32 m0, s46
	s_nop 0
	global_load_lds_dwordx4 v203, s[38:39]
	s_add_u32 s64, s38, 0x80000
	s_addc_u32 s65, s39, 0
	s_mov_b32 m0, s47
	s_nop 0
	global_load_lds_dwordx4 v200, s[64:65]
	s_nop 0
	s_mov_b32 m0, s48
	s_nop 0
	global_load_lds_dwordx4 v203, s[64:65]
	s_mov_b32 m0, s44
	s_nop 0
	global_load_lds_dwordx4 v179, s[40:41]
	s_nop 0
	s_mov_b32 m0, s49
	s_nop 0
	global_load_lds_dwordx4 v201, s[40:41]
	s_waitcnt vmcnt(8)
	s_waitcnt lgkmcnt(0)
	s_barrier
	s_setprio 1
	v_mfma_f32_16x16x32_bf16 v[62:65], v[110:113], v[162:165], v[62:65]
	v_mfma_f32_16x16x32_bf16 v[58:61], v[130:133], v[162:165], v[58:61]
	v_mfma_f32_16x16x32_bf16 v[46:49], v[110:113], v[170:173], v[46:49]
	v_mfma_f32_16x16x32_bf16 v[42:45], v[130:133], v[170:173], v[42:45]
	v_mfma_f32_16x16x32_bf16 v[30:33], v[110:113], v[188:191], v[30:33]
	v_mfma_f32_16x16x32_bf16 v[26:29], v[130:133], v[188:191], v[26:29]
	v_mfma_f32_16x16x32_bf16 v[14:17], v[110:113], v[196:199], v[14:17]
	v_mfma_f32_16x16x32_bf16 v[10:13], v[130:133], v[196:199], v[10:13]
	v_mfma_f32_16x16x32_bf16 v[62:65], v[126:129], v[166:169], v[62:65]
	v_mfma_f32_16x16x32_bf16 v[58:61], v[142:145], v[166:169], v[58:61]
	v_mfma_f32_16x16x32_bf16 v[46:49], v[126:129], v[174:177], v[46:49]
	v_mfma_f32_16x16x32_bf16 v[42:45], v[142:145], v[174:177], v[42:45]
	v_mfma_f32_16x16x32_bf16 v[30:33], v[126:129], v[192:195], v[30:33]
	v_mfma_f32_16x16x32_bf16 v[26:29], v[142:145], v[192:195], v[26:29]
	v_mfma_f32_16x16x32_bf16 v[14:17], v[126:129], v[212:215], v[14:17]
	v_mfma_f32_16x16x32_bf16 v[10:13], v[142:145], v[212:215], v[10:13]
	v_mfma_f32_16x16x32_bf16 v[54:57], v[146:149], v[162:165], v[54:57]
	v_mfma_f32_16x16x32_bf16 v[50:53], v[154:157], v[162:165], v[50:53]
	v_mfma_f32_16x16x32_bf16 v[38:41], v[146:149], v[170:173], v[38:41]
	v_mfma_f32_16x16x32_bf16 v[34:37], v[154:157], v[170:173], v[34:37]
	v_mfma_f32_16x16x32_bf16 v[22:25], v[146:149], v[188:191], v[22:25]
	v_mfma_f32_16x16x32_bf16 v[18:21], v[154:157], v[188:191], v[18:21]
	v_mfma_f32_16x16x32_bf16 v[6:9], v[146:149], v[196:199], v[6:9]
	v_mfma_f32_16x16x32_bf16 v[2:5], v[154:157], v[196:199], v[2:5]
	v_mfma_f32_16x16x32_bf16 v[54:57], v[150:153], v[166:169], v[54:57]
	v_mfma_f32_16x16x32_bf16 v[50:53], v[158:161], v[166:169], v[50:53]
	v_mfma_f32_16x16x32_bf16 v[38:41], v[150:153], v[174:177], v[38:41]
	v_mfma_f32_16x16x32_bf16 v[34:37], v[158:161], v[174:177], v[34:37]
	v_mfma_f32_16x16x32_bf16 v[22:25], v[150:153], v[192:195], v[22:25]
	v_mfma_f32_16x16x32_bf16 v[18:21], v[158:161], v[192:195], v[18:21]
	v_mfma_f32_16x16x32_bf16 v[6:9], v[150:153], v[212:215], v[6:9]
	v_mfma_f32_16x16x32_bf16 v[2:5], v[158:161], v[212:215], v[2:5]
	s_setprio 0
	s_barrier
; #define PG8_STAGE(bufoff, gbase, voff) do { _Pragma("unroll") for (int _i = 0; _i < 2; ++_i) { unsigned keep_; \
;         asm volatile("s_mov_b32 %0, m0\n\ts_mov_b32 m0, %3\n\ts_nop 0\n\tglobal_load_lds_dwordx4 %1, %2\n\ts_mov_b32 m0, %0" \
;             : "=&s"(keep_) : "v"((voff)[_i]), "s"((const void*)(gbase)), "s"(ldsb0 + (unsigned)(bufoff) + (unsigned)(_i * 8192)) : "memory"); } } while (0)
; #define PG8_LDA(dst, b, h) do { _Pragma("unroll") for (int m = 0; m < 4; ++m) _Pragma("unroll") for (int k = 0; k < 2; ++k) dst[m][k] = *(const LAS bf16x8*)(lds + PG8_SA(b, h) + aoff + m * 2048 + k * 1024); } while (0)
; #define PG8_LDB(dst, b, h) do { _Pragma("unroll") for (int n = 0; n < 2; ++n) _Pragma("unroll") for (int k = 0; k < 2; ++k) dst[n][k] = *(const LAS bf16x8*)(lds + PG8_SB(b, h) + boff + n * 2048 + k * 1024); } while (0)
; template <class Epi, class Sched, bool ALIGN_EPI>
; __device__ __forceinline__ void gemm_phase(LAS unsigned char* lds, const Gemm g, const Sched& S, const Epi& E) {
;     ...
;         for (int t = 0; t < nt; t += 2) {
;             const bool last = (t == nt - 2);
;             const char* a1 = cA + (size_t)(t + 1) * kstep;
;             const char* a2 = last ? nA : cA + (size_t)(t + 2) * kstep; const char* b2 = last ? nB : cB + (size_t)(t + 2) * kstep;
;             const char* a3 = a2 + kstep; const char* b3 = b2 + kstep;
;             PG8_LDB(B0, 0, 0); PG8_LDB(B1, 0, 1); PG8_SCHED; PG8_LDA(At, 0, 0); PG8_STAGE(PG8_SA(1, 1), a1 + hstepA, voffA);
;             PG8_WAIT_V(8); PG8_WAIT_L(0); PG8_BAR; PG8_MMA(0, 0, At, B0); PG8_MMA(0, 1, At, B1); PG8_BAR; PG8_SCHED;
;             PG8_LDA(At, 0, 1); PG8_STAGE(PG8_SB(0, 0), b2, voffB); PG8_STAGE(PG8_SB(0, 1), b2 + hstepB, voffB); PG8_STAGE(PG8_SA(0, 0), a2, voffA);
;             PG8_WAIT_V(8); PG8_WAIT_L(0); PG8_BAR; PG8_MMA(1, 0, At, B0); PG8_MMA(1, 1, At, B1); PG8_BAR; PG8_SCHED;
;             PG8_LDB(B0, 1, 0); PG8_LDB(B1, 1, 1); PG8_SCHED; PG8_LDA(At, 1, 0); PG8_STAGE(PG8_SA(0, 1), a2 + hstepA, voffA);
;             PG8_WAIT_V(8); PG8_WAIT_L(0); PG8_BAR; PG8_MMA(0, 0, At, B0); PG8_MMA(0, 1, At, B1); PG8_BAR; PG8_SCHED;
;             PG8_LDA(At, 1, 1); PG8_STAGE(PG8_SB(1, 0), b3, voffB); PG8_STAGE(PG8_SB(1, 1), b3 + hstepB, voffB); PG8_STAGE(PG8_SA(1, 0), a3, voffA);
;             PG8_WAIT_V(8); PG8_WAIT_L(0); PG8_BAR; PG8_MMA(1, 0, At, B0); PG8_MMA(1, 1, At, B1); PG8_BAR; PG8_SCHED;
	ds_read_b128 v[110:113], v209
	ds_read_b128 v[126:129], v209 offset:1024
	ds_read_b128 v[130:133], v209 offset:2048
	ds_read_b128 v[142:145], v209 offset:3072
	ds_read_b128 v[146:149], v210
	ds_read_b128 v[150:153], v210 offset:1024
	ds_read_b128 v[154:157], v210 offset:2048
	ds_read_b128 v[158:161], v210 offset:3072
	ds_read_b128 v[162:165], v208 offset:32768
	ds_read_b128 v[166:169], v208 offset:33792
	ds_read_b128 v[170:173], v208 offset:34816
	ds_read_b128 v[174:177], v208 offset:35840
	ds_read_b128 v[188:191], v208 offset:36864
	ds_read_b128 v[192:195], v208 offset:37888
	ds_read_b128 v[196:199], v208 offset:38912
	ds_read_b128 v[212:215], v208 offset:39936
	s_add_u32 s40, s40, 0x80000
	s_addc_u32 s41, s41, 0
	s_mov_b32 m0, s50
	s_nop 0
	global_load_lds_dwordx4 v179, s[40:41]
	s_nop 0
	s_mov_b32 m0, s51
	s_nop 0
	global_load_lds_dwordx4 v201, s[40:41]
	s_waitcnt vmcnt(8)
	s_waitcnt lgkmcnt(0)
	s_barrier
	s_setprio 1
	v_mfma_f32_16x16x32_bf16 v[138:141], v[110:113], v[162:165], v[138:141]
	v_mfma_f32_16x16x32_bf16 v[134:137], v[130:133], v[162:165], v[134:137]
	v_mfma_f32_16x16x32_bf16 v[114:117], v[110:113], v[170:173], v[114:117]
	v_mfma_f32_16x16x32_bf16 v[106:109], v[130:133], v[170:173], v[106:109]
	v_mfma_f32_16x16x32_bf16 v[94:97], v[110:113], v[188:191], v[94:97]
	v_mfma_f32_16x16x32_bf16 v[90:93], v[130:133], v[188:191], v[90:93]
	v_mfma_f32_16x16x32_bf16 v[78:81], v[110:113], v[196:199], v[78:81]
	v_mfma_f32_16x16x32_bf16 v[74:77], v[130:133], v[196:199], v[74:77]
	v_mfma_f32_16x16x32_bf16 v[138:141], v[126:129], v[166:169], v[138:141]
	v_mfma_f32_16x16x32_bf16 v[134:137], v[142:145], v[166:169], v[134:137]
	v_mfma_f32_16x16x32_bf16 v[114:117], v[126:129], v[174:177], v[114:117]
	v_mfma_f32_16x16x32_bf16 v[106:109], v[142:145], v[174:177], v[106:109]
	v_mfma_f32_16x16x32_bf16 v[94:97], v[126:129], v[192:195], v[94:97]
	v_mfma_f32_16x16x32_bf16 v[90:93], v[142:145], v[192:195], v[90:93]
	v_mfma_f32_16x16x32_bf16 v[78:81], v[126:129], v[212:215], v[78:81]
	v_mfma_f32_16x16x32_bf16 v[74:77], v[142:145], v[212:215], v[74:77]
	v_mfma_f32_16x16x32_bf16 v[122:125], v[146:149], v[162:165], v[122:125]
	v_mfma_f32_16x16x32_bf16 v[118:121], v[154:157], v[162:165], v[118:121]
	v_mfma_f32_16x16x32_bf16 v[102:105], v[146:149], v[170:173], v[102:105]
	v_mfma_f32_16x16x32_bf16 v[98:101], v[154:157], v[170:173], v[98:101]
	v_mfma_f32_16x16x32_bf16 v[86:89], v[146:149], v[188:191], v[86:89]
	v_mfma_f32_16x16x32_bf16 v[82:85], v[154:157], v[188:191], v[82:85]
	v_mfma_f32_16x16x32_bf16 v[70:73], v[146:149], v[196:199], v[70:73]
	v_mfma_f32_16x16x32_bf16 v[66:69], v[154:157], v[196:199], v[66:69]
	v_mfma_f32_16x16x32_bf16 v[122:125], v[150:153], v[166:169], v[122:125]
	v_mfma_f32_16x16x32_bf16 v[118:121], v[158:161], v[166:169], v[118:121]
	v_mfma_f32_16x16x32_bf16 v[102:105], v[150:153], v[174:177], v[102:105]
	v_mfma_f32_16x16x32_bf16 v[98:101], v[158:161], v[174:177], v[98:101]
	v_mfma_f32_16x16x32_bf16 v[86:89], v[150:153], v[192:195], v[86:89]
	v_mfma_f32_16x16x32_bf16 v[82:85], v[158:161], v[192:195], v[82:85]
	v_mfma_f32_16x16x32_bf16 v[70:73], v[150:153], v[212:215], v[70:73]
	v_mfma_f32_16x16x32_bf16 v[66:69], v[158:161], v[212:215], v[66:69]
	s_setprio 0
	s_barrier
	ds_read_b128 v[162:165], v208 offset:49152
	ds_read_b128 v[166:169], v208 offset:50176
	ds_read_b128 v[170:173], v208 offset:51200
	ds_read_b128 v[174:177], v208 offset:52224
	ds_read_b128 v[188:191], v208 offset:53248
	ds_read_b128 v[192:195], v208 offset:54272
	ds_read_b128 v[196:199], v208 offset:55296
	ds_read_b128 v[212:215], v208 offset:56320
	s_add_u32 s40, s38, 0x80
	s_addc_u32 s41, s39, 0
	s_mov_b32 m0, s52
	s_nop 0
	global_load_lds_dwordx4 v200, s[40:41]
	s_add_u32 s38, s38, 0x80080
	s_mov_b32 m0, s53
	s_nop 0
	global_load_lds_dwordx4 v203, s[40:41]
	s_addc_u32 s39, s39, 0
	s_mov_b32 m0, s56
	s_nop 0
	global_load_lds_dwordx4 v200, s[38:39]
	s_nop 0
	s_mov_b32 m0, s57
	s_nop 0
	global_load_lds_dwordx4 v203, s[38:39]
	s_mov_b32 m0, s54
	s_nop 0
	global_load_lds_dwordx4 v179, s[36:37]
	s_nop 0
	s_mov_b32 m0, s55
	s_nop 0
	global_load_lds_dwordx4 v201, s[36:37]
	s_waitcnt vmcnt(8)
	s_waitcnt lgkmcnt(0)
	s_barrier
	s_setprio 1
	v_mfma_f32_16x16x32_bf16 v[62:65], v[110:113], v[162:165], v[62:65]
	v_mfma_f32_16x16x32_bf16 v[58:61], v[130:133], v[162:165], v[58:61]
	v_mfma_f32_16x16x32_bf16 v[46:49], v[110:113], v[170:173], v[46:49]
	v_mfma_f32_16x16x32_bf16 v[42:45], v[130:133], v[170:173], v[42:45]
	s_add_i32 s63, s63, 2
	s_add_u32 s19, s19, 0x100
	s_addc_u32 s27, s27, 0
	s_add_u32 s61, s61, 0x100
	s_addc_u32 s62, s62, 0
	s_add_u32 s34, s34, 0x100
	s_addc_u32 s35, s35, 0
	s_cmp_gt_u32 s63, 29
	v_mfma_f32_16x16x32_bf16 v[30:33], v[110:113], v[188:191], v[30:33]
	v_mfma_f32_16x16x32_bf16 v[26:29], v[130:133], v[188:191], v[26:29]
	v_mfma_f32_16x16x32_bf16 v[14:17], v[110:113], v[196:199], v[14:17]
	v_mfma_f32_16x16x32_bf16 v[10:13], v[130:133], v[196:199], v[10:13]
	v_mfma_f32_16x16x32_bf16 v[62:65], v[126:129], v[166:169], v[62:65]
	v_mfma_f32_16x16x32_bf16 v[58:61], v[142:145], v[166:169], v[58:61]
	v_mfma_f32_16x16x32_bf16 v[46:49], v[126:129], v[174:177], v[46:49]
	v_mfma_f32_16x16x32_bf16 v[42:45], v[142:145], v[174:177], v[42:45]
	v_mfma_f32_16x16x32_bf16 v[30:33], v[126:129], v[192:195], v[30:33]
	v_mfma_f32_16x16x32_bf16 v[26:29], v[142:145], v[192:195], v[26:29]
	v_mfma_f32_16x16x32_bf16 v[14:17], v[126:129], v[212:215], v[14:17]
	v_mfma_f32_16x16x32_bf16 v[10:13], v[142:145], v[212:215], v[10:13]
	v_mfma_f32_16x16x32_bf16 v[54:57], v[146:149], v[162:165], v[54:57]
	v_mfma_f32_16x16x32_bf16 v[50:53], v[154:157], v[162:165], v[50:53]
	v_mfma_f32_16x16x32_bf16 v[38:41], v[146:149], v[170:173], v[38:41]
	v_mfma_f32_16x16x32_bf16 v[34:37], v[154:157], v[170:173], v[34:37]
	v_mfma_f32_16x16x32_bf16 v[22:25], v[146:149], v[188:191], v[22:25]
	v_mfma_f32_16x16x32_bf16 v[18:21], v[154:157], v[188:191], v[18:21]
	v_mfma_f32_16x16x32_bf16 v[6:9], v[146:149], v[196:199], v[6:9]
	v_mfma_f32_16x16x32_bf16 v[2:5], v[154:157], v[196:199], v[2:5]
	v_mfma_f32_16x16x32_bf16 v[54:57], v[150:153], v[166:169], v[54:57]
	v_mfma_f32_16x16x32_bf16 v[50:53], v[158:161], v[166:169], v[50:53]
	v_mfma_f32_16x16x32_bf16 v[38:41], v[150:153], v[174:177], v[38:41]
	v_mfma_f32_16x16x32_bf16 v[34:37], v[158:161], v[174:177], v[34:37]
	v_mfma_f32_16x16x32_bf16 v[22:25], v[150:153], v[192:195], v[22:25]
	v_mfma_f32_16x16x32_bf16 v[18:21], v[158:161], v[192:195], v[18:21]
	v_mfma_f32_16x16x32_bf16 v[6:9], v[150:153], v[212:215], v[6:9]
	v_mfma_f32_16x16x32_bf16 v[2:5], v[158:161], v[212:215], v[2:5]
	s_setprio 0
	s_barrier
	s_cbranch_scc0 .LBB0_1137
	s_and_b64 vcc, exec, s[16:17]
	s_cbranch_vccz .LBB0_1140
	s_barrier

; #define PG8_STAGE(bufoff, gbase, voff) do { _Pragma("unroll") for (int _i = 0; _i < 2; ++_i) { unsigned keep_; \
;         asm volatile("s_mov_b32 %0, m0\n\ts_mov_b32 m0, %3\n\ts_nop 0\n\tglobal_load_lds_dwordx4 %1, %2\n\ts_mov_b32 m0, %0" \
;             : "=&s"(keep_) : "v"((voff)[_i]), "s"((const void*)(gbase)), "s"(ldsb0 + (unsigned)(bufoff) + (unsigned)(_i * 8192)) : "memory"); } } while (0)
; #define PG8_LDA(dst, b, h) do { _Pragma("unroll") for (int m = 0; m < 4; ++m) _Pragma("unroll") for (int k = 0; k < 2; ++k) dst[m][k] = *(const LAS bf16x8*)(lds + PG8_SA(b, h) + aoff + m * 2048 + k * 1024); } while (0)
; #define PG8_LDB(dst, b, h) do { _Pragma("unroll") for (int n = 0; n < 2; ++n) _Pragma("unroll") for (int k = 0; k < 2; ++k) dst[n][k] = *(const LAS bf16x8*)(lds + PG8_SB(b, h) + boff + n * 2048 + k * 1024); } while (0)
; template <class Epi, class Sched, bool ALIGN_EPI>
; __device__ __forceinline__ void gemm_phase(LAS unsigned char* lds, const Gemm g, const Sched& S, const Epi& E) {
;     ...
;         for (int t = 0; t < nt; t += 2) {
;             const bool last = (t == nt - 2);
;             const char* a1 = cA + (size_t)(t + 1) * kstep;
;             const char* a2 = last ? nA : cA + (size_t)(t + 2) * kstep; const char* b2 = last ? nB : cB + (size_t)(t + 2) * kstep;
;             const char* a3 = a2 + kstep; const char* b3 = b2 + kstep;
;             PG8_LDB(B0, 0, 0); PG8_LDB(B1, 0, 1); PG8_SCHED; PG8_LDA(At, 0, 0); PG8_STAGE(PG8_SA(1, 1), a1 + hstepA, voffA);
;             PG8_WAIT_V(8); PG8_WAIT_L(0); PG8_BAR; PG8_MMA(0, 0, At, B0); PG8_MMA(0, 1, At, B1); PG8_BAR; PG8_SCHED;
;             PG8_LDA(At, 0, 1); PG8_STAGE(PG8_SB(0, 0), b2, voffB); PG8_STAGE(PG8_SB(0, 1), b2 + hstepB, voffB); PG8_STAGE(PG8_SA(0, 0), a2, voffA);
;             PG8_WAIT_V(8); PG8_WAIT_L(0); PG8_BAR; PG8_MMA(1, 0, At, B0); PG8_MMA(1, 1, At, B1); PG8_BAR; PG8_SCHED;
;             PG8_LDB(B0, 1, 0); PG8_LDB(B1, 1, 1); PG8_SCHED; PG8_LDA(At, 1, 0); PG8_STAGE(PG8_SA(0, 1), a2 + hstepA, voffA);
;             PG8_WAIT_V(8); PG8_WAIT_L(0); PG8_BAR; PG8_MMA(0, 0, At, B0); PG8_MMA(0, 1, At, B1); PG8_BAR; PG8_SCHED;
;             PG8_LDA(At, 1, 1); PG8_STAGE(PG8_SB(1, 0), b3, voffB); PG8_STAGE(PG8_SB(1, 1), b3 + hstepB, voffB); PG8_STAGE(PG8_SA(1, 0), a3, voffA);
;             PG8_WAIT_V(8); PG8_WAIT_L(0); PG8_BAR; PG8_MMA(1, 0, At, B0); PG8_MMA(1, 1, At, B1); PG8_BAR; PG8_SCHED;
.LBB0_1218:
	ds_read_b128 v[154:157], v141
	ds_read_b128 v[158:161], v141 offset:1024
	ds_read_b128 v[162:165], v141 offset:2048
	ds_read_b128 v[166:169], v141 offset:3072
	ds_read_b128 v[170:173], v142
	ds_read_b128 v[174:177], v142 offset:1024
	ds_read_b128 v[180:183], v142 offset:2048
	ds_read_b128 v[184:187], v142 offset:3072
	s_add_u32 s36, s34, 0x100
	s_addc_u32 s37, s35, 0
	s_cmp_eq_u32 s64, 28
	s_cselect_b32 s42, s5, s36
	s_cselect_b32 s43, s3, s37
	s_cselect_b32 s40, s7, s19
	s_cselect_b32 s41, s6, s27
	s_add_u32 s38, s42, 0x80
	s_addc_u32 s39, s43, 0
	ds_read_b128 v[188:191], v143
	ds_read_b128 v[192:195], v143 offset:1024
	ds_read_b128 v[196:199], v143 offset:2048
	ds_read_b128 v[204:207], v143 offset:3072
	ds_read_b128 v[208:211], v143 offset:4096
	ds_read_b128 v[212:215], v143 offset:5120
	ds_read_b128 v[216:219], v143 offset:6144
	ds_read_b128 v[220:223], v143 offset:7168
	s_add_u32 s34, s34, 0x80080
	s_addc_u32 s35, s35, 0
	s_mov_b32 m0, s61
	s_nop 0
	global_load_lds_dwordx4 v134, s[34:35]
	s_nop 0
	s_mov_b32 m0, s62
	s_nop 0
	global_load_lds_dwordx4 v136, s[34:35]
	s_waitcnt vmcnt(8)
	s_waitcnt lgkmcnt(0)
	s_barrier
	s_setprio 1
	v_mfma_f32_16x16x32_bf16 v[126:129], v[154:157], v[188:191], v[126:129]
	v_mfma_f32_16x16x32_bf16 v[122:125], v[162:165], v[188:191], v[122:125]
	v_mfma_f32_16x16x32_bf16 v[110:113], v[154:157], v[196:199], v[110:113]
	v_mfma_f32_16x16x32_bf16 v[106:109], v[162:165], v[196:199], v[106:109]
	v_mfma_f32_16x16x32_bf16 v[94:97], v[154:157], v[208:211], v[94:97]
	v_mfma_f32_16x16x32_bf16 v[90:93], v[162:165], v[208:211], v[90:93]
	v_mfma_f32_16x16x32_bf16 v[78:81], v[154:157], v[216:219], v[78:81]
	v_mfma_f32_16x16x32_bf16 v[74:77], v[162:165], v[216:219], v[74:77]
	v_mfma_f32_16x16x32_bf16 v[126:129], v[158:161], v[192:195], v[126:129]
	v_mfma_f32_16x16x32_bf16 v[122:125], v[166:169], v[192:195], v[122:125]
	v_mfma_f32_16x16x32_bf16 v[110:113], v[158:161], v[204:207], v[110:113]
	v_mfma_f32_16x16x32_bf16 v[106:109], v[166:169], v[204:207], v[106:109]
	v_mfma_f32_16x16x32_bf16 v[94:97], v[158:161], v[212:215], v[94:97]
	v_mfma_f32_16x16x32_bf16 v[90:93], v[166:169], v[212:215], v[90:93]
	v_mfma_f32_16x16x32_bf16 v[78:81], v[158:161], v[220:223], v[78:81]
	v_mfma_f32_16x16x32_bf16 v[74:77], v[166:169], v[220:223], v[74:77]
	v_mfma_f32_16x16x32_bf16 v[118:121], v[170:173], v[188:191], v[118:121]
	v_mfma_f32_16x16x32_bf16 v[114:117], v[180:183], v[188:191], v[114:117]
	v_mfma_f32_16x16x32_bf16 v[102:105], v[170:173], v[196:199], v[102:105]
	v_mfma_f32_16x16x32_bf16 v[98:101], v[180:183], v[196:199], v[98:101]
	v_mfma_f32_16x16x32_bf16 v[86:89], v[170:173], v[208:211], v[86:89]
	v_mfma_f32_16x16x32_bf16 v[82:85], v[180:183], v[208:211], v[82:85]
	v_mfma_f32_16x16x32_bf16 v[70:73], v[170:173], v[216:219], v[70:73]
	v_mfma_f32_16x16x32_bf16 v[66:69], v[180:183], v[216:219], v[66:69]
	v_mfma_f32_16x16x32_bf16 v[118:121], v[174:177], v[192:195], v[118:121]
	v_mfma_f32_16x16x32_bf16 v[114:117], v[184:187], v[192:195], v[114:117]
	v_mfma_f32_16x16x32_bf16 v[102:105], v[174:177], v[204:207], v[102:105]
	v_mfma_f32_16x16x32_bf16 v[98:101], v[184:187], v[204:207], v[98:101]
	v_mfma_f32_16x16x32_bf16 v[86:89], v[174:177], v[212:215], v[86:89]
	v_mfma_f32_16x16x32_bf16 v[82:85], v[184:187], v[212:215], v[82:85]
	v_mfma_f32_16x16x32_bf16 v[70:73], v[174:177], v[220:223], v[70:73]
	v_mfma_f32_16x16x32_bf16 v[66:69], v[184:187], v[220:223], v[66:69]
	s_setprio 0
	s_barrier
	ds_read_b128 v[188:191], v143 offset:16384
	ds_read_b128 v[192:195], v143 offset:17408
	ds_read_b128 v[196:199], v143 offset:18432
	ds_read_b128 v[204:207], v143 offset:19456
	ds_read_b128 v[208:211], v143 offset:20480
	ds_read_b128 v[212:215], v143 offset:21504
	ds_read_b128 v[216:219], v143 offset:22528
	ds_read_b128 v[220:223], v143 offset:23552
	s_mov_b32 m0, s47
	s_nop 0
	global_load_lds_dwordx4 v135, s[40:41]
	s_nop 0
	s_mov_b32 m0, s48
	s_nop 0
	global_load_lds_dwordx4 v137, s[40:41]
	s_add_u32 s34, s40, 0x80000
	s_addc_u32 s35, s41, 0
	s_mov_b32 m0, s49
	s_nop 0
	global_load_lds_dwordx4 v135, s[34:35]
	s_nop 0
	s_mov_b32 m0, s50
	s_nop 0
	global_load_lds_dwordx4 v137, s[34:35]
	s_mov_b32 m0, s45
	s_nop 0
	global_load_lds_dwordx4 v134, s[42:43]
	s_nop 0
	s_mov_b32 m0, s51
	s_nop 0
	global_load_lds_dwordx4 v136, s[42:43]
	s_waitcnt vmcnt(8)
	s_waitcnt lgkmcnt(0)
	s_barrier
	s_setprio 1
	v_mfma_f32_16x16x32_bf16 v[62:65], v[154:157], v[188:191], v[62:65]
	v_mfma_f32_16x16x32_bf16 v[58:61], v[162:165], v[188:191], v[58:61]
	v_mfma_f32_16x16x32_bf16 v[46:49], v[154:157], v[196:199], v[46:49]
	v_mfma_f32_16x16x32_bf16 v[42:45], v[162:165], v[196:199], v[42:45]
	v_mfma_f32_16x16x32_bf16 v[30:33], v[154:157], v[208:211], v[30:33]
	v_mfma_f32_16x16x32_bf16 v[26:29], v[162:165], v[208:211], v[26:29]
	v_mfma_f32_16x16x32_bf16 v[14:17], v[154:157], v[216:219], v[14:17]
	v_mfma_f32_16x16x32_bf16 v[10:13], v[162:165], v[216:219], v[10:13]
	v_mfma_f32_16x16x32_bf16 v[62:65], v[158:161], v[192:195], v[62:65]
	v_mfma_f32_16x16x32_bf16 v[58:61], v[166:169], v[192:195], v[58:61]
	v_mfma_f32_16x16x32_bf16 v[46:49], v[158:161], v[204:207], v[46:49]
	v_mfma_f32_16x16x32_bf16 v[42:45], v[166:169], v[204:207], v[42:45]
	v_mfma_f32_16x16x32_bf16 v[30:33], v[158:161], v[212:215], v[30:33]
	v_mfma_f32_16x16x32_bf16 v[26:29], v[166:169], v[212:215], v[26:29]
	v_mfma_f32_16x16x32_bf16 v[14:17], v[158:161], v[220:223], v[14:17]
	v_mfma_f32_16x16x32_bf16 v[10:13], v[166:169], v[220:223], v[10:13]
	v_mfma_f32_16x16x32_bf16 v[54:57], v[170:173], v[188:191], v[54:57]
	v_mfma_f32_16x16x32_bf16 v[50:53], v[180:183], v[188:191], v[50:53]
	v_mfma_f32_16x16x32_bf16 v[38:41], v[170:173], v[196:199], v[38:41]
	v_mfma_f32_16x16x32_bf16 v[34:37], v[180:183], v[196:199], v[34:37]
	v_mfma_f32_16x16x32_bf16 v[22:25], v[170:173], v[208:211], v[22:25]
	v_mfma_f32_16x16x32_bf16 v[18:21], v[180:183], v[208:211], v[18:21]
	v_mfma_f32_16x16x32_bf16 v[6:9], v[170:173], v[216:219], v[6:9]
	v_mfma_f32_16x16x32_bf16 v[2:5], v[180:183], v[216:219], v[2:5]
	v_mfma_f32_16x16x32_bf16 v[54:57], v[174:177], v[192:195], v[54:57]
	v_mfma_f32_16x16x32_bf16 v[50:53], v[184:187], v[192:195], v[50:53]
	v_mfma_f32_16x16x32_bf16 v[38:41], v[174:177], v[204:207], v[38:41]
	v_mfma_f32_16x16x32_bf16 v[34:37], v[184:187], v[204:207], v[34:37]
	v_mfma_f32_16x16x32_bf16 v[22:25], v[174:177], v[212:215], v[22:25]
	v_mfma_f32_16x16x32_bf16 v[18:21], v[184:187], v[212:215], v[18:21]
	v_mfma_f32_16x16x32_bf16 v[6:9], v[174:177], v[220:223], v[6:9]
	v_mfma_f32_16x16x32_bf16 v[2:5], v[184:187], v[220:223], v[2:5]
	s_setprio 0
	s_barrier
; #define PG8_STAGE(bufoff, gbase, voff) do { _Pragma("unroll") for (int _i = 0; _i < 2; ++_i) { unsigned keep_; \
;         asm volatile("s_mov_b32 %0, m0\n\ts_mov_b32 m0, %3\n\ts_nop 0\n\tglobal_load_lds_dwordx4 %1, %2\n\ts_mov_b32 m0, %0" \
;             : "=&s"(keep_) : "v"((voff)[_i]), "s"((const void*)(gbase)), "s"(ldsb0 + (unsigned)(bufoff) + (unsigned)(_i * 8192)) : "memory"); } } while (0)
; #define PG8_LDA(dst, b, h) do { _Pragma("unroll") for (int m = 0; m < 4; ++m) _Pragma("unroll") for (int k = 0; k < 2; ++k) dst[m][k] = *(const LAS bf16x8*)(lds + PG8_SA(b, h) + aoff + m * 2048 + k * 1024); } while (0)
; #define PG8_LDB(dst, b, h) do { _Pragma("unroll") for (int n = 0; n < 2; ++n) _Pragma("unroll") for (int k = 0; k < 2; ++k) dst[n][k] = *(const LAS bf16x8*)(lds + PG8_SB(b, h) + boff + n * 2048 + k * 1024); } while (0)
; template <class Epi, class Sched, bool ALIGN_EPI>
; __device__ __forceinline__ void gemm_phase(LAS unsigned char* lds, const Gemm g, const Sched& S, const Epi& E) {
;     ...
;         for (int t = 0; t < nt; t += 2) {
;             const bool last = (t == nt - 2);
;             const char* a1 = cA + (size_t)(t + 1) * kstep;
;             const char* a2 = last ? nA : cA + (size_t)(t + 2) * kstep; const char* b2 = last ? nB : cB + (size_t)(t + 2) * kstep;
;             const char* a3 = a2 + kstep; const char* b3 = b2 + kstep;
;             PG8_LDB(B0, 0, 0); PG8_LDB(B1, 0, 1); PG8_SCHED; PG8_LDA(At, 0, 0); PG8_STAGE(PG8_SA(1, 1), a1 + hstepA, voffA);
;             PG8_WAIT_V(8); PG8_WAIT_L(0); PG8_BAR; PG8_MMA(0, 0, At, B0); PG8_MMA(0, 1, At, B1); PG8_BAR; PG8_SCHED;
;             PG8_LDA(At, 0, 1); PG8_STAGE(PG8_SB(0, 0), b2, voffB); PG8_STAGE(PG8_SB(0, 1), b2 + hstepB, voffB); PG8_STAGE(PG8_SA(0, 0), a2, voffA);
;             PG8_WAIT_V(8); PG8_WAIT_L(0); PG8_BAR; PG8_MMA(1, 0, At, B0); PG8_MMA(1, 1, At, B1); PG8_BAR; PG8_SCHED;
;             PG8_LDB(B0, 1, 0); PG8_LDB(B1, 1, 1); PG8_SCHED; PG8_LDA(At, 1, 0); PG8_STAGE(PG8_SA(0, 1), a2 + hstepA, voffA);
;             PG8_WAIT_V(8); PG8_WAIT_L(0); PG8_BAR; PG8_MMA(0, 0, At, B0); PG8_MMA(0, 1, At, B1); PG8_BAR; PG8_SCHED;
;             PG8_LDA(At, 1, 1); PG8_STAGE(PG8_SB(1, 0), b3, voffB); PG8_STAGE(PG8_SB(1, 1), b3 + hstepB, voffB); PG8_STAGE(PG8_SA(1, 0), a3, voffA);
;             PG8_WAIT_V(8); PG8_WAIT_L(0); PG8_BAR; PG8_MMA(1, 0, At, B0); PG8_MMA(1, 1, At, B1); PG8_BAR; PG8_SCHED;
	ds_read_b128 v[154:157], v144
	ds_read_b128 v[158:161], v144 offset:1024
	ds_read_b128 v[162:165], v144 offset:2048
	ds_read_b128 v[166:169], v144 offset:3072
	ds_read_b128 v[170:173], v145
	ds_read_b128 v[174:177], v145 offset:1024
	ds_read_b128 v[180:183], v145 offset:2048
	ds_read_b128 v[184:187], v145 offset:3072
	ds_read_b128 v[188:191], v143 offset:32768
	ds_read_b128 v[192:195], v143 offset:33792
	ds_read_b128 v[196:199], v143 offset:34816
	ds_read_b128 v[204:207], v143 offset:35840
	ds_read_b128 v[208:211], v143 offset:36864
	ds_read_b128 v[212:215], v143 offset:37888
	ds_read_b128 v[216:219], v143 offset:38912
	ds_read_b128 v[220:223], v143 offset:39936
	s_add_u32 s34, s42, 0x80000
	s_addc_u32 s35, s43, 0
	s_mov_b32 m0, s52
	s_nop 0
	global_load_lds_dwordx4 v134, s[34:35]
	s_nop 0
	s_mov_b32 m0, s53
	s_nop 0
	global_load_lds_dwordx4 v136, s[34:35]
	s_waitcnt vmcnt(8)
	s_waitcnt lgkmcnt(0)
	s_barrier
	s_setprio 1
	v_mfma_f32_16x16x32_bf16 v[126:129], v[154:157], v[188:191], v[126:129]
	v_mfma_f32_16x16x32_bf16 v[122:125], v[162:165], v[188:191], v[122:125]
	v_mfma_f32_16x16x32_bf16 v[110:113], v[154:157], v[196:199], v[110:113]
	v_mfma_f32_16x16x32_bf16 v[106:109], v[162:165], v[196:199], v[106:109]
	v_mfma_f32_16x16x32_bf16 v[94:97], v[154:157], v[208:211], v[94:97]
	v_mfma_f32_16x16x32_bf16 v[90:93], v[162:165], v[208:211], v[90:93]
	v_mfma_f32_16x16x32_bf16 v[78:81], v[154:157], v[216:219], v[78:81]
	v_mfma_f32_16x16x32_bf16 v[74:77], v[162:165], v[216:219], v[74:77]
	v_mfma_f32_16x16x32_bf16 v[126:129], v[158:161], v[192:195], v[126:129]
	v_mfma_f32_16x16x32_bf16 v[122:125], v[166:169], v[192:195], v[122:125]
	v_mfma_f32_16x16x32_bf16 v[110:113], v[158:161], v[204:207], v[110:113]
	v_mfma_f32_16x16x32_bf16 v[106:109], v[166:169], v[204:207], v[106:109]
	v_mfma_f32_16x16x32_bf16 v[94:97], v[158:161], v[212:215], v[94:97]
	v_mfma_f32_16x16x32_bf16 v[90:93], v[166:169], v[212:215], v[90:93]
	v_mfma_f32_16x16x32_bf16 v[78:81], v[158:161], v[220:223], v[78:81]
	v_mfma_f32_16x16x32_bf16 v[74:77], v[166:169], v[220:223], v[74:77]
	v_mfma_f32_16x16x32_bf16 v[118:121], v[170:173], v[188:191], v[118:121]
	v_mfma_f32_16x16x32_bf16 v[114:117], v[180:183], v[188:191], v[114:117]
	v_mfma_f32_16x16x32_bf16 v[102:105], v[170:173], v[196:199], v[102:105]
	v_mfma_f32_16x16x32_bf16 v[98:101], v[180:183], v[196:199], v[98:101]
	v_mfma_f32_16x16x32_bf16 v[86:89], v[170:173], v[208:211], v[86:89]
	v_mfma_f32_16x16x32_bf16 v[82:85], v[180:183], v[208:211], v[82:85]
	v_mfma_f32_16x16x32_bf16 v[70:73], v[170:173], v[216:219], v[70:73]
	v_mfma_f32_16x16x32_bf16 v[66:69], v[180:183], v[216:219], v[66:69]
	v_mfma_f32_16x16x32_bf16 v[118:121], v[174:177], v[192:195], v[118:121]
	v_mfma_f32_16x16x32_bf16 v[114:117], v[184:187], v[192:195], v[114:117]
	v_mfma_f32_16x16x32_bf16 v[102:105], v[174:177], v[204:207], v[102:105]
	v_mfma_f32_16x16x32_bf16 v[98:101], v[184:187], v[204:207], v[98:101]
	v_mfma_f32_16x16x32_bf16 v[86:89], v[174:177], v[212:215], v[86:89]
	v_mfma_f32_16x16x32_bf16 v[82:85], v[184:187], v[212:215], v[82:85]
	v_mfma_f32_16x16x32_bf16 v[70:73], v[174:177], v[220:223], v[70:73]
	v_mfma_f32_16x16x32_bf16 v[66:69], v[184:187], v[220:223], v[66:69]
	s_setprio 0
	s_barrier
	ds_read_b128 v[188:191], v143 offset:49152
	ds_read_b128 v[192:195], v143 offset:50176
	ds_read_b128 v[196:199], v143 offset:51200
	ds_read_b128 v[204:207], v143 offset:52224
	ds_read_b128 v[208:211], v143 offset:53248
	ds_read_b128 v[212:215], v143 offset:54272
	ds_read_b128 v[216:219], v143 offset:55296
	ds_read_b128 v[220:223], v143 offset:56320
	s_add_u32 s34, s40, 0x80
	s_addc_u32 s35, s41, 0
	s_mov_b32 m0, s54
	s_nop 0
	global_load_lds_dwordx4 v135, s[34:35]
	s_nop 0
	s_mov_b32 m0, s55
	s_nop 0
	global_load_lds_dwordx4 v137, s[34:35]
	s_add_u32 s34, s40, 0x80080
	s_addc_u32 s35, s41, 0
	s_mov_b32 m0, s58
	s_nop 0
	global_load_lds_dwordx4 v135, s[34:35]
	s_nop 0
	s_mov_b32 m0, s59
	s_nop 0
	global_load_lds_dwordx4 v137, s[34:35]
	s_mov_b32 m0, s56
	s_nop 0
	global_load_lds_dwordx4 v134, s[38:39]
	s_nop 0
	s_mov_b32 m0, s57
	s_nop 0
	global_load_lds_dwordx4 v136, s[38:39]
	s_waitcnt vmcnt(8)
	s_waitcnt lgkmcnt(0)
	s_barrier
	s_setprio 1
	v_mfma_f32_16x16x32_bf16 v[62:65], v[154:157], v[188:191], v[62:65]
	v_mfma_f32_16x16x32_bf16 v[58:61], v[162:165], v[188:191], v[58:61]
	v_mfma_f32_16x16x32_bf16 v[46:49], v[154:157], v[196:199], v[46:49]
	v_mfma_f32_16x16x32_bf16 v[42:45], v[162:165], v[196:199], v[42:45]
	s_add_i32 s64, s64, 2
	s_add_u32 s19, s19, 0x100
	s_addc_u32 s27, s27, 0
	s_cmp_gt_u32 s64, 29
	s_mov_b64 s[34:35], s[36:37]
	v_mfma_f32_16x16x32_bf16 v[30:33], v[154:157], v[208:211], v[30:33]
	v_mfma_f32_16x16x32_bf16 v[26:29], v[162:165], v[208:211], v[26:29]
	v_mfma_f32_16x16x32_bf16 v[14:17], v[154:157], v[216:219], v[14:17]
	v_mfma_f32_16x16x32_bf16 v[10:13], v[162:165], v[216:219], v[10:13]
	v_mfma_f32_16x16x32_bf16 v[62:65], v[158:161], v[192:195], v[62:65]
	v_mfma_f32_16x16x32_bf16 v[58:61], v[166:169], v[192:195], v[58:61]
	v_mfma_f32_16x16x32_bf16 v[46:49], v[158:161], v[204:207], v[46:49]
	v_mfma_f32_16x16x32_bf16 v[42:45], v[166:169], v[204:207], v[42:45]
	v_mfma_f32_16x16x32_bf16 v[30:33], v[158:161], v[212:215], v[30:33]
	v_mfma_f32_16x16x32_bf16 v[26:29], v[166:169], v[212:215], v[26:29]
	v_mfma_f32_16x16x32_bf16 v[14:17], v[158:161], v[220:223], v[14:17]
	v_mfma_f32_16x16x32_bf16 v[10:13], v[166:169], v[220:223], v[10:13]
	v_mfma_f32_16x16x32_bf16 v[54:57], v[170:173], v[188:191], v[54:57]
	v_mfma_f32_16x16x32_bf16 v[50:53], v[180:183], v[188:191], v[50:53]
	v_mfma_f32_16x16x32_bf16 v[38:41], v[170:173], v[196:199], v[38:41]
	v_mfma_f32_16x16x32_bf16 v[34:37], v[180:183], v[196:199], v[34:37]
	v_mfma_f32_16x16x32_bf16 v[22:25], v[170:173], v[208:211], v[22:25]
	v_mfma_f32_16x16x32_bf16 v[18:21], v[180:183], v[208:211], v[18:21]
	v_mfma_f32_16x16x32_bf16 v[6:9], v[170:173], v[216:219], v[6:9]
	v_mfma_f32_16x16x32_bf16 v[2:5], v[180:183], v[216:219], v[2:5]
	v_mfma_f32_16x16x32_bf16 v[54:57], v[174:177], v[192:195], v[54:57]
	v_mfma_f32_16x16x32_bf16 v[50:53], v[184:187], v[192:195], v[50:53]
	v_mfma_f32_16x16x32_bf16 v[38:41], v[174:177], v[204:207], v[38:41]
	v_mfma_f32_16x16x32_bf16 v[34:37], v[184:187], v[204:207], v[34:37]
	v_mfma_f32_16x16x32_bf16 v[22:25], v[174:177], v[212:215], v[22:25]
	v_mfma_f32_16x16x32_bf16 v[18:21], v[184:187], v[212:215], v[18:21]
	v_mfma_f32_16x16x32_bf16 v[6:9], v[174:177], v[220:223], v[6:9]
	v_mfma_f32_16x16x32_bf16 v[2:5], v[184:187], v[220:223], v[2:5]
	s_setprio 0
	s_barrier
	s_cbranch_scc0 .LBB0_1218
	s_and_b64 vcc, exec, s[16:17]
	s_cbranch_vccz .LBB0_1221
	s_barrier

; #define PG8_STAGE(bufoff, gbase, voff) do { _Pragma("unroll") for (int _i = 0; _i < 2; ++_i) { unsigned keep_; \
;         asm volatile("s_mov_b32 %0, m0\n\ts_mov_b32 m0, %3\n\ts_nop 0\n\tglobal_load_lds_dwordx4 %1, %2\n\ts_mov_b32 m0, %0" \
;             : "=&s"(keep_) : "v"((voff)[_i]), "s"((const void*)(gbase)), "s"(ldsb0 + (unsigned)(bufoff) + (unsigned)(_i * 8192)) : "memory"); } } while (0)
; #define PG8_LDA(dst, b, h) do { _Pragma("unroll") for (int m = 0; m < 4; ++m) _Pragma("unroll") for (int k = 0; k < 2; ++k) dst[m][k] = *(const LAS bf16x8*)(lds + PG8_SA(b, h) + aoff + m * 2048 + k * 1024); } while (0)
; #define PG8_LDB(dst, b, h) do { _Pragma("unroll") for (int n = 0; n < 2; ++n) _Pragma("unroll") for (int k = 0; k < 2; ++k) dst[n][k] = *(const LAS bf16x8*)(lds + PG8_SB(b, h) + boff + n * 2048 + k * 1024); } while (0)
; template <class Epi, class Sched, bool ALIGN_EPI>
; __device__ __forceinline__ void gemm_phase(LAS unsigned char* lds, const Gemm g, const Sched& S, const Epi& E) {
;     ...
;         for (int t = 0; t < nt; t += 2) {
;             const bool last = (t == nt - 2);
;             const char* a1 = cA + (size_t)(t + 1) * kstep;
;             const char* a2 = last ? nA : cA + (size_t)(t + 2) * kstep; const char* b2 = last ? nB : cB + (size_t)(t + 2) * kstep;
;             const char* a3 = a2 + kstep; const char* b3 = b2 + kstep;
;             PG8_LDB(B0, 0, 0); PG8_LDB(B1, 0, 1); PG8_SCHED; PG8_LDA(At, 0, 0); PG8_STAGE(PG8_SA(1, 1), a1 + hstepA, voffA);
;             PG8_WAIT_V(8); PG8_WAIT_L(0); PG8_BAR; PG8_MMA(0, 0, At, B0); PG8_MMA(0, 1, At, B1); PG8_BAR; PG8_SCHED;
;             PG8_LDA(At, 0, 1); PG8_STAGE(PG8_SB(0, 0), b2, voffB); PG8_STAGE(PG8_SB(0, 1), b2 + hstepB, voffB); PG8_STAGE(PG8_SA(0, 0), a2, voffA);
;             PG8_WAIT_V(8); PG8_WAIT_L(0); PG8_BAR; PG8_MMA(1, 0, At, B0); PG8_MMA(1, 1, At, B1); PG8_BAR; PG8_SCHED;
;             PG8_LDB(B0, 1, 0); PG8_LDB(B1, 1, 1); PG8_SCHED; PG8_LDA(At, 1, 0); PG8_STAGE(PG8_SA(0, 1), a2 + hstepA, voffA);
;             PG8_WAIT_V(8); PG8_WAIT_L(0); PG8_BAR; PG8_MMA(0, 0, At, B0); PG8_MMA(0, 1, At, B1); PG8_BAR; PG8_SCHED;
;             PG8_LDA(At, 1, 1); PG8_STAGE(PG8_SB(1, 0), b3, voffB); PG8_STAGE(PG8_SB(1, 1), b3 + hstepB, voffB); PG8_STAGE(PG8_SA(1, 0), a3, voffA);
;             PG8_WAIT_V(8); PG8_WAIT_L(0); PG8_BAR; PG8_MMA(1, 0, At, B0); PG8_MMA(1, 1, At, B1); PG8_BAR; PG8_SCHED;
.LBB0_1317:
	ds_read_b128 v[110:113], v206
	ds_read_b128 v[126:129], v206 offset:1024
	ds_read_b128 v[130:133], v206 offset:2048
	ds_read_b128 v[142:145], v206 offset:3072
	ds_read_b128 v[146:149], v207
	ds_read_b128 v[150:153], v207 offset:1024
	ds_read_b128 v[154:157], v207 offset:2048
	ds_read_b128 v[158:161], v207 offset:3072
	s_cmpk_eq_i32 s58, 0x54
	s_cselect_b32 s34, s14, s6
	s_cselect_b32 s35, s15, s7
	s_cselect_b32 s30, s26, s56
	s_cselect_b32 s31, s27, s57
	s_add_u32 s28, s34, 0x80
	s_addc_u32 s29, s35, 0
	ds_read_b128 v[162:165], v208
	ds_read_b128 v[166:169], v208 offset:1024
	ds_read_b128 v[170:173], v208 offset:2048
	ds_read_b128 v[174:177], v208 offset:3072
	ds_read_b128 v[188:191], v208 offset:4096
	ds_read_b128 v[192:195], v208 offset:5120
	ds_read_b128 v[196:199], v208 offset:6144
	ds_read_b128 v[212:215], v208 offset:7168
	s_mov_b32 m0, s52
	s_nop 0
	global_load_lds_dwordx4 v179, s[4:5]
	s_nop 0
	s_mov_b32 m0, s53
	s_nop 0
	global_load_lds_dwordx4 v201, s[4:5]
	s_waitcnt vmcnt(8)
	s_waitcnt lgkmcnt(0)
	s_barrier
	s_setprio 1
	v_mfma_f32_16x16x32_bf16 v[138:141], v[110:113], v[162:165], v[138:141]
	v_mfma_f32_16x16x32_bf16 v[134:137], v[130:133], v[162:165], v[134:137]
	v_mfma_f32_16x16x32_bf16 v[114:117], v[110:113], v[170:173], v[114:117]
	v_mfma_f32_16x16x32_bf16 v[106:109], v[130:133], v[170:173], v[106:109]
	v_mfma_f32_16x16x32_bf16 v[94:97], v[110:113], v[188:191], v[94:97]
	v_mfma_f32_16x16x32_bf16 v[90:93], v[130:133], v[188:191], v[90:93]
	v_mfma_f32_16x16x32_bf16 v[78:81], v[110:113], v[196:199], v[78:81]
	v_mfma_f32_16x16x32_bf16 v[74:77], v[130:133], v[196:199], v[74:77]
	v_mfma_f32_16x16x32_bf16 v[138:141], v[126:129], v[166:169], v[138:141]
	v_mfma_f32_16x16x32_bf16 v[134:137], v[142:145], v[166:169], v[134:137]
	v_mfma_f32_16x16x32_bf16 v[114:117], v[126:129], v[174:177], v[114:117]
	v_mfma_f32_16x16x32_bf16 v[106:109], v[142:145], v[174:177], v[106:109]
	v_mfma_f32_16x16x32_bf16 v[94:97], v[126:129], v[192:195], v[94:97]
	v_mfma_f32_16x16x32_bf16 v[90:93], v[142:145], v[192:195], v[90:93]
	v_mfma_f32_16x16x32_bf16 v[78:81], v[126:129], v[212:215], v[78:81]
	v_mfma_f32_16x16x32_bf16 v[74:77], v[142:145], v[212:215], v[74:77]
	v_mfma_f32_16x16x32_bf16 v[122:125], v[146:149], v[162:165], v[122:125]
	v_mfma_f32_16x16x32_bf16 v[118:121], v[154:157], v[162:165], v[118:121]
	v_mfma_f32_16x16x32_bf16 v[102:105], v[146:149], v[170:173], v[102:105]
	v_mfma_f32_16x16x32_bf16 v[98:101], v[154:157], v[170:173], v[98:101]
	v_mfma_f32_16x16x32_bf16 v[86:89], v[146:149], v[188:191], v[86:89]
	v_mfma_f32_16x16x32_bf16 v[82:85], v[154:157], v[188:191], v[82:85]
	v_mfma_f32_16x16x32_bf16 v[70:73], v[146:149], v[196:199], v[70:73]
	v_mfma_f32_16x16x32_bf16 v[66:69], v[154:157], v[196:199], v[66:69]
	v_mfma_f32_16x16x32_bf16 v[122:125], v[150:153], v[166:169], v[122:125]
	v_mfma_f32_16x16x32_bf16 v[118:121], v[158:161], v[166:169], v[118:121]
	v_mfma_f32_16x16x32_bf16 v[102:105], v[150:153], v[174:177], v[102:105]
	v_mfma_f32_16x16x32_bf16 v[98:101], v[158:161], v[174:177], v[98:101]
	v_mfma_f32_16x16x32_bf16 v[86:89], v[150:153], v[192:195], v[86:89]
	v_mfma_f32_16x16x32_bf16 v[82:85], v[158:161], v[192:195], v[82:85]
	v_mfma_f32_16x16x32_bf16 v[70:73], v[150:153], v[212:215], v[70:73]
	v_mfma_f32_16x16x32_bf16 v[66:69], v[158:161], v[212:215], v[66:69]
	s_setprio 0
	s_barrier
	ds_read_b128 v[162:165], v208 offset:16384
	ds_read_b128 v[166:169], v208 offset:17408
	ds_read_b128 v[170:173], v208 offset:18432
	ds_read_b128 v[174:177], v208 offset:19456
	ds_read_b128 v[188:191], v208 offset:20480
	ds_read_b128 v[192:195], v208 offset:21504
	ds_read_b128 v[196:199], v208 offset:22528
	ds_read_b128 v[212:215], v208 offset:23552
	s_mov_b32 m0, s39
	s_nop 0
	global_load_lds_dwordx4 v200, s[30:31]
	s_add_u32 s62, s30, 0x160000
	s_mov_b32 m0, s40
	s_nop 0
	global_load_lds_dwordx4 v203, s[30:31]
	s_addc_u32 s63, s31, 0
	s_mov_b32 m0, s41
	s_nop 0
	global_load_lds_dwordx4 v200, s[62:63]
	s_nop 0
	s_mov_b32 m0, s42
	s_nop 0
	global_load_lds_dwordx4 v203, s[62:63]
	s_nop 0
	s_mov_b32 m0, s38
	s_nop 0
	global_load_lds_dwordx4 v179, s[34:35]
	s_nop 0
	s_mov_b32 m0, s43
	s_nop 0
	global_load_lds_dwordx4 v201, s[34:35]
	s_waitcnt vmcnt(8)
	s_waitcnt lgkmcnt(0)
	s_barrier
	s_setprio 1
	v_mfma_f32_16x16x32_bf16 v[62:65], v[110:113], v[162:165], v[62:65]
	v_mfma_f32_16x16x32_bf16 v[58:61], v[130:133], v[162:165], v[58:61]
	v_mfma_f32_16x16x32_bf16 v[46:49], v[110:113], v[170:173], v[46:49]
	v_mfma_f32_16x16x32_bf16 v[42:45], v[130:133], v[170:173], v[42:45]
	v_mfma_f32_16x16x32_bf16 v[30:33], v[110:113], v[188:191], v[30:33]
	v_mfma_f32_16x16x32_bf16 v[26:29], v[130:133], v[188:191], v[26:29]
	v_mfma_f32_16x16x32_bf16 v[14:17], v[110:113], v[196:199], v[14:17]
	v_mfma_f32_16x16x32_bf16 v[10:13], v[130:133], v[196:199], v[10:13]
	v_mfma_f32_16x16x32_bf16 v[62:65], v[126:129], v[166:169], v[62:65]
	v_mfma_f32_16x16x32_bf16 v[58:61], v[142:145], v[166:169], v[58:61]
	v_mfma_f32_16x16x32_bf16 v[46:49], v[126:129], v[174:177], v[46:49]
	v_mfma_f32_16x16x32_bf16 v[42:45], v[142:145], v[174:177], v[42:45]
	v_mfma_f32_16x16x32_bf16 v[30:33], v[126:129], v[192:195], v[30:33]
	v_mfma_f32_16x16x32_bf16 v[26:29], v[142:145], v[192:195], v[26:29]
	v_mfma_f32_16x16x32_bf16 v[14:17], v[126:129], v[212:215], v[14:17]
	v_mfma_f32_16x16x32_bf16 v[10:13], v[142:145], v[212:215], v[10:13]
	v_mfma_f32_16x16x32_bf16 v[54:57], v[146:149], v[162:165], v[54:57]
	v_mfma_f32_16x16x32_bf16 v[50:53], v[154:157], v[162:165], v[50:53]
	v_mfma_f32_16x16x32_bf16 v[38:41], v[146:149], v[170:173], v[38:41]
	v_mfma_f32_16x16x32_bf16 v[34:37], v[154:157], v[170:173], v[34:37]
	v_mfma_f32_16x16x32_bf16 v[22:25], v[146:149], v[188:191], v[22:25]
	v_mfma_f32_16x16x32_bf16 v[18:21], v[154:157], v[188:191], v[18:21]
	v_mfma_f32_16x16x32_bf16 v[6:9], v[146:149], v[196:199], v[6:9]
	v_mfma_f32_16x16x32_bf16 v[2:5], v[154:157], v[196:199], v[2:5]
	v_mfma_f32_16x16x32_bf16 v[54:57], v[150:153], v[166:169], v[54:57]
	v_mfma_f32_16x16x32_bf16 v[50:53], v[158:161], v[166:169], v[50:53]
	v_mfma_f32_16x16x32_bf16 v[38:41], v[150:153], v[174:177], v[38:41]
	v_mfma_f32_16x16x32_bf16 v[34:37], v[158:161], v[174:177], v[34:37]
	v_mfma_f32_16x16x32_bf16 v[22:25], v[150:153], v[192:195], v[22:25]
	v_mfma_f32_16x16x32_bf16 v[18:21], v[158:161], v[192:195], v[18:21]
	v_mfma_f32_16x16x32_bf16 v[6:9], v[150:153], v[212:215], v[6:9]
	v_mfma_f32_16x16x32_bf16 v[2:5], v[158:161], v[212:215], v[2:5]
	s_setprio 0
	s_barrier
; #define PG8_STAGE(bufoff, gbase, voff) do { _Pragma("unroll") for (int _i = 0; _i < 2; ++_i) { unsigned keep_; \
;         asm volatile("s_mov_b32 %0, m0\n\ts_mov_b32 m0, %3\n\ts_nop 0\n\tglobal_load_lds_dwordx4 %1, %2\n\ts_mov_b32 m0, %0" \
;             : "=&s"(keep_) : "v"((voff)[_i]), "s"((const void*)(gbase)), "s"(ldsb0 + (unsigned)(bufoff) + (unsigned)(_i * 8192)) : "memory"); } } while (0)
; #define PG8_LDA(dst, b, h) do { _Pragma("unroll") for (int m = 0; m < 4; ++m) _Pragma("unroll") for (int k = 0; k < 2; ++k) dst[m][k] = *(const LAS bf16x8*)(lds + PG8_SA(b, h) + aoff + m * 2048 + k * 1024); } while (0)
; #define PG8_LDB(dst, b, h) do { _Pragma("unroll") for (int n = 0; n < 2; ++n) _Pragma("unroll") for (int k = 0; k < 2; ++k) dst[n][k] = *(const LAS bf16x8*)(lds + PG8_SB(b, h) + boff + n * 2048 + k * 1024); } while (0)
; template <class Epi, class Sched, bool ALIGN_EPI>
; __device__ __forceinline__ void gemm_phase(LAS unsigned char* lds, const Gemm g, const Sched& S, const Epi& E) {
;     ...
;         for (int t = 0; t < nt; t += 2) {
;             const bool last = (t == nt - 2);
;             const char* a1 = cA + (size_t)(t + 1) * kstep;
;             const char* a2 = last ? nA : cA + (size_t)(t + 2) * kstep; const char* b2 = last ? nB : cB + (size_t)(t + 2) * kstep;
;             const char* a3 = a2 + kstep; const char* b3 = b2 + kstep;
;             PG8_LDB(B0, 0, 0); PG8_LDB(B1, 0, 1); PG8_SCHED; PG8_LDA(At, 0, 0); PG8_STAGE(PG8_SA(1, 1), a1 + hstepA, voffA);
;             PG8_WAIT_V(8); PG8_WAIT_L(0); PG8_BAR; PG8_MMA(0, 0, At, B0); PG8_MMA(0, 1, At, B1); PG8_BAR; PG8_SCHED;
;             PG8_LDA(At, 0, 1); PG8_STAGE(PG8_SB(0, 0), b2, voffB); PG8_STAGE(PG8_SB(0, 1), b2 + hstepB, voffB); PG8_STAGE(PG8_SA(0, 0), a2, voffA);
;             PG8_WAIT_V(8); PG8_WAIT_L(0); PG8_BAR; PG8_MMA(1, 0, At, B0); PG8_MMA(1, 1, At, B1); PG8_BAR; PG8_SCHED;
;             PG8_LDB(B0, 1, 0); PG8_LDB(B1, 1, 1); PG8_SCHED; PG8_LDA(At, 1, 0); PG8_STAGE(PG8_SA(0, 1), a2 + hstepA, voffA);
;             PG8_WAIT_V(8); PG8_WAIT_L(0); PG8_BAR; PG8_MMA(0, 0, At, B0); PG8_MMA(0, 1, At, B1); PG8_BAR; PG8_SCHED;
;             PG8_LDA(At, 1, 1); PG8_STAGE(PG8_SB(1, 0), b3, voffB); PG8_STAGE(PG8_SB(1, 1), b3 + hstepB, voffB); PG8_STAGE(PG8_SA(1, 0), a3, voffA);
;             PG8_WAIT_V(8); PG8_WAIT_L(0); PG8_BAR; PG8_MMA(1, 0, At, B0); PG8_MMA(1, 1, At, B1); PG8_BAR; PG8_SCHED;
	ds_read_b128 v[110:113], v209
	ds_read_b128 v[126:129], v209 offset:1024
	ds_read_b128 v[130:133], v209 offset:2048
	ds_read_b128 v[142:145], v209 offset:3072
	ds_read_b128 v[146:149], v210
	ds_read_b128 v[150:153], v210 offset:1024
	ds_read_b128 v[154:157], v210 offset:2048
	ds_read_b128 v[158:161], v210 offset:3072
	ds_read_b128 v[162:165], v208 offset:32768
	ds_read_b128 v[166:169], v208 offset:33792
	ds_read_b128 v[170:173], v208 offset:34816
	ds_read_b128 v[174:177], v208 offset:35840
	ds_read_b128 v[188:191], v208 offset:36864
	ds_read_b128 v[192:195], v208 offset:37888
	ds_read_b128 v[196:199], v208 offset:38912
	ds_read_b128 v[212:215], v208 offset:39936
	s_add_u32 s34, s34, 0x160000
	s_addc_u32 s35, s35, 0
	s_mov_b32 m0, s44
	s_nop 0
	global_load_lds_dwordx4 v179, s[34:35]
	s_nop 0
	s_mov_b32 m0, s45
	s_nop 0
	global_load_lds_dwordx4 v201, s[34:35]
	s_waitcnt vmcnt(8)
	s_waitcnt lgkmcnt(0)
	s_barrier
	s_setprio 1
	v_mfma_f32_16x16x32_bf16 v[138:141], v[110:113], v[162:165], v[138:141]
	v_mfma_f32_16x16x32_bf16 v[134:137], v[130:133], v[162:165], v[134:137]
	v_mfma_f32_16x16x32_bf16 v[114:117], v[110:113], v[170:173], v[114:117]
	v_mfma_f32_16x16x32_bf16 v[106:109], v[130:133], v[170:173], v[106:109]
	v_mfma_f32_16x16x32_bf16 v[94:97], v[110:113], v[188:191], v[94:97]
	v_mfma_f32_16x16x32_bf16 v[90:93], v[130:133], v[188:191], v[90:93]
	v_mfma_f32_16x16x32_bf16 v[78:81], v[110:113], v[196:199], v[78:81]
	v_mfma_f32_16x16x32_bf16 v[74:77], v[130:133], v[196:199], v[74:77]
	v_mfma_f32_16x16x32_bf16 v[138:141], v[126:129], v[166:169], v[138:141]
	v_mfma_f32_16x16x32_bf16 v[134:137], v[142:145], v[166:169], v[134:137]
	v_mfma_f32_16x16x32_bf16 v[114:117], v[126:129], v[174:177], v[114:117]
	v_mfma_f32_16x16x32_bf16 v[106:109], v[142:145], v[174:177], v[106:109]
	v_mfma_f32_16x16x32_bf16 v[94:97], v[126:129], v[192:195], v[94:97]
	v_mfma_f32_16x16x32_bf16 v[90:93], v[142:145], v[192:195], v[90:93]
	v_mfma_f32_16x16x32_bf16 v[78:81], v[126:129], v[212:215], v[78:81]
	v_mfma_f32_16x16x32_bf16 v[74:77], v[142:145], v[212:215], v[74:77]
	v_mfma_f32_16x16x32_bf16 v[122:125], v[146:149], v[162:165], v[122:125]
	v_mfma_f32_16x16x32_bf16 v[118:121], v[154:157], v[162:165], v[118:121]
	v_mfma_f32_16x16x32_bf16 v[102:105], v[146:149], v[170:173], v[102:105]
	v_mfma_f32_16x16x32_bf16 v[98:101], v[154:157], v[170:173], v[98:101]
	v_mfma_f32_16x16x32_bf16 v[86:89], v[146:149], v[188:191], v[86:89]
	v_mfma_f32_16x16x32_bf16 v[82:85], v[154:157], v[188:191], v[82:85]
	v_mfma_f32_16x16x32_bf16 v[70:73], v[146:149], v[196:199], v[70:73]
	v_mfma_f32_16x16x32_bf16 v[66:69], v[154:157], v[196:199], v[66:69]
	v_mfma_f32_16x16x32_bf16 v[122:125], v[150:153], v[166:169], v[122:125]
	v_mfma_f32_16x16x32_bf16 v[118:121], v[158:161], v[166:169], v[118:121]
	v_mfma_f32_16x16x32_bf16 v[102:105], v[150:153], v[174:177], v[102:105]
	v_mfma_f32_16x16x32_bf16 v[98:101], v[158:161], v[174:177], v[98:101]
	v_mfma_f32_16x16x32_bf16 v[86:89], v[150:153], v[192:195], v[86:89]
	v_mfma_f32_16x16x32_bf16 v[82:85], v[158:161], v[192:195], v[82:85]
	v_mfma_f32_16x16x32_bf16 v[70:73], v[150:153], v[212:215], v[70:73]
	v_mfma_f32_16x16x32_bf16 v[66:69], v[158:161], v[212:215], v[66:69]
	s_setprio 0
	s_barrier
	ds_read_b128 v[162:165], v208 offset:49152
	ds_read_b128 v[166:169], v208 offset:50176
	ds_read_b128 v[170:173], v208 offset:51200
	ds_read_b128 v[174:177], v208 offset:52224
	ds_read_b128 v[188:191], v208 offset:53248
	ds_read_b128 v[192:195], v208 offset:54272
	ds_read_b128 v[196:199], v208 offset:55296
	ds_read_b128 v[212:215], v208 offset:56320
	s_add_u32 s34, s30, 0x80
	s_addc_u32 s35, s31, 0
	s_mov_b32 m0, s46
	s_nop 0
	global_load_lds_dwordx4 v200, s[34:35]
	s_add_u32 s30, s30, 0x160080
	s_mov_b32 m0, s47
	s_nop 0
	global_load_lds_dwordx4 v203, s[34:35]
	s_addc_u32 s31, s31, 0
	s_mov_b32 m0, s50
	s_nop 0
	global_load_lds_dwordx4 v200, s[30:31]
	s_nop 0
	s_mov_b32 m0, s51
	s_nop 0
	global_load_lds_dwordx4 v203, s[30:31]
	s_mov_b32 m0, s48
	s_nop 0
	global_load_lds_dwordx4 v179, s[28:29]
	s_nop 0
	s_mov_b32 m0, s49
	s_nop 0
	global_load_lds_dwordx4 v201, s[28:29]
	s_waitcnt vmcnt(8)
	s_waitcnt lgkmcnt(0)
	s_barrier
	s_setprio 1
	v_mfma_f32_16x16x32_bf16 v[62:65], v[110:113], v[162:165], v[62:65]
	v_mfma_f32_16x16x32_bf16 v[58:61], v[130:133], v[162:165], v[58:61]
	v_mfma_f32_16x16x32_bf16 v[46:49], v[110:113], v[170:173], v[46:49]
	v_mfma_f32_16x16x32_bf16 v[42:45], v[130:133], v[170:173], v[42:45]
	s_add_i32 s58, s58, 2
	s_add_u32 s6, s6, 0x100
	s_addc_u32 s7, s7, 0
	s_add_u32 s56, s56, 0x100
	s_addc_u32 s57, s57, 0
	s_add_u32 s4, s4, 0x100
	s_addc_u32 s5, s5, 0
	s_cmpk_gt_u32 s58, 0x55
	v_mfma_f32_16x16x32_bf16 v[30:33], v[110:113], v[188:191], v[30:33]
	v_mfma_f32_16x16x32_bf16 v[26:29], v[130:133], v[188:191], v[26:29]
	v_mfma_f32_16x16x32_bf16 v[14:17], v[110:113], v[196:199], v[14:17]
	v_mfma_f32_16x16x32_bf16 v[10:13], v[130:133], v[196:199], v[10:13]
	v_mfma_f32_16x16x32_bf16 v[62:65], v[126:129], v[166:169], v[62:65]
	v_mfma_f32_16x16x32_bf16 v[58:61], v[142:145], v[166:169], v[58:61]
	v_mfma_f32_16x16x32_bf16 v[46:49], v[126:129], v[174:177], v[46:49]
	v_mfma_f32_16x16x32_bf16 v[42:45], v[142:145], v[174:177], v[42:45]
	v_mfma_f32_16x16x32_bf16 v[30:33], v[126:129], v[192:195], v[30:33]
	v_mfma_f32_16x16x32_bf16 v[26:29], v[142:145], v[192:195], v[26:29]
	v_mfma_f32_16x16x32_bf16 v[14:17], v[126:129], v[212:215], v[14:17]
	v_mfma_f32_16x16x32_bf16 v[10:13], v[142:145], v[212:215], v[10:13]
	v_mfma_f32_16x16x32_bf16 v[54:57], v[146:149], v[162:165], v[54:57]
	v_mfma_f32_16x16x32_bf16 v[50:53], v[154:157], v[162:165], v[50:53]
	v_mfma_f32_16x16x32_bf16 v[38:41], v[146:149], v[170:173], v[38:41]
	v_mfma_f32_16x16x32_bf16 v[34:37], v[154:157], v[170:173], v[34:37]
	v_mfma_f32_16x16x32_bf16 v[22:25], v[146:149], v[188:191], v[22:25]
	v_mfma_f32_16x16x32_bf16 v[18:21], v[154:157], v[188:191], v[18:21]
	v_mfma_f32_16x16x32_bf16 v[6:9], v[146:149], v[196:199], v[6:9]
	v_mfma_f32_16x16x32_bf16 v[2:5], v[154:157], v[196:199], v[2:5]
	v_mfma_f32_16x16x32_bf16 v[54:57], v[150:153], v[166:169], v[54:57]
	v_mfma_f32_16x16x32_bf16 v[50:53], v[158:161], v[166:169], v[50:53]
	v_mfma_f32_16x16x32_bf16 v[38:41], v[150:153], v[174:177], v[38:41]
	v_mfma_f32_16x16x32_bf16 v[34:37], v[158:161], v[174:177], v[34:37]
	v_mfma_f32_16x16x32_bf16 v[22:25], v[150:153], v[192:195], v[22:25]
	v_mfma_f32_16x16x32_bf16 v[18:21], v[158:161], v[192:195], v[18:21]
	v_mfma_f32_16x16x32_bf16 v[6:9], v[150:153], v[212:215], v[6:9]
	v_mfma_f32_16x16x32_bf16 v[2:5], v[158:161], v[212:215], v[2:5]
	s_setprio 0
	s_barrier
	s_cbranch_scc0 .LBB0_1317
	s_and_b64 vcc, exec, s[18:19]
	s_cbranch_vccz .LBB0_1320
	s_barrier

; #define PG8_STAGE(bufoff, gbase, voff) do { _Pragma("unroll") for (int _i = 0; _i < 2; ++_i) { unsigned keep_; \
;         asm volatile("s_mov_b32 %0, m0\n\ts_mov_b32 m0, %3\n\ts_nop 0\n\tglobal_load_lds_dwordx4 %1, %2\n\ts_mov_b32 m0, %0" \
;             : "=&s"(keep_) : "v"((voff)[_i]), "s"((const void*)(gbase)), "s"(ldsb0 + (unsigned)(bufoff) + (unsigned)(_i * 8192)) : "memory"); } } while (0)
; #define PG8_LDA(dst, b, h) do { _Pragma("unroll") for (int m = 0; m < 4; ++m) _Pragma("unroll") for (int k = 0; k < 2; ++k) dst[m][k] = *(const LAS bf16x8*)(lds + PG8_SA(b, h) + aoff + m * 2048 + k * 1024); } while (0)
; #define PG8_LDB(dst, b, h) do { _Pragma("unroll") for (int n = 0; n < 2; ++n) _Pragma("unroll") for (int k = 0; k < 2; ++k) dst[n][k] = *(const LAS bf16x8*)(lds + PG8_SB(b, h) + boff + n * 2048 + k * 1024); } while (0)
; template <class Epi, class Sched, bool ALIGN_EPI>
; __device__ __forceinline__ void gemm_phase(LAS unsigned char* lds, const Gemm g, const Sched& S, const Epi& E) {
;     ...
;         for (int t = 0; t < nt; t += 2) {
;             const bool last = (t == nt - 2);
;             const char* a1 = cA + (size_t)(t + 1) * kstep;
;             const char* a2 = last ? nA : cA + (size_t)(t + 2) * kstep; const char* b2 = last ? nB : cB + (size_t)(t + 2) * kstep;
;             const char* a3 = a2 + kstep; const char* b3 = b2 + kstep;
;             PG8_LDB(B0, 0, 0); PG8_LDB(B1, 0, 1); PG8_SCHED; PG8_LDA(At, 0, 0); PG8_STAGE(PG8_SA(1, 1), a1 + hstepA, voffA);
;             PG8_WAIT_V(8); PG8_WAIT_L(0); PG8_BAR; PG8_MMA(0, 0, At, B0); PG8_MMA(0, 1, At, B1); PG8_BAR; PG8_SCHED;
;             PG8_LDA(At, 0, 1); PG8_STAGE(PG8_SB(0, 0), b2, voffB); PG8_STAGE(PG8_SB(0, 1), b2 + hstepB, voffB); PG8_STAGE(PG8_SA(0, 0), a2, voffA);
;             PG8_WAIT_V(8); PG8_WAIT_L(0); PG8_BAR; PG8_MMA(1, 0, At, B0); PG8_MMA(1, 1, At, B1); PG8_BAR; PG8_SCHED;
;             PG8_LDB(B0, 1, 0); PG8_LDB(B1, 1, 1); PG8_SCHED; PG8_LDA(At, 1, 0); PG8_STAGE(PG8_SA(0, 1), a2 + hstepA, voffA);
;             PG8_WAIT_V(8); PG8_WAIT_L(0); PG8_BAR; PG8_MMA(0, 0, At, B0); PG8_MMA(0, 1, At, B1); PG8_BAR; PG8_SCHED;
;             PG8_LDA(At, 1, 1); PG8_STAGE(PG8_SB(1, 0), b3, voffB); PG8_STAGE(PG8_SB(1, 1), b3 + hstepB, voffB); PG8_STAGE(PG8_SA(1, 0), a3, voffA);
;             PG8_WAIT_V(8); PG8_WAIT_L(0); PG8_BAR; PG8_MMA(1, 0, At, B0); PG8_MMA(1, 1, At, B1); PG8_BAR; PG8_SCHED;
.LBB0_1409:
	ds_read_b128 v[132:135], v146
	ds_read_b128 v[136:139], v146 offset:1024
	ds_read_b128 v[160:163], v146 offset:2048
	ds_read_b128 v[164:167], v146 offset:3072
	ds_read_b128 v[168:171], v147
	ds_read_b128 v[172:175], v147 offset:1024
	ds_read_b128 v[180:183], v147 offset:2048
	ds_read_b128 v[184:187], v147 offset:3072
	s_add_u32 s8, s4, 0x100
	s_addc_u32 s9, s5, 0
	s_cmp_eq_u32 s39, 28
	s_cselect_b32 s46, s3, s8
	s_cselect_b32 s47, s2, s9
	s_cselect_b32 s12, s7, s23
	s_cselect_b32 s13, s6, s37
	s_add_u32 s10, s46, 0x80
	s_addc_u32 s11, s47, 0
	ds_read_b128 v[188:191], v148
	ds_read_b128 v[192:195], v148 offset:1024
	ds_read_b128 v[196:199], v148 offset:2048
	ds_read_b128 v[204:207], v148 offset:3072
	ds_read_b128 v[208:211], v148 offset:4096
	ds_read_b128 v[212:215], v148 offset:5120
	ds_read_b128 v[216:219], v148 offset:6144
	ds_read_b128 v[220:223], v148 offset:7168
	s_add_u32 s4, s4, 0x80080
	s_addc_u32 s5, s5, 0
	s_mov_b32 m0, s68
	s_nop 0
	global_load_lds_dwordx4 v140, s[4:5]
	s_nop 0
	s_mov_b32 m0, s69
	s_nop 0
	global_load_lds_dwordx4 v142, s[4:5]
	s_waitcnt vmcnt(8)
	s_waitcnt lgkmcnt(0)
	s_barrier
	s_setprio 1
	v_mfma_f32_16x16x32_bf16 v[126:129], v[132:135], v[188:191], v[126:129]
	v_mfma_f32_16x16x32_bf16 v[122:125], v[160:163], v[188:191], v[122:125]
	v_mfma_f32_16x16x32_bf16 v[110:113], v[132:135], v[196:199], v[110:113]
	v_mfma_f32_16x16x32_bf16 v[106:109], v[160:163], v[196:199], v[106:109]
	v_mfma_f32_16x16x32_bf16 v[94:97], v[132:135], v[208:211], v[94:97]
	v_mfma_f32_16x16x32_bf16 v[90:93], v[160:163], v[208:211], v[90:93]
	v_mfma_f32_16x16x32_bf16 v[78:81], v[132:135], v[216:219], v[78:81]
	v_mfma_f32_16x16x32_bf16 v[74:77], v[160:163], v[216:219], v[74:77]
	v_mfma_f32_16x16x32_bf16 v[126:129], v[136:139], v[192:195], v[126:129]
	v_mfma_f32_16x16x32_bf16 v[122:125], v[164:167], v[192:195], v[122:125]
	v_mfma_f32_16x16x32_bf16 v[110:113], v[136:139], v[204:207], v[110:113]
	v_mfma_f32_16x16x32_bf16 v[106:109], v[164:167], v[204:207], v[106:109]
	v_mfma_f32_16x16x32_bf16 v[94:97], v[136:139], v[212:215], v[94:97]
	v_mfma_f32_16x16x32_bf16 v[90:93], v[164:167], v[212:215], v[90:93]
	v_mfma_f32_16x16x32_bf16 v[78:81], v[136:139], v[220:223], v[78:81]
	v_mfma_f32_16x16x32_bf16 v[74:77], v[164:167], v[220:223], v[74:77]
	v_mfma_f32_16x16x32_bf16 v[118:121], v[168:171], v[188:191], v[118:121]
	v_mfma_f32_16x16x32_bf16 v[114:117], v[180:183], v[188:191], v[114:117]
	v_mfma_f32_16x16x32_bf16 v[102:105], v[168:171], v[196:199], v[102:105]
	v_mfma_f32_16x16x32_bf16 v[98:101], v[180:183], v[196:199], v[98:101]
	v_mfma_f32_16x16x32_bf16 v[86:89], v[168:171], v[208:211], v[86:89]
	v_mfma_f32_16x16x32_bf16 v[82:85], v[180:183], v[208:211], v[82:85]
	v_mfma_f32_16x16x32_bf16 v[70:73], v[168:171], v[216:219], v[70:73]
	v_mfma_f32_16x16x32_bf16 v[66:69], v[180:183], v[216:219], v[66:69]
	v_mfma_f32_16x16x32_bf16 v[118:121], v[172:175], v[192:195], v[118:121]
	v_mfma_f32_16x16x32_bf16 v[114:117], v[184:187], v[192:195], v[114:117]
	v_mfma_f32_16x16x32_bf16 v[102:105], v[172:175], v[204:207], v[102:105]
	v_mfma_f32_16x16x32_bf16 v[98:101], v[184:187], v[204:207], v[98:101]
	v_mfma_f32_16x16x32_bf16 v[86:89], v[172:175], v[212:215], v[86:89]
	v_mfma_f32_16x16x32_bf16 v[82:85], v[184:187], v[212:215], v[82:85]
	v_mfma_f32_16x16x32_bf16 v[70:73], v[172:175], v[220:223], v[70:73]
	v_mfma_f32_16x16x32_bf16 v[66:69], v[184:187], v[220:223], v[66:69]
	s_setprio 0
	s_barrier
	ds_read_b128 v[188:191], v148 offset:16384
	ds_read_b128 v[192:195], v148 offset:17408
	ds_read_b128 v[196:199], v148 offset:18432
	ds_read_b128 v[204:207], v148 offset:19456
	ds_read_b128 v[208:211], v148 offset:20480
	ds_read_b128 v[212:215], v148 offset:21504
	ds_read_b128 v[216:219], v148 offset:22528
	ds_read_b128 v[220:223], v148 offset:23552
	s_mov_b32 m0, s53
	s_nop 0
	global_load_lds_dwordx4 v141, s[12:13]
	s_nop 0
	s_mov_b32 m0, s54
	s_nop 0
	global_load_lds_dwordx4 v143, s[12:13]
	s_add_u32 s4, s12, 0x80000
	s_addc_u32 s5, s13, 0
	s_mov_b32 m0, s55
	s_nop 0
	global_load_lds_dwordx4 v141, s[4:5]
	s_nop 0
	s_mov_b32 m0, s56
	s_nop 0
	global_load_lds_dwordx4 v143, s[4:5]
	s_mov_b32 m0, s52
	s_nop 0
	global_load_lds_dwordx4 v140, s[46:47]
	s_nop 0
	s_mov_b32 m0, s57
	s_nop 0
	global_load_lds_dwordx4 v142, s[46:47]
	s_waitcnt vmcnt(8)
	s_waitcnt lgkmcnt(0)
	s_barrier
	s_setprio 1
	v_mfma_f32_16x16x32_bf16 v[62:65], v[132:135], v[188:191], v[62:65]
	v_mfma_f32_16x16x32_bf16 v[58:61], v[160:163], v[188:191], v[58:61]
	v_mfma_f32_16x16x32_bf16 v[46:49], v[132:135], v[196:199], v[46:49]
	v_mfma_f32_16x16x32_bf16 v[42:45], v[160:163], v[196:199], v[42:45]
	v_mfma_f32_16x16x32_bf16 v[30:33], v[132:135], v[208:211], v[30:33]
	v_mfma_f32_16x16x32_bf16 v[26:29], v[160:163], v[208:211], v[26:29]
	v_mfma_f32_16x16x32_bf16 v[14:17], v[132:135], v[216:219], v[14:17]
	v_mfma_f32_16x16x32_bf16 v[10:13], v[160:163], v[216:219], v[10:13]
	v_mfma_f32_16x16x32_bf16 v[62:65], v[136:139], v[192:195], v[62:65]
	v_mfma_f32_16x16x32_bf16 v[58:61], v[164:167], v[192:195], v[58:61]
	v_mfma_f32_16x16x32_bf16 v[46:49], v[136:139], v[204:207], v[46:49]
	v_mfma_f32_16x16x32_bf16 v[42:45], v[164:167], v[204:207], v[42:45]
	v_mfma_f32_16x16x32_bf16 v[30:33], v[136:139], v[212:215], v[30:33]
	v_mfma_f32_16x16x32_bf16 v[26:29], v[164:167], v[212:215], v[26:29]
	v_mfma_f32_16x16x32_bf16 v[14:17], v[136:139], v[220:223], v[14:17]
	v_mfma_f32_16x16x32_bf16 v[10:13], v[164:167], v[220:223], v[10:13]
	v_mfma_f32_16x16x32_bf16 v[54:57], v[168:171], v[188:191], v[54:57]
	v_mfma_f32_16x16x32_bf16 v[50:53], v[180:183], v[188:191], v[50:53]
	v_mfma_f32_16x16x32_bf16 v[38:41], v[168:171], v[196:199], v[38:41]
	v_mfma_f32_16x16x32_bf16 v[34:37], v[180:183], v[196:199], v[34:37]
	v_mfma_f32_16x16x32_bf16 v[22:25], v[168:171], v[208:211], v[22:25]
	v_mfma_f32_16x16x32_bf16 v[18:21], v[180:183], v[208:211], v[18:21]
	v_mfma_f32_16x16x32_bf16 v[6:9], v[168:171], v[216:219], v[6:9]
	v_mfma_f32_16x16x32_bf16 v[2:5], v[180:183], v[216:219], v[2:5]
	v_mfma_f32_16x16x32_bf16 v[54:57], v[172:175], v[192:195], v[54:57]
	v_mfma_f32_16x16x32_bf16 v[50:53], v[184:187], v[192:195], v[50:53]
	v_mfma_f32_16x16x32_bf16 v[38:41], v[172:175], v[204:207], v[38:41]
	v_mfma_f32_16x16x32_bf16 v[34:37], v[184:187], v[204:207], v[34:37]
	v_mfma_f32_16x16x32_bf16 v[22:25], v[172:175], v[212:215], v[22:25]
	v_mfma_f32_16x16x32_bf16 v[18:21], v[184:187], v[212:215], v[18:21]
	v_mfma_f32_16x16x32_bf16 v[6:9], v[172:175], v[220:223], v[6:9]
	v_mfma_f32_16x16x32_bf16 v[2:5], v[184:187], v[220:223], v[2:5]
	s_setprio 0
	s_barrier
; #define PG8_STAGE(bufoff, gbase, voff) do { _Pragma("unroll") for (int _i = 0; _i < 2; ++_i) { unsigned keep_; \
;         asm volatile("s_mov_b32 %0, m0\n\ts_mov_b32 m0, %3\n\ts_nop 0\n\tglobal_load_lds_dwordx4 %1, %2\n\ts_mov_b32 m0, %0" \
;             : "=&s"(keep_) : "v"((voff)[_i]), "s"((const void*)(gbase)), "s"(ldsb0 + (unsigned)(bufoff) + (unsigned)(_i * 8192)) : "memory"); } } while (0)
; #define PG8_LDA(dst, b, h) do { _Pragma("unroll") for (int m = 0; m < 4; ++m) _Pragma("unroll") for (int k = 0; k < 2; ++k) dst[m][k] = *(const LAS bf16x8*)(lds + PG8_SA(b, h) + aoff + m * 2048 + k * 1024); } while (0)
; #define PG8_LDB(dst, b, h) do { _Pragma("unroll") for (int n = 0; n < 2; ++n) _Pragma("unroll") for (int k = 0; k < 2; ++k) dst[n][k] = *(const LAS bf16x8*)(lds + PG8_SB(b, h) + boff + n * 2048 + k * 1024); } while (0)
; #define PG8_MMA(ai, bj, At, Bt) do { __builtin_amdgcn_s_setprio(1); _Pragma("unroll") for (int m = 0; m < 4; ++m) _Pragma("unroll") for (int n = 0; n < 2; ++n) _Pragma("unroll") for (int k = 0; k < 2; ++k) \
;         acc[ai][bj][m][n] = __builtin_amdgcn_mfma_f32_16x16x32_bf16(Bt[n][k], At[m][k], acc[ai][bj][m][n], 0, 0, 0); __builtin_amdgcn_s_setprio(0); } while (0)
; #define PG8_WAIT_V(n) asm volatile("s_waitcnt vmcnt(" #n ")" ::: "memory")
; #define PG8_WAIT_L(n) asm volatile("s_waitcnt lgkmcnt(" #n ")" ::: "memory")
; #define PG8_BAR __builtin_amdgcn_s_barrier()
; #define PG8_SCHED __builtin_amdgcn_sched_barrier(0)
; template <class Epi, class Sched, bool ALIGN_EPI>
; __device__ __forceinline__ void gemm_phase(LAS unsigned char* lds, const Gemm g, const Sched& S, const Epi& E) {
;     ...
;             PG8_LDB(B0, 1, 0); PG8_LDB(B1, 1, 1); PG8_SCHED; PG8_LDA(At, 1, 0); PG8_STAGE(PG8_SA(0, 1), a2 + hstepA, voffA);
;             PG8_WAIT_V(8); PG8_WAIT_L(0); PG8_BAR; PG8_MMA(0, 0, At, B0); PG8_MMA(0, 1, At, B1); PG8_BAR; PG8_SCHED;
;             PG8_LDA(At, 1, 1); PG8_STAGE(PG8_SB(1, 0), b3, voffB); PG8_STAGE(PG8_SB(1, 1), b3 + hstepB, voffB); PG8_STAGE(PG8_SA(1, 0), a3, voffA);
;             PG8_WAIT_V(8); PG8_WAIT_L(0); PG8_BAR; PG8_MMA(1, 0, At, B0); PG8_MMA(1, 1, At, B1); PG8_BAR; PG8_SCHED;
	ds_read_b128 v[132:135], v149
	ds_read_b128 v[136:139], v149 offset:1024
	ds_read_b128 v[160:163], v149 offset:2048
	ds_read_b128 v[164:167], v149 offset:3072
	ds_read_b128 v[168:171], v150
	ds_read_b128 v[172:175], v150 offset:1024
	ds_read_b128 v[180:183], v150 offset:2048
	ds_read_b128 v[184:187], v150 offset:3072
	ds_read_b128 v[188:191], v148 offset:32768
	ds_read_b128 v[192:195], v148 offset:33792
	ds_read_b128 v[196:199], v148 offset:34816
	ds_read_b128 v[204:207], v148 offset:35840
	ds_read_b128 v[208:211], v148 offset:36864
	ds_read_b128 v[212:215], v148 offset:37888
	ds_read_b128 v[216:219], v148 offset:38912
	ds_read_b128 v[220:223], v148 offset:39936
	s_add_u32 s4, s46, 0x80000
	s_addc_u32 s5, s47, 0
	s_mov_b32 m0, s59
	s_nop 0
	global_load_lds_dwordx4 v140, s[4:5]
	s_nop 0
	s_mov_b32 m0, s61
	s_nop 0
	global_load_lds_dwordx4 v142, s[4:5]
	s_waitcnt vmcnt(8)
	s_waitcnt lgkmcnt(0)
	s_barrier
	s_setprio 1
	v_mfma_f32_16x16x32_bf16 v[126:129], v[132:135], v[188:191], v[126:129]
	v_mfma_f32_16x16x32_bf16 v[122:125], v[160:163], v[188:191], v[122:125]
	v_mfma_f32_16x16x32_bf16 v[110:113], v[132:135], v[196:199], v[110:113]
	v_mfma_f32_16x16x32_bf16 v[106:109], v[160:163], v[196:199], v[106:109]
	v_mfma_f32_16x16x32_bf16 v[94:97], v[132:135], v[208:211], v[94:97]
	v_mfma_f32_16x16x32_bf16 v[90:93], v[160:163], v[208:211], v[90:93]
	v_mfma_f32_16x16x32_bf16 v[78:81], v[132:135], v[216:219], v[78:81]
	v_mfma_f32_16x16x32_bf16 v[74:77], v[160:163], v[216:219], v[74:77]
	v_mfma_f32_16x16x32_bf16 v[126:129], v[136:139], v[192:195], v[126:129]
	v_mfma_f32_16x16x32_bf16 v[122:125], v[164:167], v[192:195], v[122:125]
	v_mfma_f32_16x16x32_bf16 v[110:113], v[136:139], v[204:207], v[110:113]
	v_mfma_f32_16x16x32_bf16 v[106:109], v[164:167], v[204:207], v[106:109]
	v_mfma_f32_16x16x32_bf16 v[94:97], v[136:139], v[212:215], v[94:97]
	v_mfma_f32_16x16x32_bf16 v[90:93], v[164:167], v[212:215], v[90:93]
	v_mfma_f32_16x16x32_bf16 v[78:81], v[136:139], v[220:223], v[78:81]
	v_mfma_f32_16x16x32_bf16 v[74:77], v[164:167], v[220:223], v[74:77]
	v_mfma_f32_16x16x32_bf16 v[118:121], v[168:171], v[188:191], v[118:121]
	v_mfma_f32_16x16x32_bf16 v[114:117], v[180:183], v[188:191], v[114:117]
	v_mfma_f32_16x16x32_bf16 v[102:105], v[168:171], v[196:199], v[102:105]
	v_mfma_f32_16x16x32_bf16 v[98:101], v[180:183], v[196:199], v[98:101]
	v_mfma_f32_16x16x32_bf16 v[86:89], v[168:171], v[208:211], v[86:89]
	v_mfma_f32_16x16x32_bf16 v[82:85], v[180:183], v[208:211], v[82:85]
	v_mfma_f32_16x16x32_bf16 v[70:73], v[168:171], v[216:219], v[70:73]
	v_mfma_f32_16x16x32_bf16 v[66:69], v[180:183], v[216:219], v[66:69]
	v_mfma_f32_16x16x32_bf16 v[118:121], v[172:175], v[192:195], v[118:121]
	v_mfma_f32_16x16x32_bf16 v[114:117], v[184:187], v[192:195], v[114:117]
	v_mfma_f32_16x16x32_bf16 v[102:105], v[172:175], v[204:207], v[102:105]
	v_mfma_f32_16x16x32_bf16 v[98:101], v[184:187], v[204:207], v[98:101]
	v_mfma_f32_16x16x32_bf16 v[86:89], v[172:175], v[212:215], v[86:89]
	v_mfma_f32_16x16x32_bf16 v[82:85], v[184:187], v[212:215], v[82:85]
	v_mfma_f32_16x16x32_bf16 v[70:73], v[172:175], v[220:223], v[70:73]
	v_mfma_f32_16x16x32_bf16 v[66:69], v[184:187], v[220:223], v[66:69]
	s_setprio 0
	s_barrier
	ds_read_b128 v[188:191], v148 offset:49152
	ds_read_b128 v[192:195], v148 offset:50176
	ds_read_b128 v[196:199], v148 offset:51200
	ds_read_b128 v[204:207], v148 offset:52224
	ds_read_b128 v[208:211], v148 offset:53248
	ds_read_b128 v[212:215], v148 offset:54272
	ds_read_b128 v[216:219], v148 offset:55296
	ds_read_b128 v[220:223], v148 offset:56320
	s_add_u32 s4, s12, 0x80
	s_addc_u32 s5, s13, 0
	s_mov_b32 m0, s62
	s_nop 0
	global_load_lds_dwordx4 v141, s[4:5]
	s_nop 0
	s_mov_b32 m0, s63
	s_nop 0
	global_load_lds_dwordx4 v143, s[4:5]
	s_add_u32 s4, s12, 0x80080
	s_addc_u32 s5, s13, 0
	s_mov_b32 m0, s66
	s_nop 0
	global_load_lds_dwordx4 v141, s[4:5]
	s_nop 0
	s_mov_b32 m0, s67
	s_nop 0
	global_load_lds_dwordx4 v143, s[4:5]
	s_mov_b32 m0, s64
	s_nop 0
	global_load_lds_dwordx4 v140, s[10:11]
	s_nop 0
	s_mov_b32 m0, s65
	s_nop 0
	global_load_lds_dwordx4 v142, s[10:11]
	s_waitcnt vmcnt(8)
	s_waitcnt lgkmcnt(0)
	s_barrier
	s_setprio 1
	v_mfma_f32_16x16x32_bf16 v[62:65], v[132:135], v[188:191], v[62:65]
	v_mfma_f32_16x16x32_bf16 v[58:61], v[160:163], v[188:191], v[58:61]
	v_mfma_f32_16x16x32_bf16 v[46:49], v[132:135], v[196:199], v[46:49]
	v_mfma_f32_16x16x32_bf16 v[42:45], v[160:163], v[196:199], v[42:45]
	s_add_i32 s39, s39, 2
	s_add_u32 s23, s23, 0x100
	s_addc_u32 s37, s37, 0
	s_cmp_gt_u32 s39, 29
	s_mov_b64 s[4:5], s[8:9]
	v_mfma_f32_16x16x32_bf16 v[30:33], v[132:135], v[208:211], v[30:33]
	v_mfma_f32_16x16x32_bf16 v[26:29], v[160:163], v[208:211], v[26:29]
	v_mfma_f32_16x16x32_bf16 v[14:17], v[132:135], v[216:219], v[14:17]
	v_mfma_f32_16x16x32_bf16 v[10:13], v[160:163], v[216:219], v[10:13]
	v_mfma_f32_16x16x32_bf16 v[62:65], v[136:139], v[192:195], v[62:65]
	v_mfma_f32_16x16x32_bf16 v[58:61], v[164:167], v[192:195], v[58:61]
	v_mfma_f32_16x16x32_bf16 v[46:49], v[136:139], v[204:207], v[46:49]
	v_mfma_f32_16x16x32_bf16 v[42:45], v[164:167], v[204:207], v[42:45]
	v_mfma_f32_16x16x32_bf16 v[30:33], v[136:139], v[212:215], v[30:33]
	v_mfma_f32_16x16x32_bf16 v[26:29], v[164:167], v[212:215], v[26:29]
	v_mfma_f32_16x16x32_bf16 v[14:17], v[136:139], v[220:223], v[14:17]
	v_mfma_f32_16x16x32_bf16 v[10:13], v[164:167], v[220:223], v[10:13]
	v_mfma_f32_16x16x32_bf16 v[54:57], v[168:171], v[188:191], v[54:57]
	v_mfma_f32_16x16x32_bf16 v[50:53], v[180:183], v[188:191], v[50:53]
	v_mfma_f32_16x16x32_bf16 v[38:41], v[168:171], v[196:199], v[38:41]
	v_mfma_f32_16x16x32_bf16 v[34:37], v[180:183], v[196:199], v[34:37]
	v_mfma_f32_16x16x32_bf16 v[22:25], v[168:171], v[208:211], v[22:25]
	v_mfma_f32_16x16x32_bf16 v[18:21], v[180:183], v[208:211], v[18:21]
	v_mfma_f32_16x16x32_bf16 v[6:9], v[168:171], v[216:219], v[6:9]
	v_mfma_f32_16x16x32_bf16 v[2:5], v[180:183], v[216:219], v[2:5]
	v_mfma_f32_16x16x32_bf16 v[54:57], v[172:175], v[192:195], v[54:57]
	v_mfma_f32_16x16x32_bf16 v[50:53], v[184:187], v[192:195], v[50:53]
	v_mfma_f32_16x16x32_bf16 v[38:41], v[172:175], v[204:207], v[38:41]
	v_mfma_f32_16x16x32_bf16 v[34:37], v[184:187], v[204:207], v[34:37]
	v_mfma_f32_16x16x32_bf16 v[22:25], v[172:175], v[212:215], v[22:25]
	v_mfma_f32_16x16x32_bf16 v[18:21], v[184:187], v[212:215], v[18:21]
	v_mfma_f32_16x16x32_bf16 v[6:9], v[172:175], v[220:223], v[6:9]
	v_mfma_f32_16x16x32_bf16 v[2:5], v[184:187], v[220:223], v[2:5]
	s_setprio 0
	s_barrier
	s_cbranch_scc0 .LBB0_1409
	s_and_b64 vcc, exec, s[34:35]
	s_cbranch_vccz .LBB0_1412
	s_barrier

; #define PG8_STAGE(bufoff, gbase, voff) do { _Pragma("unroll") for (int _i = 0; _i < 2; ++_i) { unsigned keep_; \
;         asm volatile("s_mov_b32 %0, m0\n\ts_mov_b32 m0, %3\n\ts_nop 0\n\tglobal_load_lds_dwordx4 %1, %2\n\ts_mov_b32 m0, %0" \
;             : "=&s"(keep_) : "v"((voff)[_i]), "s"((const void*)(gbase)), "s"(ldsb0 + (unsigned)(bufoff) + (unsigned)(_i * 8192)) : "memory"); } } while (0)
; #define PG8_LDA(dst, b, h) do { _Pragma("unroll") for (int m = 0; m < 4; ++m) _Pragma("unroll") for (int k = 0; k < 2; ++k) dst[m][k] = *(const LAS bf16x8*)(lds + PG8_SA(b, h) + aoff + m * 2048 + k * 1024); } while (0)
; #define PG8_LDB(dst, b, h) do { _Pragma("unroll") for (int n = 0; n < 2; ++n) _Pragma("unroll") for (int k = 0; k < 2; ++k) dst[n][k] = *(const LAS bf16x8*)(lds + PG8_SB(b, h) + boff + n * 2048 + k * 1024); } while (0)
; #define PG8_MMA(ai, bj, At, Bt) do { __builtin_amdgcn_s_setprio(1); _Pragma("unroll") for (int m = 0; m < 4; ++m) _Pragma("unroll") for (int n = 0; n < 2; ++n) _Pragma("unroll") for (int k = 0; k < 2; ++k) \
;         acc[ai][bj][m][n] = __builtin_amdgcn_mfma_f32_16x16x32_bf16(Bt[n][k], At[m][k], acc[ai][bj][m][n], 0, 0, 0); __builtin_amdgcn_s_setprio(0); } while (0)
; #define PG8_WAIT_V(n) asm volatile("s_waitcnt vmcnt(" #n ")" ::: "memory")
; #define PG8_WAIT_L(n) asm volatile("s_waitcnt lgkmcnt(" #n ")" ::: "memory")
; template <class Epi, class Sched, bool ALIGN_EPI>
; __device__ __forceinline__ void gemm_phase(LAS unsigned char* lds, const Gemm g, const Sched& S, const Epi& E) {
;     ...
;             const bool last = (t == nt - 2);
;             const char* a1 = cA + (size_t)(t + 1) * kstep;
;             const char* a2 = last ? nA : cA + (size_t)(t + 2) * kstep; const char* b2 = last ? nB : cB + (size_t)(t + 2) * kstep;
;             const char* a3 = a2 + kstep; const char* b3 = b2 + kstep;
;             PG8_LDB(B0, 0, 0); PG8_LDB(B1, 0, 1); PG8_SCHED; PG8_LDA(At, 0, 0); PG8_STAGE(PG8_SA(1, 1), a1 + hstepA, voffA);
;             PG8_WAIT_V(8); PG8_WAIT_L(0); PG8_BAR; PG8_MMA(0, 0, At, B0); PG8_MMA(0, 1, At, B1); PG8_BAR; PG8_SCHED;
;             PG8_LDA(At, 0, 1); PG8_STAGE(PG8_SB(0, 0), b2, voffB); PG8_STAGE(PG8_SB(0, 1), b2 + hstepB, voffB); PG8_STAGE(PG8_SA(0, 0), a2, voffA);
;             PG8_WAIT_V(8); PG8_WAIT_L(0); PG8_BAR; PG8_MMA(1, 0, At, B0); PG8_MMA(1, 1, At, B1); PG8_BAR; PG8_SCHED;
.LBB0_1994:
	ds_read_b128 v[110:113], v206
	ds_read_b128 v[126:129], v206 offset:1024
	ds_read_b128 v[130:133], v206 offset:2048
	ds_read_b128 v[142:145], v206 offset:3072
	ds_read_b128 v[146:149], v207
	ds_read_b128 v[150:153], v207 offset:1024
	ds_read_b128 v[154:157], v207 offset:2048
	ds_read_b128 v[158:161], v207 offset:3072
	s_cmp_eq_u32 s59, 28
	s_cselect_b32 s34, s5, s19
	s_cselect_b32 s35, s3, s21
	s_cselect_b32 s30, s7, s57
	s_cselect_b32 s31, s6, s58
	s_add_u32 s28, s34, 0x80
	s_addc_u32 s29, s35, 0
	ds_read_b128 v[162:165], v208
	ds_read_b128 v[166:169], v208 offset:1024
	ds_read_b128 v[170:173], v208 offset:2048
	ds_read_b128 v[174:177], v208 offset:3072
	ds_read_b128 v[188:191], v208 offset:4096
	ds_read_b128 v[192:195], v208 offset:5120
	ds_read_b128 v[196:199], v208 offset:6144
	ds_read_b128 v[212:215], v208 offset:7168
	s_mov_b32 m0, s55
	s_nop 0
	global_load_lds_dwordx4 v179, s[26:27]
	s_nop 0
	s_mov_b32 m0, s56
	s_nop 0
	global_load_lds_dwordx4 v201, s[26:27]
	s_waitcnt vmcnt(8)
	s_waitcnt lgkmcnt(0)
	s_barrier
	s_setprio 1
	v_mfma_f32_16x16x32_bf16 v[138:141], v[110:113], v[162:165], v[138:141]
	v_mfma_f32_16x16x32_bf16 v[134:137], v[130:133], v[162:165], v[134:137]
	v_mfma_f32_16x16x32_bf16 v[114:117], v[110:113], v[170:173], v[114:117]
	v_mfma_f32_16x16x32_bf16 v[106:109], v[130:133], v[170:173], v[106:109]
	v_mfma_f32_16x16x32_bf16 v[94:97], v[110:113], v[188:191], v[94:97]
	v_mfma_f32_16x16x32_bf16 v[90:93], v[130:133], v[188:191], v[90:93]
	v_mfma_f32_16x16x32_bf16 v[78:81], v[110:113], v[196:199], v[78:81]
	v_mfma_f32_16x16x32_bf16 v[74:77], v[130:133], v[196:199], v[74:77]
	v_mfma_f32_16x16x32_bf16 v[138:141], v[126:129], v[166:169], v[138:141]
	v_mfma_f32_16x16x32_bf16 v[134:137], v[142:145], v[166:169], v[134:137]
	v_mfma_f32_16x16x32_bf16 v[114:117], v[126:129], v[174:177], v[114:117]
	v_mfma_f32_16x16x32_bf16 v[106:109], v[142:145], v[174:177], v[106:109]
	v_mfma_f32_16x16x32_bf16 v[94:97], v[126:129], v[192:195], v[94:97]
	v_mfma_f32_16x16x32_bf16 v[90:93], v[142:145], v[192:195], v[90:93]
	v_mfma_f32_16x16x32_bf16 v[78:81], v[126:129], v[212:215], v[78:81]
	v_mfma_f32_16x16x32_bf16 v[74:77], v[142:145], v[212:215], v[74:77]
	v_mfma_f32_16x16x32_bf16 v[122:125], v[146:149], v[162:165], v[122:125]
	v_mfma_f32_16x16x32_bf16 v[118:121], v[154:157], v[162:165], v[118:121]
	v_mfma_f32_16x16x32_bf16 v[102:105], v[146:149], v[170:173], v[102:105]
	v_mfma_f32_16x16x32_bf16 v[98:101], v[154:157], v[170:173], v[98:101]
	v_mfma_f32_16x16x32_bf16 v[86:89], v[146:149], v[188:191], v[86:89]
	v_mfma_f32_16x16x32_bf16 v[82:85], v[154:157], v[188:191], v[82:85]
	v_mfma_f32_16x16x32_bf16 v[70:73], v[146:149], v[196:199], v[70:73]
	v_mfma_f32_16x16x32_bf16 v[66:69], v[154:157], v[196:199], v[66:69]
	v_mfma_f32_16x16x32_bf16 v[122:125], v[150:153], v[166:169], v[122:125]
	v_mfma_f32_16x16x32_bf16 v[118:121], v[158:161], v[166:169], v[118:121]
	v_mfma_f32_16x16x32_bf16 v[102:105], v[150:153], v[174:177], v[102:105]
	v_mfma_f32_16x16x32_bf16 v[98:101], v[158:161], v[174:177], v[98:101]
	v_mfma_f32_16x16x32_bf16 v[86:89], v[150:153], v[192:195], v[86:89]
	v_mfma_f32_16x16x32_bf16 v[82:85], v[158:161], v[192:195], v[82:85]
	v_mfma_f32_16x16x32_bf16 v[70:73], v[150:153], v[212:215], v[70:73]
	v_mfma_f32_16x16x32_bf16 v[66:69], v[158:161], v[212:215], v[66:69]
	s_setprio 0
	s_barrier
	ds_read_b128 v[162:165], v208 offset:16384
	ds_read_b128 v[166:169], v208 offset:17408
	ds_read_b128 v[170:173], v208 offset:18432
	ds_read_b128 v[174:177], v208 offset:19456
	ds_read_b128 v[188:191], v208 offset:20480
	ds_read_b128 v[192:195], v208 offset:21504
	ds_read_b128 v[196:199], v208 offset:22528
	ds_read_b128 v[212:215], v208 offset:23552
	s_mov_b32 m0, s42
	s_nop 0
	global_load_lds_dwordx4 v200, s[30:31]
	s_nop 0
	s_mov_b32 m0, s43
	s_nop 0
	global_load_lds_dwordx4 v203, s[30:31]
	s_add_u32 s60, s30, 0x80000
	s_addc_u32 s61, s31, 0
	s_mov_b32 m0, s44
	s_nop 0
	global_load_lds_dwordx4 v200, s[60:61]
	s_nop 0
	s_mov_b32 m0, s45
	s_nop 0
	global_load_lds_dwordx4 v203, s[60:61]
	s_mov_b32 m0, s41
	s_nop 0
	global_load_lds_dwordx4 v179, s[34:35]
	s_nop 0
	s_mov_b32 m0, s46
	s_nop 0
	global_load_lds_dwordx4 v201, s[34:35]
	s_waitcnt vmcnt(8)
	s_waitcnt lgkmcnt(0)
	s_barrier
	s_setprio 1
	v_mfma_f32_16x16x32_bf16 v[62:65], v[110:113], v[162:165], v[62:65]
	v_mfma_f32_16x16x32_bf16 v[58:61], v[130:133], v[162:165], v[58:61]
	v_mfma_f32_16x16x32_bf16 v[46:49], v[110:113], v[170:173], v[46:49]
	v_mfma_f32_16x16x32_bf16 v[42:45], v[130:133], v[170:173], v[42:45]
	v_mfma_f32_16x16x32_bf16 v[30:33], v[110:113], v[188:191], v[30:33]
	v_mfma_f32_16x16x32_bf16 v[26:29], v[130:133], v[188:191], v[26:29]
	v_mfma_f32_16x16x32_bf16 v[14:17], v[110:113], v[196:199], v[14:17]
	v_mfma_f32_16x16x32_bf16 v[10:13], v[130:133], v[196:199], v[10:13]
	v_mfma_f32_16x16x32_bf16 v[62:65], v[126:129], v[166:169], v[62:65]
	v_mfma_f32_16x16x32_bf16 v[58:61], v[142:145], v[166:169], v[58:61]
	v_mfma_f32_16x16x32_bf16 v[46:49], v[126:129], v[174:177], v[46:49]
	v_mfma_f32_16x16x32_bf16 v[42:45], v[142:145], v[174:177], v[42:45]
	v_mfma_f32_16x16x32_bf16 v[30:33], v[126:129], v[192:195], v[30:33]
	v_mfma_f32_16x16x32_bf16 v[26:29], v[142:145], v[192:195], v[26:29]
	v_mfma_f32_16x16x32_bf16 v[14:17], v[126:129], v[212:215], v[14:17]
	v_mfma_f32_16x16x32_bf16 v[10:13], v[142:145], v[212:215], v[10:13]
	v_mfma_f32_16x16x32_bf16 v[54:57], v[146:149], v[162:165], v[54:57]
	v_mfma_f32_16x16x32_bf16 v[50:53], v[154:157], v[162:165], v[50:53]
	v_mfma_f32_16x16x32_bf16 v[38:41], v[146:149], v[170:173], v[38:41]
	v_mfma_f32_16x16x32_bf16 v[34:37], v[154:157], v[170:173], v[34:37]
	v_mfma_f32_16x16x32_bf16 v[22:25], v[146:149], v[188:191], v[22:25]
	v_mfma_f32_16x16x32_bf16 v[18:21], v[154:157], v[188:191], v[18:21]
	v_mfma_f32_16x16x32_bf16 v[6:9], v[146:149], v[196:199], v[6:9]
	v_mfma_f32_16x16x32_bf16 v[2:5], v[154:157], v[196:199], v[2:5]
	v_mfma_f32_16x16x32_bf16 v[54:57], v[150:153], v[166:169], v[54:57]
	v_mfma_f32_16x16x32_bf16 v[50:53], v[158:161], v[166:169], v[50:53]
	v_mfma_f32_16x16x32_bf16 v[38:41], v[150:153], v[174:177], v[38:41]
	v_mfma_f32_16x16x32_bf16 v[34:37], v[158:161], v[174:177], v[34:37]
	v_mfma_f32_16x16x32_bf16 v[22:25], v[150:153], v[192:195], v[22:25]
	v_mfma_f32_16x16x32_bf16 v[18:21], v[158:161], v[192:195], v[18:21]
	v_mfma_f32_16x16x32_bf16 v[6:9], v[150:153], v[212:215], v[6:9]
	v_mfma_f32_16x16x32_bf16 v[2:5], v[158:161], v[212:215], v[2:5]
	s_setprio 0
	s_barrier
; #define PG8_STAGE(bufoff, gbase, voff) do { _Pragma("unroll") for (int _i = 0; _i < 2; ++_i) { unsigned keep_; \
;         asm volatile("s_mov_b32 %0, m0\n\ts_mov_b32 m0, %3\n\ts_nop 0\n\tglobal_load_lds_dwordx4 %1, %2\n\ts_mov_b32 m0, %0" \
;             : "=&s"(keep_) : "v"((voff)[_i]), "s"((const void*)(gbase)), "s"(ldsb0 + (unsigned)(bufoff) + (unsigned)(_i * 8192)) : "memory"); } } while (0)
; #define PG8_LDA(dst, b, h) do { _Pragma("unroll") for (int m = 0; m < 4; ++m) _Pragma("unroll") for (int k = 0; k < 2; ++k) dst[m][k] = *(const LAS bf16x8*)(lds + PG8_SA(b, h) + aoff + m * 2048 + k * 1024); } while (0)
; #define PG8_LDB(dst, b, h) do { _Pragma("unroll") for (int n = 0; n < 2; ++n) _Pragma("unroll") for (int k = 0; k < 2; ++k) dst[n][k] = *(const LAS bf16x8*)(lds + PG8_SB(b, h) + boff + n * 2048 + k * 1024); } while (0)
; #define PG8_MMA(ai, bj, At, Bt) do { __builtin_amdgcn_s_setprio(1); _Pragma("unroll") for (int m = 0; m < 4; ++m) _Pragma("unroll") for (int n = 0; n < 2; ++n) _Pragma("unroll") for (int k = 0; k < 2; ++k) \
;         acc[ai][bj][m][n] = __builtin_amdgcn_mfma_f32_16x16x32_bf16(Bt[n][k], At[m][k], acc[ai][bj][m][n], 0, 0, 0); __builtin_amdgcn_s_setprio(0); } while (0)
; #define PG8_WAIT_V(n) asm volatile("s_waitcnt vmcnt(" #n ")" ::: "memory")
; #define PG8_WAIT_L(n) asm volatile("s_waitcnt lgkmcnt(" #n ")" ::: "memory")
; #define PG8_BAR __builtin_amdgcn_s_barrier()
; #define PG8_SCHED __builtin_amdgcn_sched_barrier(0)
; template <class Epi, class Sched, bool ALIGN_EPI>
; __device__ __forceinline__ void gemm_phase(LAS unsigned char* lds, const Gemm g, const Sched& S, const Epi& E) {
;     ...
;             PG8_LDB(B0, 1, 0); PG8_LDB(B1, 1, 1); PG8_SCHED; PG8_LDA(At, 1, 0); PG8_STAGE(PG8_SA(0, 1), a2 + hstepA, voffA);
;             PG8_WAIT_V(8); PG8_WAIT_L(0); PG8_BAR; PG8_MMA(0, 0, At, B0); PG8_MMA(0, 1, At, B1); PG8_BAR; PG8_SCHED;
;             PG8_LDA(At, 1, 1); PG8_STAGE(PG8_SB(1, 0), b3, voffB); PG8_STAGE(PG8_SB(1, 1), b3 + hstepB, voffB); PG8_STAGE(PG8_SA(1, 0), a3, voffA);
;             PG8_WAIT_V(8); PG8_WAIT_L(0); PG8_BAR; PG8_MMA(1, 0, At, B0); PG8_MMA(1, 1, At, B1); PG8_BAR; PG8_SCHED;
	ds_read_b128 v[110:113], v209
	ds_read_b128 v[126:129], v209 offset:1024
	ds_read_b128 v[130:133], v209 offset:2048
	ds_read_b128 v[142:145], v209 offset:3072
	ds_read_b128 v[146:149], v210
	ds_read_b128 v[150:153], v210 offset:1024
	ds_read_b128 v[154:157], v210 offset:2048
	ds_read_b128 v[158:161], v210 offset:3072
	ds_read_b128 v[162:165], v208 offset:32768
	ds_read_b128 v[166:169], v208 offset:33792
	ds_read_b128 v[170:173], v208 offset:34816
	ds_read_b128 v[174:177], v208 offset:35840
	ds_read_b128 v[188:191], v208 offset:36864
	ds_read_b128 v[192:195], v208 offset:37888
	ds_read_b128 v[196:199], v208 offset:38912
	ds_read_b128 v[212:215], v208 offset:39936
	s_add_u32 s34, s34, 0x80000
	s_addc_u32 s35, s35, 0
	s_mov_b32 m0, s47
	s_nop 0
	global_load_lds_dwordx4 v179, s[34:35]
	s_nop 0
	s_mov_b32 m0, s48
	s_nop 0
	global_load_lds_dwordx4 v201, s[34:35]
	s_waitcnt vmcnt(8)
	s_waitcnt lgkmcnt(0)
	s_barrier
	s_setprio 1
	v_mfma_f32_16x16x32_bf16 v[138:141], v[110:113], v[162:165], v[138:141]
	v_mfma_f32_16x16x32_bf16 v[134:137], v[130:133], v[162:165], v[134:137]
	v_mfma_f32_16x16x32_bf16 v[114:117], v[110:113], v[170:173], v[114:117]
	v_mfma_f32_16x16x32_bf16 v[106:109], v[130:133], v[170:173], v[106:109]
	v_mfma_f32_16x16x32_bf16 v[94:97], v[110:113], v[188:191], v[94:97]
	v_mfma_f32_16x16x32_bf16 v[90:93], v[130:133], v[188:191], v[90:93]
	v_mfma_f32_16x16x32_bf16 v[78:81], v[110:113], v[196:199], v[78:81]
	v_mfma_f32_16x16x32_bf16 v[74:77], v[130:133], v[196:199], v[74:77]
	v_mfma_f32_16x16x32_bf16 v[138:141], v[126:129], v[166:169], v[138:141]
	v_mfma_f32_16x16x32_bf16 v[134:137], v[142:145], v[166:169], v[134:137]
	v_mfma_f32_16x16x32_bf16 v[114:117], v[126:129], v[174:177], v[114:117]
	v_mfma_f32_16x16x32_bf16 v[106:109], v[142:145], v[174:177], v[106:109]
	v_mfma_f32_16x16x32_bf16 v[94:97], v[126:129], v[192:195], v[94:97]
	v_mfma_f32_16x16x32_bf16 v[90:93], v[142:145], v[192:195], v[90:93]
	v_mfma_f32_16x16x32_bf16 v[78:81], v[126:129], v[212:215], v[78:81]
	v_mfma_f32_16x16x32_bf16 v[74:77], v[142:145], v[212:215], v[74:77]
	v_mfma_f32_16x16x32_bf16 v[122:125], v[146:149], v[162:165], v[122:125]
	v_mfma_f32_16x16x32_bf16 v[118:121], v[154:157], v[162:165], v[118:121]
	v_mfma_f32_16x16x32_bf16 v[102:105], v[146:149], v[170:173], v[102:105]
	v_mfma_f32_16x16x32_bf16 v[98:101], v[154:157], v[170:173], v[98:101]
	v_mfma_f32_16x16x32_bf16 v[86:89], v[146:149], v[188:191], v[86:89]
	v_mfma_f32_16x16x32_bf16 v[82:85], v[154:157], v[188:191], v[82:85]
	v_mfma_f32_16x16x32_bf16 v[70:73], v[146:149], v[196:199], v[70:73]
	v_mfma_f32_16x16x32_bf16 v[66:69], v[154:157], v[196:199], v[66:69]
	v_mfma_f32_16x16x32_bf16 v[122:125], v[150:153], v[166:169], v[122:125]
	v_mfma_f32_16x16x32_bf16 v[118:121], v[158:161], v[166:169], v[118:121]
	v_mfma_f32_16x16x32_bf16 v[102:105], v[150:153], v[174:177], v[102:105]
	v_mfma_f32_16x16x32_bf16 v[98:101], v[158:161], v[174:177], v[98:101]
	v_mfma_f32_16x16x32_bf16 v[86:89], v[150:153], v[192:195], v[86:89]
	v_mfma_f32_16x16x32_bf16 v[82:85], v[158:161], v[192:195], v[82:85]
	v_mfma_f32_16x16x32_bf16 v[70:73], v[150:153], v[212:215], v[70:73]
	v_mfma_f32_16x16x32_bf16 v[66:69], v[158:161], v[212:215], v[66:69]
	s_setprio 0
	s_barrier
	ds_read_b128 v[162:165], v208 offset:49152
	ds_read_b128 v[166:169], v208 offset:50176
	ds_read_b128 v[170:173], v208 offset:51200
	ds_read_b128 v[174:177], v208 offset:52224
	ds_read_b128 v[188:191], v208 offset:53248
	ds_read_b128 v[192:195], v208 offset:54272
	ds_read_b128 v[196:199], v208 offset:55296
	ds_read_b128 v[212:215], v208 offset:56320
	s_add_u32 s34, s30, 0x80
	s_addc_u32 s35, s31, 0
	s_mov_b32 m0, s49
	s_nop 0
	global_load_lds_dwordx4 v200, s[34:35]
	s_add_u32 s30, s30, 0x80080
	s_mov_b32 m0, s50
	s_nop 0
	global_load_lds_dwordx4 v203, s[34:35]
	s_addc_u32 s31, s31, 0
	s_mov_b32 m0, s53
	s_nop 0
	global_load_lds_dwordx4 v200, s[30:31]
	s_nop 0
	s_mov_b32 m0, s54
	s_nop 0
	global_load_lds_dwordx4 v203, s[30:31]
	s_mov_b32 m0, s51
	s_nop 0
	global_load_lds_dwordx4 v179, s[28:29]
	s_nop 0
	s_mov_b32 m0, s52
	s_nop 0
	global_load_lds_dwordx4 v201, s[28:29]
	s_waitcnt vmcnt(8)
	s_waitcnt lgkmcnt(0)
	s_barrier
	s_setprio 1
	v_mfma_f32_16x16x32_bf16 v[62:65], v[110:113], v[162:165], v[62:65]
	v_mfma_f32_16x16x32_bf16 v[58:61], v[130:133], v[162:165], v[58:61]
	v_mfma_f32_16x16x32_bf16 v[46:49], v[110:113], v[170:173], v[46:49]
	v_mfma_f32_16x16x32_bf16 v[42:45], v[130:133], v[170:173], v[42:45]
	s_add_i32 s59, s59, 2
	s_add_u32 s19, s19, 0x100
	s_addc_u32 s21, s21, 0
	s_add_u32 s57, s57, 0x100
	s_addc_u32 s58, s58, 0
	s_add_u32 s26, s26, 0x100
	s_addc_u32 s27, s27, 0
	s_cmp_gt_u32 s59, 29
	v_mfma_f32_16x16x32_bf16 v[30:33], v[110:113], v[188:191], v[30:33]
	v_mfma_f32_16x16x32_bf16 v[26:29], v[130:133], v[188:191], v[26:29]
	v_mfma_f32_16x16x32_bf16 v[14:17], v[110:113], v[196:199], v[14:17]
	v_mfma_f32_16x16x32_bf16 v[10:13], v[130:133], v[196:199], v[10:13]
	v_mfma_f32_16x16x32_bf16 v[62:65], v[126:129], v[166:169], v[62:65]
	v_mfma_f32_16x16x32_bf16 v[58:61], v[142:145], v[166:169], v[58:61]
	v_mfma_f32_16x16x32_bf16 v[46:49], v[126:129], v[174:177], v[46:49]
	v_mfma_f32_16x16x32_bf16 v[42:45], v[142:145], v[174:177], v[42:45]
	v_mfma_f32_16x16x32_bf16 v[30:33], v[126:129], v[192:195], v[30:33]
	v_mfma_f32_16x16x32_bf16 v[26:29], v[142:145], v[192:195], v[26:29]
	v_mfma_f32_16x16x32_bf16 v[14:17], v[126:129], v[212:215], v[14:17]
	v_mfma_f32_16x16x32_bf16 v[10:13], v[142:145], v[212:215], v[10:13]
	v_mfma_f32_16x16x32_bf16 v[54:57], v[146:149], v[162:165], v[54:57]
	v_mfma_f32_16x16x32_bf16 v[50:53], v[154:157], v[162:165], v[50:53]
	v_mfma_f32_16x16x32_bf16 v[38:41], v[146:149], v[170:173], v[38:41]
	v_mfma_f32_16x16x32_bf16 v[34:37], v[154:157], v[170:173], v[34:37]
	v_mfma_f32_16x16x32_bf16 v[22:25], v[146:149], v[188:191], v[22:25]
	v_mfma_f32_16x16x32_bf16 v[18:21], v[154:157], v[188:191], v[18:21]
	v_mfma_f32_16x16x32_bf16 v[6:9], v[146:149], v[196:199], v[6:9]
	v_mfma_f32_16x16x32_bf16 v[2:5], v[154:157], v[196:199], v[2:5]
	v_mfma_f32_16x16x32_bf16 v[54:57], v[150:153], v[166:169], v[54:57]
	v_mfma_f32_16x16x32_bf16 v[50:53], v[158:161], v[166:169], v[50:53]
	v_mfma_f32_16x16x32_bf16 v[38:41], v[150:153], v[174:177], v[38:41]
	v_mfma_f32_16x16x32_bf16 v[34:37], v[158:161], v[174:177], v[34:37]
	v_mfma_f32_16x16x32_bf16 v[22:25], v[150:153], v[192:195], v[22:25]
	v_mfma_f32_16x16x32_bf16 v[18:21], v[158:161], v[192:195], v[18:21]
	v_mfma_f32_16x16x32_bf16 v[6:9], v[150:153], v[212:215], v[6:9]
	v_mfma_f32_16x16x32_bf16 v[2:5], v[158:161], v[212:215], v[2:5]
	s_setprio 0
	s_barrier
	s_cbranch_scc0 .LBB0_1994
	s_and_b64 vcc, exec, s[16:17]
	s_cbranch_vccz .LBB0_1997
	s_barrier

; #define PG8_STAGE(bufoff, gbase, voff) do { _Pragma("unroll") for (int _i = 0; _i < 2; ++_i) { unsigned keep_; \
;         asm volatile("s_mov_b32 %0, m0\n\ts_mov_b32 m0, %3\n\ts_nop 0\n\tglobal_load_lds_dwordx4 %1, %2\n\ts_mov_b32 m0, %0" \
;             : "=&s"(keep_) : "v"((voff)[_i]), "s"((const void*)(gbase)), "s"(ldsb0 + (unsigned)(bufoff) + (unsigned)(_i * 8192)) : "memory"); } } while (0)
; #define PG8_LDA(dst, b, h) do { _Pragma("unroll") for (int m = 0; m < 4; ++m) _Pragma("unroll") for (int k = 0; k < 2; ++k) dst[m][k] = *(const LAS bf16x8*)(lds + PG8_SA(b, h) + aoff + m * 2048 + k * 1024); } while (0)
; #define PG8_LDB(dst, b, h) do { _Pragma("unroll") for (int n = 0; n < 2; ++n) _Pragma("unroll") for (int k = 0; k < 2; ++k) dst[n][k] = *(const LAS bf16x8*)(lds + PG8_SB(b, h) + boff + n * 2048 + k * 1024); } while (0)
; #define PG8_MMA(ai, bj, At, Bt) do { __builtin_amdgcn_s_setprio(1); _Pragma("unroll") for (int m = 0; m < 4; ++m) _Pragma("unroll") for (int n = 0; n < 2; ++n) _Pragma("unroll") for (int k = 0; k < 2; ++k) \
;         acc[ai][bj][m][n] = __builtin_amdgcn_mfma_f32_16x16x32_bf16(Bt[n][k], At[m][k], acc[ai][bj][m][n], 0, 0, 0); __builtin_amdgcn_s_setprio(0); } while (0)
; #define PG8_WAIT_V(n) asm volatile("s_waitcnt vmcnt(" #n ")" ::: "memory")
; #define PG8_WAIT_L(n) asm volatile("s_waitcnt lgkmcnt(" #n ")" ::: "memory")
; template <class Epi, class Sched, bool ALIGN_EPI>
; __device__ __forceinline__ void gemm_phase(LAS unsigned char* lds, const Gemm g, const Sched& S, const Epi& E) {
;     ...
;             const bool last = (t == nt - 2);
;             const char* a1 = cA + (size_t)(t + 1) * kstep;
;             const char* a2 = last ? nA : cA + (size_t)(t + 2) * kstep; const char* b2 = last ? nB : cB + (size_t)(t + 2) * kstep;
;             const char* a3 = a2 + kstep; const char* b3 = b2 + kstep;
;             PG8_LDB(B0, 0, 0); PG8_LDB(B1, 0, 1); PG8_SCHED; PG8_LDA(At, 0, 0); PG8_STAGE(PG8_SA(1, 1), a1 + hstepA, voffA);
;             PG8_WAIT_V(8); PG8_WAIT_L(0); PG8_BAR; PG8_MMA(0, 0, At, B0); PG8_MMA(0, 1, At, B1); PG8_BAR; PG8_SCHED;
;             PG8_LDA(At, 0, 1); PG8_STAGE(PG8_SB(0, 0), b2, voffB); PG8_STAGE(PG8_SB(0, 1), b2 + hstepB, voffB); PG8_STAGE(PG8_SA(0, 0), a2, voffA);
;             PG8_WAIT_V(8); PG8_WAIT_L(0); PG8_BAR; PG8_MMA(1, 0, At, B0); PG8_MMA(1, 1, At, B1); PG8_BAR; PG8_SCHED;
.LBB0_2075:
	ds_read_b128 v[154:157], v141
	ds_read_b128 v[158:161], v141 offset:1024
	ds_read_b128 v[162:165], v141 offset:2048
	ds_read_b128 v[166:169], v141 offset:3072
	ds_read_b128 v[170:173], v142
	ds_read_b128 v[174:177], v142 offset:1024
	ds_read_b128 v[180:183], v142 offset:2048
	ds_read_b128 v[184:187], v142 offset:3072
	s_add_u32 s28, s26, 0x100
	s_addc_u32 s29, s27, 0
	s_cmp_eq_u32 s60, 28
	s_cselect_b32 s36, s5, s28
	s_cselect_b32 s37, s3, s29
	s_cselect_b32 s34, s7, s19
	s_cselect_b32 s35, s6, s21
	s_add_u32 s30, s36, 0x80
	s_addc_u32 s31, s37, 0
	ds_read_b128 v[188:191], v143
	ds_read_b128 v[192:195], v143 offset:1024
	ds_read_b128 v[196:199], v143 offset:2048
	ds_read_b128 v[204:207], v143 offset:3072
	ds_read_b128 v[208:211], v143 offset:4096
	ds_read_b128 v[212:215], v143 offset:5120
	ds_read_b128 v[216:219], v143 offset:6144
	ds_read_b128 v[220:223], v143 offset:7168
	s_add_u32 s26, s26, 0x80080
	s_addc_u32 s27, s27, 0
	s_mov_b32 m0, s57
	s_nop 0
	global_load_lds_dwordx4 v134, s[26:27]
	s_nop 0
	s_mov_b32 m0, s58
	s_nop 0
	global_load_lds_dwordx4 v136, s[26:27]
	s_waitcnt vmcnt(8)
	s_waitcnt lgkmcnt(0)
	s_barrier
	s_setprio 1
	v_mfma_f32_16x16x32_bf16 v[126:129], v[154:157], v[188:191], v[126:129]
	v_mfma_f32_16x16x32_bf16 v[122:125], v[162:165], v[188:191], v[122:125]
	v_mfma_f32_16x16x32_bf16 v[110:113], v[154:157], v[196:199], v[110:113]
	v_mfma_f32_16x16x32_bf16 v[106:109], v[162:165], v[196:199], v[106:109]
	v_mfma_f32_16x16x32_bf16 v[94:97], v[154:157], v[208:211], v[94:97]
	v_mfma_f32_16x16x32_bf16 v[90:93], v[162:165], v[208:211], v[90:93]
	v_mfma_f32_16x16x32_bf16 v[78:81], v[154:157], v[216:219], v[78:81]
	v_mfma_f32_16x16x32_bf16 v[74:77], v[162:165], v[216:219], v[74:77]
	v_mfma_f32_16x16x32_bf16 v[126:129], v[158:161], v[192:195], v[126:129]
	v_mfma_f32_16x16x32_bf16 v[122:125], v[166:169], v[192:195], v[122:125]
	v_mfma_f32_16x16x32_bf16 v[110:113], v[158:161], v[204:207], v[110:113]
	v_mfma_f32_16x16x32_bf16 v[106:109], v[166:169], v[204:207], v[106:109]
	v_mfma_f32_16x16x32_bf16 v[94:97], v[158:161], v[212:215], v[94:97]
	v_mfma_f32_16x16x32_bf16 v[90:93], v[166:169], v[212:215], v[90:93]
	v_mfma_f32_16x16x32_bf16 v[78:81], v[158:161], v[220:223], v[78:81]
	v_mfma_f32_16x16x32_bf16 v[74:77], v[166:169], v[220:223], v[74:77]
	v_mfma_f32_16x16x32_bf16 v[118:121], v[170:173], v[188:191], v[118:121]
	v_mfma_f32_16x16x32_bf16 v[114:117], v[180:183], v[188:191], v[114:117]
	v_mfma_f32_16x16x32_bf16 v[102:105], v[170:173], v[196:199], v[102:105]
	v_mfma_f32_16x16x32_bf16 v[98:101], v[180:183], v[196:199], v[98:101]
	v_mfma_f32_16x16x32_bf16 v[86:89], v[170:173], v[208:211], v[86:89]
	v_mfma_f32_16x16x32_bf16 v[82:85], v[180:183], v[208:211], v[82:85]
	v_mfma_f32_16x16x32_bf16 v[70:73], v[170:173], v[216:219], v[70:73]
	v_mfma_f32_16x16x32_bf16 v[66:69], v[180:183], v[216:219], v[66:69]
	v_mfma_f32_16x16x32_bf16 v[118:121], v[174:177], v[192:195], v[118:121]
	v_mfma_f32_16x16x32_bf16 v[114:117], v[184:187], v[192:195], v[114:117]
	v_mfma_f32_16x16x32_bf16 v[102:105], v[174:177], v[204:207], v[102:105]
	v_mfma_f32_16x16x32_bf16 v[98:101], v[184:187], v[204:207], v[98:101]
	v_mfma_f32_16x16x32_bf16 v[86:89], v[174:177], v[212:215], v[86:89]
	v_mfma_f32_16x16x32_bf16 v[82:85], v[184:187], v[212:215], v[82:85]
	v_mfma_f32_16x16x32_bf16 v[70:73], v[174:177], v[220:223], v[70:73]
	v_mfma_f32_16x16x32_bf16 v[66:69], v[184:187], v[220:223], v[66:69]
	s_setprio 0
	s_barrier
	ds_read_b128 v[188:191], v143 offset:16384
	ds_read_b128 v[192:195], v143 offset:17408
	ds_read_b128 v[196:199], v143 offset:18432
	ds_read_b128 v[204:207], v143 offset:19456
	ds_read_b128 v[208:211], v143 offset:20480
	ds_read_b128 v[212:215], v143 offset:21504
	ds_read_b128 v[216:219], v143 offset:22528
	ds_read_b128 v[220:223], v143 offset:23552
	s_mov_b32 m0, s44
	s_nop 0
	global_load_lds_dwordx4 v135, s[34:35]
	s_nop 0
	s_mov_b32 m0, s45
	s_nop 0
	global_load_lds_dwordx4 v137, s[34:35]
	s_add_u32 s26, s34, 0x80000
	s_addc_u32 s27, s35, 0
	s_mov_b32 m0, s46
	s_nop 0
	global_load_lds_dwordx4 v135, s[26:27]
	s_nop 0
	s_mov_b32 m0, s47
	s_nop 0
	global_load_lds_dwordx4 v137, s[26:27]
	s_mov_b32 m0, s42
	s_nop 0
	global_load_lds_dwordx4 v134, s[36:37]
	s_nop 0
	s_mov_b32 m0, s48
	s_nop 0
	global_load_lds_dwordx4 v136, s[36:37]
	s_waitcnt vmcnt(8)
	s_waitcnt lgkmcnt(0)
	s_barrier
	s_setprio 1
	v_mfma_f32_16x16x32_bf16 v[62:65], v[154:157], v[188:191], v[62:65]
	v_mfma_f32_16x16x32_bf16 v[58:61], v[162:165], v[188:191], v[58:61]
	v_mfma_f32_16x16x32_bf16 v[46:49], v[154:157], v[196:199], v[46:49]
	v_mfma_f32_16x16x32_bf16 v[42:45], v[162:165], v[196:199], v[42:45]
	v_mfma_f32_16x16x32_bf16 v[30:33], v[154:157], v[208:211], v[30:33]
	v_mfma_f32_16x16x32_bf16 v[26:29], v[162:165], v[208:211], v[26:29]
	v_mfma_f32_16x16x32_bf16 v[14:17], v[154:157], v[216:219], v[14:17]
	v_mfma_f32_16x16x32_bf16 v[10:13], v[162:165], v[216:219], v[10:13]
	v_mfma_f32_16x16x32_bf16 v[62:65], v[158:161], v[192:195], v[62:65]
	v_mfma_f32_16x16x32_bf16 v[58:61], v[166:169], v[192:195], v[58:61]
	v_mfma_f32_16x16x32_bf16 v[46:49], v[158:161], v[204:207], v[46:49]
	v_mfma_f32_16x16x32_bf16 v[42:45], v[166:169], v[204:207], v[42:45]
	v_mfma_f32_16x16x32_bf16 v[30:33], v[158:161], v[212:215], v[30:33]
	v_mfma_f32_16x16x32_bf16 v[26:29], v[166:169], v[212:215], v[26:29]
	v_mfma_f32_16x16x32_bf16 v[14:17], v[158:161], v[220:223], v[14:17]
	v_mfma_f32_16x16x32_bf16 v[10:13], v[166:169], v[220:223], v[10:13]
	v_mfma_f32_16x16x32_bf16 v[54:57], v[170:173], v[188:191], v[54:57]
	v_mfma_f32_16x16x32_bf16 v[50:53], v[180:183], v[188:191], v[50:53]
	v_mfma_f32_16x16x32_bf16 v[38:41], v[170:173], v[196:199], v[38:41]
	v_mfma_f32_16x16x32_bf16 v[34:37], v[180:183], v[196:199], v[34:37]
	v_mfma_f32_16x16x32_bf16 v[22:25], v[170:173], v[208:211], v[22:25]
	v_mfma_f32_16x16x32_bf16 v[18:21], v[180:183], v[208:211], v[18:21]
	v_mfma_f32_16x16x32_bf16 v[6:9], v[170:173], v[216:219], v[6:9]
	v_mfma_f32_16x16x32_bf16 v[2:5], v[180:183], v[216:219], v[2:5]
	v_mfma_f32_16x16x32_bf16 v[54:57], v[174:177], v[192:195], v[54:57]
	v_mfma_f32_16x16x32_bf16 v[50:53], v[184:187], v[192:195], v[50:53]
	v_mfma_f32_16x16x32_bf16 v[38:41], v[174:177], v[204:207], v[38:41]
	v_mfma_f32_16x16x32_bf16 v[34:37], v[184:187], v[204:207], v[34:37]
	v_mfma_f32_16x16x32_bf16 v[22:25], v[174:177], v[212:215], v[22:25]
	v_mfma_f32_16x16x32_bf16 v[18:21], v[184:187], v[212:215], v[18:21]
	v_mfma_f32_16x16x32_bf16 v[6:9], v[174:177], v[220:223], v[6:9]
	v_mfma_f32_16x16x32_bf16 v[2:5], v[184:187], v[220:223], v[2:5]
	s_setprio 0
	s_barrier
; #define PG8_STAGE(bufoff, gbase, voff) do { _Pragma("unroll") for (int _i = 0; _i < 2; ++_i) { unsigned keep_; \
;         asm volatile("s_mov_b32 %0, m0\n\ts_mov_b32 m0, %3\n\ts_nop 0\n\tglobal_load_lds_dwordx4 %1, %2\n\ts_mov_b32 m0, %0" \
;             : "=&s"(keep_) : "v"((voff)[_i]), "s"((const void*)(gbase)), "s"(ldsb0 + (unsigned)(bufoff) + (unsigned)(_i * 8192)) : "memory"); } } while (0)
; #define PG8_LDA(dst, b, h) do { _Pragma("unroll") for (int m = 0; m < 4; ++m) _Pragma("unroll") for (int k = 0; k < 2; ++k) dst[m][k] = *(const LAS bf16x8*)(lds + PG8_SA(b, h) + aoff + m * 2048 + k * 1024); } while (0)
; #define PG8_LDB(dst, b, h) do { _Pragma("unroll") for (int n = 0; n < 2; ++n) _Pragma("unroll") for (int k = 0; k < 2; ++k) dst[n][k] = *(const LAS bf16x8*)(lds + PG8_SB(b, h) + boff + n * 2048 + k * 1024); } while (0)
; #define PG8_MMA(ai, bj, At, Bt) do { __builtin_amdgcn_s_setprio(1); _Pragma("unroll") for (int m = 0; m < 4; ++m) _Pragma("unroll") for (int n = 0; n < 2; ++n) _Pragma("unroll") for (int k = 0; k < 2; ++k) \
;         acc[ai][bj][m][n] = __builtin_amdgcn_mfma_f32_16x16x32_bf16(Bt[n][k], At[m][k], acc[ai][bj][m][n], 0, 0, 0); __builtin_amdgcn_s_setprio(0); } while (0)
; #define PG8_WAIT_V(n) asm volatile("s_waitcnt vmcnt(" #n ")" ::: "memory")
; #define PG8_WAIT_L(n) asm volatile("s_waitcnt lgkmcnt(" #n ")" ::: "memory")
; #define PG8_BAR __builtin_amdgcn_s_barrier()
; #define PG8_SCHED __builtin_amdgcn_sched_barrier(0)
; template <class Epi, class Sched, bool ALIGN_EPI>
; __device__ __forceinline__ void gemm_phase(LAS unsigned char* lds, const Gemm g, const Sched& S, const Epi& E) {
;     ...
;             PG8_LDB(B0, 1, 0); PG8_LDB(B1, 1, 1); PG8_SCHED; PG8_LDA(At, 1, 0); PG8_STAGE(PG8_SA(0, 1), a2 + hstepA, voffA);
;             PG8_WAIT_V(8); PG8_WAIT_L(0); PG8_BAR; PG8_MMA(0, 0, At, B0); PG8_MMA(0, 1, At, B1); PG8_BAR; PG8_SCHED;
;             PG8_LDA(At, 1, 1); PG8_STAGE(PG8_SB(1, 0), b3, voffB); PG8_STAGE(PG8_SB(1, 1), b3 + hstepB, voffB); PG8_STAGE(PG8_SA(1, 0), a3, voffA);
;             PG8_WAIT_V(8); PG8_WAIT_L(0); PG8_BAR; PG8_MMA(1, 0, At, B0); PG8_MMA(1, 1, At, B1); PG8_BAR; PG8_SCHED;
	ds_read_b128 v[154:157], v144
	ds_read_b128 v[158:161], v144 offset:1024
	ds_read_b128 v[162:165], v144 offset:2048
	ds_read_b128 v[166:169], v144 offset:3072
	ds_read_b128 v[170:173], v145
	ds_read_b128 v[174:177], v145 offset:1024
	ds_read_b128 v[180:183], v145 offset:2048
	ds_read_b128 v[184:187], v145 offset:3072
	ds_read_b128 v[188:191], v143 offset:32768
	ds_read_b128 v[192:195], v143 offset:33792
	ds_read_b128 v[196:199], v143 offset:34816
	ds_read_b128 v[204:207], v143 offset:35840
	ds_read_b128 v[208:211], v143 offset:36864
	ds_read_b128 v[212:215], v143 offset:37888
	ds_read_b128 v[216:219], v143 offset:38912
	ds_read_b128 v[220:223], v143 offset:39936
	s_add_u32 s26, s36, 0x80000
	s_addc_u32 s27, s37, 0
	s_mov_b32 m0, s49
	s_nop 0
	global_load_lds_dwordx4 v134, s[26:27]
	s_nop 0
	s_mov_b32 m0, s50
	s_nop 0
	global_load_lds_dwordx4 v136, s[26:27]
	s_waitcnt vmcnt(8)
	s_waitcnt lgkmcnt(0)
	s_barrier
	s_setprio 1
	v_mfma_f32_16x16x32_bf16 v[126:129], v[154:157], v[188:191], v[126:129]
	v_mfma_f32_16x16x32_bf16 v[122:125], v[162:165], v[188:191], v[122:125]
	v_mfma_f32_16x16x32_bf16 v[110:113], v[154:157], v[196:199], v[110:113]
	v_mfma_f32_16x16x32_bf16 v[106:109], v[162:165], v[196:199], v[106:109]
	v_mfma_f32_16x16x32_bf16 v[94:97], v[154:157], v[208:211], v[94:97]
	v_mfma_f32_16x16x32_bf16 v[90:93], v[162:165], v[208:211], v[90:93]
	v_mfma_f32_16x16x32_bf16 v[78:81], v[154:157], v[216:219], v[78:81]
	v_mfma_f32_16x16x32_bf16 v[74:77], v[162:165], v[216:219], v[74:77]
	v_mfma_f32_16x16x32_bf16 v[126:129], v[158:161], v[192:195], v[126:129]
	v_mfma_f32_16x16x32_bf16 v[122:125], v[166:169], v[192:195], v[122:125]
	v_mfma_f32_16x16x32_bf16 v[110:113], v[158:161], v[204:207], v[110:113]
	v_mfma_f32_16x16x32_bf16 v[106:109], v[166:169], v[204:207], v[106:109]
	v_mfma_f32_16x16x32_bf16 v[94:97], v[158:161], v[212:215], v[94:97]
	v_mfma_f32_16x16x32_bf16 v[90:93], v[166:169], v[212:215], v[90:93]
	v_mfma_f32_16x16x32_bf16 v[78:81], v[158:161], v[220:223], v[78:81]
	v_mfma_f32_16x16x32_bf16 v[74:77], v[166:169], v[220:223], v[74:77]
	v_mfma_f32_16x16x32_bf16 v[118:121], v[170:173], v[188:191], v[118:121]
	v_mfma_f32_16x16x32_bf16 v[114:117], v[180:183], v[188:191], v[114:117]
	v_mfma_f32_16x16x32_bf16 v[102:105], v[170:173], v[196:199], v[102:105]
	v_mfma_f32_16x16x32_bf16 v[98:101], v[180:183], v[196:199], v[98:101]
	v_mfma_f32_16x16x32_bf16 v[86:89], v[170:173], v[208:211], v[86:89]
	v_mfma_f32_16x16x32_bf16 v[82:85], v[180:183], v[208:211], v[82:85]
	v_mfma_f32_16x16x32_bf16 v[70:73], v[170:173], v[216:219], v[70:73]
	v_mfma_f32_16x16x32_bf16 v[66:69], v[180:183], v[216:219], v[66:69]
	v_mfma_f32_16x16x32_bf16 v[118:121], v[174:177], v[192:195], v[118:121]
	v_mfma_f32_16x16x32_bf16 v[114:117], v[184:187], v[192:195], v[114:117]
	v_mfma_f32_16x16x32_bf16 v[102:105], v[174:177], v[204:207], v[102:105]
	v_mfma_f32_16x16x32_bf16 v[98:101], v[184:187], v[204:207], v[98:101]
	v_mfma_f32_16x16x32_bf16 v[86:89], v[174:177], v[212:215], v[86:89]
	v_mfma_f32_16x16x32_bf16 v[82:85], v[184:187], v[212:215], v[82:85]
	v_mfma_f32_16x16x32_bf16 v[70:73], v[174:177], v[220:223], v[70:73]
	v_mfma_f32_16x16x32_bf16 v[66:69], v[184:187], v[220:223], v[66:69]
	s_setprio 0
	s_barrier
	ds_read_b128 v[188:191], v143 offset:49152
	ds_read_b128 v[192:195], v143 offset:50176
	ds_read_b128 v[196:199], v143 offset:51200
	ds_read_b128 v[204:207], v143 offset:52224
	ds_read_b128 v[208:211], v143 offset:53248
	ds_read_b128 v[212:215], v143 offset:54272
	ds_read_b128 v[216:219], v143 offset:55296
	ds_read_b128 v[220:223], v143 offset:56320
	s_add_u32 s26, s34, 0x80
	s_addc_u32 s27, s35, 0
	s_mov_b32 m0, s51
	s_nop 0
	global_load_lds_dwordx4 v135, s[26:27]
	s_nop 0
	s_mov_b32 m0, s52
	s_nop 0
	global_load_lds_dwordx4 v137, s[26:27]
	s_add_u32 s26, s34, 0x80080
	s_addc_u32 s27, s35, 0
	s_mov_b32 m0, s55
	s_nop 0
	global_load_lds_dwordx4 v135, s[26:27]
	s_nop 0
	s_mov_b32 m0, s56
	s_nop 0
	global_load_lds_dwordx4 v137, s[26:27]
	s_mov_b32 m0, s53
	s_nop 0
	global_load_lds_dwordx4 v134, s[30:31]
	s_nop 0
	s_mov_b32 m0, s54
	s_nop 0
	global_load_lds_dwordx4 v136, s[30:31]
	s_waitcnt vmcnt(8)
	s_waitcnt lgkmcnt(0)
	s_barrier
	s_setprio 1
	v_mfma_f32_16x16x32_bf16 v[62:65], v[154:157], v[188:191], v[62:65]
	v_mfma_f32_16x16x32_bf16 v[58:61], v[162:165], v[188:191], v[58:61]
	v_mfma_f32_16x16x32_bf16 v[46:49], v[154:157], v[196:199], v[46:49]
	v_mfma_f32_16x16x32_bf16 v[42:45], v[162:165], v[196:199], v[42:45]
	s_add_i32 s60, s60, 2
	s_add_u32 s19, s19, 0x100
	s_addc_u32 s21, s21, 0
	s_cmp_gt_u32 s60, 29
	s_mov_b64 s[26:27], s[28:29]
	v_mfma_f32_16x16x32_bf16 v[30:33], v[154:157], v[208:211], v[30:33]
	v_mfma_f32_16x16x32_bf16 v[26:29], v[162:165], v[208:211], v[26:29]
	v_mfma_f32_16x16x32_bf16 v[14:17], v[154:157], v[216:219], v[14:17]
	v_mfma_f32_16x16x32_bf16 v[10:13], v[162:165], v[216:219], v[10:13]
	v_mfma_f32_16x16x32_bf16 v[62:65], v[158:161], v[192:195], v[62:65]
	v_mfma_f32_16x16x32_bf16 v[58:61], v[166:169], v[192:195], v[58:61]
	v_mfma_f32_16x16x32_bf16 v[46:49], v[158:161], v[204:207], v[46:49]
	v_mfma_f32_16x16x32_bf16 v[42:45], v[166:169], v[204:207], v[42:45]
	v_mfma_f32_16x16x32_bf16 v[30:33], v[158:161], v[212:215], v[30:33]
	v_mfma_f32_16x16x32_bf16 v[26:29], v[166:169], v[212:215], v[26:29]
	v_mfma_f32_16x16x32_bf16 v[14:17], v[158:161], v[220:223], v[14:17]
	v_mfma_f32_16x16x32_bf16 v[10:13], v[166:169], v[220:223], v[10:13]
	v_mfma_f32_16x16x32_bf16 v[54:57], v[170:173], v[188:191], v[54:57]
	v_mfma_f32_16x16x32_bf16 v[50:53], v[180:183], v[188:191], v[50:53]
	v_mfma_f32_16x16x32_bf16 v[38:41], v[170:173], v[196:199], v[38:41]
	v_mfma_f32_16x16x32_bf16 v[34:37], v[180:183], v[196:199], v[34:37]
	v_mfma_f32_16x16x32_bf16 v[22:25], v[170:173], v[208:211], v[22:25]
	v_mfma_f32_16x16x32_bf16 v[18:21], v[180:183], v[208:211], v[18:21]
	v_mfma_f32_16x16x32_bf16 v[6:9], v[170:173], v[216:219], v[6:9]
	v_mfma_f32_16x16x32_bf16 v[2:5], v[180:183], v[216:219], v[2:5]
	v_mfma_f32_16x16x32_bf16 v[54:57], v[174:177], v[192:195], v[54:57]
	v_mfma_f32_16x16x32_bf16 v[50:53], v[184:187], v[192:195], v[50:53]
	v_mfma_f32_16x16x32_bf16 v[38:41], v[174:177], v[204:207], v[38:41]
	v_mfma_f32_16x16x32_bf16 v[34:37], v[184:187], v[204:207], v[34:37]
	v_mfma_f32_16x16x32_bf16 v[22:25], v[174:177], v[212:215], v[22:25]
	v_mfma_f32_16x16x32_bf16 v[18:21], v[184:187], v[212:215], v[18:21]
	v_mfma_f32_16x16x32_bf16 v[6:9], v[174:177], v[220:223], v[6:9]
	v_mfma_f32_16x16x32_bf16 v[2:5], v[184:187], v[220:223], v[2:5]
	s_setprio 0
	s_barrier
	s_cbranch_scc0 .LBB0_2075
	s_and_b64 vcc, exec, s[16:17]
	s_cbranch_vccz .LBB0_2078
	s_barrier

; #define PG8_STAGE(bufoff, gbase, voff) do { _Pragma("unroll") for (int _i = 0; _i < 2; ++_i) { unsigned keep_; \
;         asm volatile("s_mov_b32 %0, m0\n\ts_mov_b32 m0, %3\n\ts_nop 0\n\tglobal_load_lds_dwordx4 %1, %2\n\ts_mov_b32 m0, %0" \
;             : "=&s"(keep_) : "v"((voff)[_i]), "s"((const void*)(gbase)), "s"(ldsb0 + (unsigned)(bufoff) + (unsigned)(_i * 8192)) : "memory"); } } while (0)
; #define PG8_LDA(dst, b, h) do { _Pragma("unroll") for (int m = 0; m < 4; ++m) _Pragma("unroll") for (int k = 0; k < 2; ++k) dst[m][k] = *(const LAS bf16x8*)(lds + PG8_SA(b, h) + aoff + m * 2048 + k * 1024); } while (0)
; #define PG8_LDB(dst, b, h) do { _Pragma("unroll") for (int n = 0; n < 2; ++n) _Pragma("unroll") for (int k = 0; k < 2; ++k) dst[n][k] = *(const LAS bf16x8*)(lds + PG8_SB(b, h) + boff + n * 2048 + k * 1024); } while (0)
; #define PG8_MMA(ai, bj, At, Bt) do { __builtin_amdgcn_s_setprio(1); _Pragma("unroll") for (int m = 0; m < 4; ++m) _Pragma("unroll") for (int n = 0; n < 2; ++n) _Pragma("unroll") for (int k = 0; k < 2; ++k) \
;         acc[ai][bj][m][n] = __builtin_amdgcn_mfma_f32_16x16x32_bf16(Bt[n][k], At[m][k], acc[ai][bj][m][n], 0, 0, 0); __builtin_amdgcn_s_setprio(0); } while (0)
; #define PG8_WAIT_V(n) asm volatile("s_waitcnt vmcnt(" #n ")" ::: "memory")
; #define PG8_WAIT_L(n) asm volatile("s_waitcnt lgkmcnt(" #n ")" ::: "memory")
; template <class Epi, class Sched, bool ALIGN_EPI>
; __device__ __forceinline__ void gemm_phase(LAS unsigned char* lds, const Gemm g, const Sched& S, const Epi& E) {
;     ...
;             const bool last = (t == nt - 2);
;             const char* a1 = cA + (size_t)(t + 1) * kstep;
;             const char* a2 = last ? nA : cA + (size_t)(t + 2) * kstep; const char* b2 = last ? nB : cB + (size_t)(t + 2) * kstep;
;             const char* a3 = a2 + kstep; const char* b3 = b2 + kstep;
;             PG8_LDB(B0, 0, 0); PG8_LDB(B1, 0, 1); PG8_SCHED; PG8_LDA(At, 0, 0); PG8_STAGE(PG8_SA(1, 1), a1 + hstepA, voffA);
;             PG8_WAIT_V(8); PG8_WAIT_L(0); PG8_BAR; PG8_MMA(0, 0, At, B0); PG8_MMA(0, 1, At, B1); PG8_BAR; PG8_SCHED;
;             PG8_LDA(At, 0, 1); PG8_STAGE(PG8_SB(0, 0), b2, voffB); PG8_STAGE(PG8_SB(0, 1), b2 + hstepB, voffB); PG8_STAGE(PG8_SA(0, 0), a2, voffA);
;             PG8_WAIT_V(8); PG8_WAIT_L(0); PG8_BAR; PG8_MMA(1, 0, At, B0); PG8_MMA(1, 1, At, B1); PG8_BAR; PG8_SCHED;
.LBB0_2172:
	s_add_u32 s61, s22, s26
	s_addc_u32 s63, s23, s27
	s_add_u32 s28, s61, 0x100
	v_add_u32_e32 v141, 0x10000, v139
	s_addc_u32 s29, s63, 0
	ds_read_b128 v[142:145], v141
	ds_read_b128 v[146:149], v141 offset:1024
	ds_read_b128 v[150:153], v141 offset:2048
	ds_read_b128 v[154:157], v141 offset:3072
	v_add_u32_e32 v141, 0x14000, v139
	s_add_u32 s30, s20, s26
	ds_read_b128 v[158:161], v141
	ds_read_b128 v[162:165], v141 offset:1024
	ds_read_b128 v[166:169], v141 offset:2048
	ds_read_b128 v[170:173], v141 offset:3072
	s_addc_u32 s31, s21, s27
	s_add_u32 s30, s30, 0x100
	s_addc_u32 s31, s31, 0
	s_cmpk_eq_i32 s60, 0x54
	s_cselect_b32 s34, s12, s28
	s_cselect_b32 s35, s13, s29
	s_cselect_b32 s30, s24, s30
	s_cselect_b32 s31, s25, s31
	s_add_u32 s28, s34, 0x80
	s_addc_u32 s29, s35, 0
	ds_read_b128 v[174:177], v140
	ds_read_b128 v[178:181], v140 offset:1024
	ds_read_b128 v[182:185], v140 offset:2048
	ds_read_b128 v[186:189], v140 offset:3072
	ds_read_b128 v[190:193], v140 offset:4096
	ds_read_b128 v[194:197], v140 offset:5120
	ds_read_b128 v[198:201], v140 offset:6144
	ds_read_b128 v[204:207], v140 offset:7168
	s_add_u32 s62, s61, 0x160080
	s_addc_u32 s63, s63, 0
	s_mov_b32 m0, s54
	s_nop 0
	global_load_lds_dwordx4 v131, s[62:63]
	s_nop 0
	s_mov_b32 m0, s55
	s_nop 0
	global_load_lds_dwordx4 v137, s[62:63]
	s_waitcnt vmcnt(8)
	s_waitcnt lgkmcnt(0)
	s_barrier
	s_setprio 1
	v_mfma_f32_16x16x32_bf16 v[126:129], v[142:145], v[174:177], v[126:129]
	v_mfma_f32_16x16x32_bf16 v[122:125], v[150:153], v[174:177], v[122:125]
	v_mfma_f32_16x16x32_bf16 v[110:113], v[142:145], v[182:185], v[110:113]
	v_mfma_f32_16x16x32_bf16 v[106:109], v[150:153], v[182:185], v[106:109]
	v_mfma_f32_16x16x32_bf16 v[94:97], v[142:145], v[190:193], v[94:97]
	v_mfma_f32_16x16x32_bf16 v[90:93], v[150:153], v[190:193], v[90:93]
	v_mfma_f32_16x16x32_bf16 v[78:81], v[142:145], v[198:201], v[78:81]
	v_mfma_f32_16x16x32_bf16 v[74:77], v[150:153], v[198:201], v[74:77]
	v_mfma_f32_16x16x32_bf16 v[126:129], v[146:149], v[178:181], v[126:129]
	v_mfma_f32_16x16x32_bf16 v[122:125], v[154:157], v[178:181], v[122:125]
	v_mfma_f32_16x16x32_bf16 v[110:113], v[146:149], v[186:189], v[110:113]
	v_mfma_f32_16x16x32_bf16 v[106:109], v[154:157], v[186:189], v[106:109]
	v_mfma_f32_16x16x32_bf16 v[94:97], v[146:149], v[194:197], v[94:97]
	v_mfma_f32_16x16x32_bf16 v[90:93], v[154:157], v[194:197], v[90:93]
	v_mfma_f32_16x16x32_bf16 v[78:81], v[146:149], v[204:207], v[78:81]
	v_mfma_f32_16x16x32_bf16 v[74:77], v[154:157], v[204:207], v[74:77]
	v_mfma_f32_16x16x32_bf16 v[118:121], v[158:161], v[174:177], v[118:121]
	v_mfma_f32_16x16x32_bf16 v[114:117], v[166:169], v[174:177], v[114:117]
	v_mfma_f32_16x16x32_bf16 v[102:105], v[158:161], v[182:185], v[102:105]
	v_mfma_f32_16x16x32_bf16 v[98:101], v[166:169], v[182:185], v[98:101]
	v_mfma_f32_16x16x32_bf16 v[86:89], v[158:161], v[190:193], v[86:89]
	v_mfma_f32_16x16x32_bf16 v[82:85], v[166:169], v[190:193], v[82:85]
	v_mfma_f32_16x16x32_bf16 v[70:73], v[158:161], v[198:201], v[70:73]
	v_mfma_f32_16x16x32_bf16 v[66:69], v[166:169], v[198:201], v[66:69]
	v_mfma_f32_16x16x32_bf16 v[118:121], v[162:165], v[178:181], v[118:121]
	v_mfma_f32_16x16x32_bf16 v[114:117], v[170:173], v[178:181], v[114:117]
	v_mfma_f32_16x16x32_bf16 v[102:105], v[162:165], v[186:189], v[102:105]
	v_mfma_f32_16x16x32_bf16 v[98:101], v[170:173], v[186:189], v[98:101]
	v_mfma_f32_16x16x32_bf16 v[86:89], v[162:165], v[194:197], v[86:89]
	v_mfma_f32_16x16x32_bf16 v[82:85], v[170:173], v[194:197], v[82:85]
	v_mfma_f32_16x16x32_bf16 v[70:73], v[162:165], v[204:207], v[70:73]
	v_mfma_f32_16x16x32_bf16 v[66:69], v[170:173], v[204:207], v[66:69]
	s_setprio 0
	s_barrier
	ds_read_b128 v[174:177], v140 offset:16384
	ds_read_b128 v[178:181], v140 offset:17408
	ds_read_b128 v[182:185], v140 offset:18432
	ds_read_b128 v[186:189], v140 offset:19456
	ds_read_b128 v[190:193], v140 offset:20480
	ds_read_b128 v[194:197], v140 offset:21504
	ds_read_b128 v[198:201], v140 offset:22528
	ds_read_b128 v[204:207], v140 offset:23552
	s_mov_b32 m0, s3
	s_nop 0
	global_load_lds_dwordx4 v136, s[30:31]
	s_add_u32 s62, s30, 0x160000
	s_mov_b32 m0, s41
	s_nop 0
	global_load_lds_dwordx4 v138, s[30:31]
	s_addc_u32 s63, s31, 0
	s_mov_b32 m0, s42
	s_nop 0
	global_load_lds_dwordx4 v136, s[62:63]
	s_nop 0
	s_mov_b32 m0, s43
	s_nop 0
	global_load_lds_dwordx4 v138, s[62:63]
	s_nop 0
	s_mov_b32 m0, s2
	s_nop 0
	global_load_lds_dwordx4 v131, s[34:35]
	s_nop 0
	s_mov_b32 m0, s44
	s_nop 0
	global_load_lds_dwordx4 v137, s[34:35]
	s_waitcnt vmcnt(8)
	s_waitcnt lgkmcnt(0)
	s_barrier
; #define PG8_STAGE(bufoff, gbase, voff) do { _Pragma("unroll") for (int _i = 0; _i < 2; ++_i) { unsigned keep_; \
;         asm volatile("s_mov_b32 %0, m0\n\ts_mov_b32 m0, %3\n\ts_nop 0\n\tglobal_load_lds_dwordx4 %1, %2\n\ts_mov_b32 m0, %0" \
;             : "=&s"(keep_) : "v"((voff)[_i]), "s"((const void*)(gbase)), "s"(ldsb0 + (unsigned)(bufoff) + (unsigned)(_i * 8192)) : "memory"); } } while (0)
; #define PG8_LDA(dst, b, h) do { _Pragma("unroll") for (int m = 0; m < 4; ++m) _Pragma("unroll") for (int k = 0; k < 2; ++k) dst[m][k] = *(const LAS bf16x8*)(lds + PG8_SA(b, h) + aoff + m * 2048 + k * 1024); } while (0)
; #define PG8_LDB(dst, b, h) do { _Pragma("unroll") for (int n = 0; n < 2; ++n) _Pragma("unroll") for (int k = 0; k < 2; ++k) dst[n][k] = *(const LAS bf16x8*)(lds + PG8_SB(b, h) + boff + n * 2048 + k * 1024); } while (0)
; #define PG8_MMA(ai, bj, At, Bt) do { __builtin_amdgcn_s_setprio(1); _Pragma("unroll") for (int m = 0; m < 4; ++m) _Pragma("unroll") for (int n = 0; n < 2; ++n) _Pragma("unroll") for (int k = 0; k < 2; ++k) \
;         acc[ai][bj][m][n] = __builtin_amdgcn_mfma_f32_16x16x32_bf16(Bt[n][k], At[m][k], acc[ai][bj][m][n], 0, 0, 0); __builtin_amdgcn_s_setprio(0); } while (0)
; #define PG8_WAIT_V(n) asm volatile("s_waitcnt vmcnt(" #n ")" ::: "memory")
; #define PG8_WAIT_L(n) asm volatile("s_waitcnt lgkmcnt(" #n ")" ::: "memory")
; #define PG8_BAR __builtin_amdgcn_s_barrier()
; #define PG8_SCHED __builtin_amdgcn_sched_barrier(0)
; template <class Epi, class Sched, bool ALIGN_EPI>
; __device__ __forceinline__ void gemm_phase(LAS unsigned char* lds, const Gemm g, const Sched& S, const Epi& E) {
;     ...
;             PG8_WAIT_V(8); PG8_WAIT_L(0); PG8_BAR; PG8_MMA(0, 0, At, B0); PG8_MMA(0, 1, At, B1); PG8_BAR; PG8_SCHED;
;             PG8_LDA(At, 0, 1); PG8_STAGE(PG8_SB(0, 0), b2, voffB); PG8_STAGE(PG8_SB(0, 1), b2 + hstepB, voffB); PG8_STAGE(PG8_SA(0, 0), a2, voffA);
;             PG8_WAIT_V(8); PG8_WAIT_L(0); PG8_BAR; PG8_MMA(1, 0, At, B0); PG8_MMA(1, 1, At, B1); PG8_BAR; PG8_SCHED;
;             PG8_LDB(B0, 1, 0); PG8_LDB(B1, 1, 1); PG8_SCHED; PG8_LDA(At, 1, 0); PG8_STAGE(PG8_SA(0, 1), a2 + hstepA, voffA);
;             PG8_WAIT_V(8); PG8_WAIT_L(0); PG8_BAR; PG8_MMA(0, 0, At, B0); PG8_MMA(0, 1, At, B1); PG8_BAR; PG8_SCHED;
	s_setprio 1
	v_mfma_f32_16x16x32_bf16 v[62:65], v[142:145], v[174:177], v[62:65]
	v_mfma_f32_16x16x32_bf16 v[58:61], v[150:153], v[174:177], v[58:61]
	v_mfma_f32_16x16x32_bf16 v[46:49], v[142:145], v[182:185], v[46:49]
	v_mfma_f32_16x16x32_bf16 v[42:45], v[150:153], v[182:185], v[42:45]
	v_mfma_f32_16x16x32_bf16 v[30:33], v[142:145], v[190:193], v[30:33]
	v_mfma_f32_16x16x32_bf16 v[26:29], v[150:153], v[190:193], v[26:29]
	v_mfma_f32_16x16x32_bf16 v[14:17], v[142:145], v[198:201], v[14:17]
	v_mfma_f32_16x16x32_bf16 v[10:13], v[150:153], v[198:201], v[10:13]
	v_mfma_f32_16x16x32_bf16 v[62:65], v[146:149], v[178:181], v[62:65]
	v_mfma_f32_16x16x32_bf16 v[58:61], v[154:157], v[178:181], v[58:61]
	v_mfma_f32_16x16x32_bf16 v[46:49], v[146:149], v[186:189], v[46:49]
	v_mfma_f32_16x16x32_bf16 v[42:45], v[154:157], v[186:189], v[42:45]
	v_mfma_f32_16x16x32_bf16 v[30:33], v[146:149], v[194:197], v[30:33]
	v_mfma_f32_16x16x32_bf16 v[26:29], v[154:157], v[194:197], v[26:29]
	v_mfma_f32_16x16x32_bf16 v[14:17], v[146:149], v[204:207], v[14:17]
	v_mfma_f32_16x16x32_bf16 v[10:13], v[154:157], v[204:207], v[10:13]
	v_mfma_f32_16x16x32_bf16 v[54:57], v[158:161], v[174:177], v[54:57]
	v_mfma_f32_16x16x32_bf16 v[50:53], v[166:169], v[174:177], v[50:53]
	v_mfma_f32_16x16x32_bf16 v[38:41], v[158:161], v[182:185], v[38:41]
	v_mfma_f32_16x16x32_bf16 v[34:37], v[166:169], v[182:185], v[34:37]
	v_mfma_f32_16x16x32_bf16 v[22:25], v[158:161], v[190:193], v[22:25]
	v_mfma_f32_16x16x32_bf16 v[18:21], v[166:169], v[190:193], v[18:21]
	v_mfma_f32_16x16x32_bf16 v[6:9], v[158:161], v[198:201], v[6:9]
	v_mfma_f32_16x16x32_bf16 v[2:5], v[166:169], v[198:201], v[2:5]
	v_mfma_f32_16x16x32_bf16 v[54:57], v[162:165], v[178:181], v[54:57]
	v_mfma_f32_16x16x32_bf16 v[50:53], v[170:173], v[178:181], v[50:53]
	v_mfma_f32_16x16x32_bf16 v[38:41], v[162:165], v[186:189], v[38:41]
	v_mfma_f32_16x16x32_bf16 v[34:37], v[170:173], v[186:189], v[34:37]
	v_mfma_f32_16x16x32_bf16 v[22:25], v[162:165], v[194:197], v[22:25]
	v_mfma_f32_16x16x32_bf16 v[18:21], v[170:173], v[194:197], v[18:21]
	v_mfma_f32_16x16x32_bf16 v[6:9], v[162:165], v[204:207], v[6:9]
	v_mfma_f32_16x16x32_bf16 v[2:5], v[170:173], v[204:207], v[2:5]
	s_setprio 0
	s_barrier
	v_add_u32_e32 v141, 0x18000, v139
	ds_read_b128 v[142:145], v141
	ds_read_b128 v[146:149], v141 offset:1024
	ds_read_b128 v[150:153], v141 offset:2048
	ds_read_b128 v[154:157], v141 offset:3072
	v_add_u32_e32 v141, 0x1c000, v139
	ds_read_b128 v[158:161], v141
	ds_read_b128 v[162:165], v141 offset:1024
	ds_read_b128 v[166:169], v141 offset:2048
	ds_read_b128 v[170:173], v141 offset:3072
	ds_read_b128 v[174:177], v140 offset:32768
	ds_read_b128 v[178:181], v140 offset:33792
	ds_read_b128 v[182:185], v140 offset:34816
	ds_read_b128 v[186:189], v140 offset:35840
	ds_read_b128 v[190:193], v140 offset:36864
	ds_read_b128 v[194:197], v140 offset:37888
	ds_read_b128 v[198:201], v140 offset:38912
	ds_read_b128 v[204:207], v140 offset:39936
	s_add_u32 s34, s34, 0x160000
	s_addc_u32 s35, s35, 0
	s_mov_b32 m0, s46
	s_nop 0
	global_load_lds_dwordx4 v131, s[34:35]
	s_nop 0
	s_mov_b32 m0, s47
	s_nop 0
	global_load_lds_dwordx4 v137, s[34:35]
	s_waitcnt vmcnt(8)
	s_waitcnt lgkmcnt(0)
	s_barrier
	s_setprio 1
	v_mfma_f32_16x16x32_bf16 v[126:129], v[142:145], v[174:177], v[126:129]
	v_mfma_f32_16x16x32_bf16 v[122:125], v[150:153], v[174:177], v[122:125]
	v_mfma_f32_16x16x32_bf16 v[110:113], v[142:145], v[182:185], v[110:113]
	v_mfma_f32_16x16x32_bf16 v[106:109], v[150:153], v[182:185], v[106:109]
	v_mfma_f32_16x16x32_bf16 v[94:97], v[142:145], v[190:193], v[94:97]
	v_mfma_f32_16x16x32_bf16 v[90:93], v[150:153], v[190:193], v[90:93]
	v_mfma_f32_16x16x32_bf16 v[78:81], v[142:145], v[198:201], v[78:81]
	v_mfma_f32_16x16x32_bf16 v[74:77], v[150:153], v[198:201], v[74:77]
	v_mfma_f32_16x16x32_bf16 v[126:129], v[146:149], v[178:181], v[126:129]
	v_mfma_f32_16x16x32_bf16 v[122:125], v[154:157], v[178:181], v[122:125]
	v_mfma_f32_16x16x32_bf16 v[110:113], v[146:149], v[186:189], v[110:113]
	v_mfma_f32_16x16x32_bf16 v[106:109], v[154:157], v[186:189], v[106:109]
	v_mfma_f32_16x16x32_bf16 v[94:97], v[146:149], v[194:197], v[94:97]
	v_mfma_f32_16x16x32_bf16 v[90:93], v[154:157], v[194:197], v[90:93]
	v_mfma_f32_16x16x32_bf16 v[78:81], v[146:149], v[204:207], v[78:81]
	v_mfma_f32_16x16x32_bf16 v[74:77], v[154:157], v[204:207], v[74:77]
	v_mfma_f32_16x16x32_bf16 v[118:121], v[158:161], v[174:177], v[118:121]
	v_mfma_f32_16x16x32_bf16 v[114:117], v[166:169], v[174:177], v[114:117]
	v_mfma_f32_16x16x32_bf16 v[102:105], v[158:161], v[182:185], v[102:105]
	v_mfma_f32_16x16x32_bf16 v[98:101], v[166:169], v[182:185], v[98:101]
	v_mfma_f32_16x16x32_bf16 v[86:89], v[158:161], v[190:193], v[86:89]
	v_mfma_f32_16x16x32_bf16 v[82:85], v[166:169], v[190:193], v[82:85]
	v_mfma_f32_16x16x32_bf16 v[70:73], v[158:161], v[198:201], v[70:73]
	v_mfma_f32_16x16x32_bf16 v[66:69], v[166:169], v[198:201], v[66:69]
	v_mfma_f32_16x16x32_bf16 v[118:121], v[162:165], v[178:181], v[118:121]
	v_mfma_f32_16x16x32_bf16 v[114:117], v[170:173], v[178:181], v[114:117]
	v_mfma_f32_16x16x32_bf16 v[102:105], v[162:165], v[186:189], v[102:105]
	v_mfma_f32_16x16x32_bf16 v[98:101], v[170:173], v[186:189], v[98:101]
	v_mfma_f32_16x16x32_bf16 v[86:89], v[162:165], v[194:197], v[86:89]
	v_mfma_f32_16x16x32_bf16 v[82:85], v[170:173], v[194:197], v[82:85]
	v_mfma_f32_16x16x32_bf16 v[70:73], v[162:165], v[204:207], v[70:73]
	v_mfma_f32_16x16x32_bf16 v[66:69], v[170:173], v[204:207], v[66:69]
	s_setprio 0
	s_barrier
; #define PG8_STAGE(bufoff, gbase, voff) do { _Pragma("unroll") for (int _i = 0; _i < 2; ++_i) { unsigned keep_; \
;         asm volatile("s_mov_b32 %0, m0\n\ts_mov_b32 m0, %3\n\ts_nop 0\n\tglobal_load_lds_dwordx4 %1, %2\n\ts_mov_b32 m0, %0" \
;             : "=&s"(keep_) : "v"((voff)[_i]), "s"((const void*)(gbase)), "s"(ldsb0 + (unsigned)(bufoff) + (unsigned)(_i * 8192)) : "memory"); } } while (0)
; #define PG8_LDA(dst, b, h) do { _Pragma("unroll") for (int m = 0; m < 4; ++m) _Pragma("unroll") for (int k = 0; k < 2; ++k) dst[m][k] = *(const LAS bf16x8*)(lds + PG8_SA(b, h) + aoff + m * 2048 + k * 1024); } while (0)
; #define PG8_MMA(ai, bj, At, Bt) do { __builtin_amdgcn_s_setprio(1); _Pragma("unroll") for (int m = 0; m < 4; ++m) _Pragma("unroll") for (int n = 0; n < 2; ++n) _Pragma("unroll") for (int k = 0; k < 2; ++k) \
;         acc[ai][bj][m][n] = __builtin_amdgcn_mfma_f32_16x16x32_bf16(Bt[n][k], At[m][k], acc[ai][bj][m][n], 0, 0, 0); __builtin_amdgcn_s_setprio(0); } while (0)
; #define PG8_WAIT_V(n) asm volatile("s_waitcnt vmcnt(" #n ")" ::: "memory")
; #define PG8_WAIT_L(n) asm volatile("s_waitcnt lgkmcnt(" #n ")" ::: "memory")
; #define PG8_BAR __builtin_amdgcn_s_barrier()
; #define PG8_SCHED __builtin_amdgcn_sched_barrier(0)
; template <class Epi, class Sched, bool ALIGN_EPI>
; __device__ __forceinline__ void gemm_phase(LAS unsigned char* lds, const Gemm g, const Sched& S, const Epi& E) {
;     ...
;             PG8_LDA(At, 1, 1); PG8_STAGE(PG8_SB(1, 0), b3, voffB); PG8_STAGE(PG8_SB(1, 1), b3 + hstepB, voffB); PG8_STAGE(PG8_SA(1, 0), a3, voffA);
;             PG8_WAIT_V(8); PG8_WAIT_L(0); PG8_BAR; PG8_MMA(1, 0, At, B0); PG8_MMA(1, 1, At, B1); PG8_BAR; PG8_SCHED;
;         }
;         if constexpr (ALIGN_EPI) { if (wr == 0) PG8_BAR; }
;         if constexpr (Epi::NPRE > 0) E(acc, cur, wr, wc, fr, fq, pre); else
;         if constexpr (!Epi::AFTER_DRAIN) E(acc, cur, wr, wc, fr, fq);
;         if (!has_next) break;
; #pragma unroll
;         for (int a = 0; a < 2; ++a)
; #pragma unroll
;             for (int b = 0; b < 2; ++b)
; #pragma unroll
;                 for (int m = 0; m < 4; ++m)
; #pragma unroll
;                     for (int n = 0; n < 2; ++n) acc[a][b][m][n] = (f32x4){0.f, 0.f, 0.f, 0.f};
;         cur = nxt; cA = nA; cB = nB; ++ui;
	ds_read_b128 v[174:177], v140 offset:49152
	ds_read_b128 v[178:181], v140 offset:50176
	ds_read_b128 v[182:185], v140 offset:51200
	ds_read_b128 v[186:189], v140 offset:52224
	ds_read_b128 v[190:193], v140 offset:53248
	ds_read_b128 v[194:197], v140 offset:54272
	ds_read_b128 v[198:201], v140 offset:55296
	ds_read_b128 v[204:207], v140 offset:56320
	s_add_u32 s34, s30, 0x80
	s_addc_u32 s35, s31, 0
	s_mov_b32 m0, s48
	s_nop 0
	global_load_lds_dwordx4 v136, s[34:35]
	s_add_u32 s30, s30, 0x160080
	s_mov_b32 m0, s49
	s_nop 0
	global_load_lds_dwordx4 v138, s[34:35]
	s_addc_u32 s31, s31, 0
	s_mov_b32 m0, s52
	s_nop 0
	global_load_lds_dwordx4 v136, s[30:31]
	s_nop 0
	s_mov_b32 m0, s53
	s_nop 0
	global_load_lds_dwordx4 v138, s[30:31]
	s_mov_b32 m0, s50
	s_nop 0
	global_load_lds_dwordx4 v131, s[28:29]
	s_nop 0
	s_mov_b32 m0, s51
	s_nop 0
	global_load_lds_dwordx4 v137, s[28:29]
	s_waitcnt vmcnt(8)
	s_waitcnt lgkmcnt(0)
	s_barrier
	s_setprio 1
	v_mfma_f32_16x16x32_bf16 v[62:65], v[142:145], v[174:177], v[62:65]
	v_mfma_f32_16x16x32_bf16 v[58:61], v[150:153], v[174:177], v[58:61]
	v_mfma_f32_16x16x32_bf16 v[46:49], v[142:145], v[182:185], v[46:49]
	v_mfma_f32_16x16x32_bf16 v[42:45], v[150:153], v[182:185], v[42:45]
	s_add_i32 s60, s60, 2
	s_add_u32 s26, s26, 0x100
	s_addc_u32 s27, s27, 0
	s_cmpk_gt_u32 s60, 0x55
	v_mfma_f32_16x16x32_bf16 v[30:33], v[142:145], v[190:193], v[30:33]
	v_mfma_f32_16x16x32_bf16 v[26:29], v[150:153], v[190:193], v[26:29]
	v_mfma_f32_16x16x32_bf16 v[14:17], v[142:145], v[198:201], v[14:17]
	v_mfma_f32_16x16x32_bf16 v[10:13], v[150:153], v[198:201], v[10:13]
	v_mfma_f32_16x16x32_bf16 v[62:65], v[146:149], v[178:181], v[62:65]
	v_mfma_f32_16x16x32_bf16 v[58:61], v[154:157], v[178:181], v[58:61]
	v_mfma_f32_16x16x32_bf16 v[46:49], v[146:149], v[186:189], v[46:49]
	v_mfma_f32_16x16x32_bf16 v[42:45], v[154:157], v[186:189], v[42:45]
	v_mfma_f32_16x16x32_bf16 v[30:33], v[146:149], v[194:197], v[30:33]
	v_mfma_f32_16x16x32_bf16 v[26:29], v[154:157], v[194:197], v[26:29]
	v_mfma_f32_16x16x32_bf16 v[14:17], v[146:149], v[204:207], v[14:17]
	v_mfma_f32_16x16x32_bf16 v[10:13], v[154:157], v[204:207], v[10:13]
	v_mfma_f32_16x16x32_bf16 v[54:57], v[158:161], v[174:177], v[54:57]
	v_mfma_f32_16x16x32_bf16 v[50:53], v[166:169], v[174:177], v[50:53]
	v_mfma_f32_16x16x32_bf16 v[38:41], v[158:161], v[182:185], v[38:41]
	v_mfma_f32_16x16x32_bf16 v[34:37], v[166:169], v[182:185], v[34:37]
	v_mfma_f32_16x16x32_bf16 v[22:25], v[158:161], v[190:193], v[22:25]
	v_mfma_f32_16x16x32_bf16 v[18:21], v[166:169], v[190:193], v[18:21]
	v_mfma_f32_16x16x32_bf16 v[6:9], v[158:161], v[198:201], v[6:9]
	v_mfma_f32_16x16x32_bf16 v[2:5], v[166:169], v[198:201], v[2:5]
	v_mfma_f32_16x16x32_bf16 v[54:57], v[162:165], v[178:181], v[54:57]
	v_mfma_f32_16x16x32_bf16 v[50:53], v[170:173], v[178:181], v[50:53]
	v_mfma_f32_16x16x32_bf16 v[38:41], v[162:165], v[186:189], v[38:41]
	v_mfma_f32_16x16x32_bf16 v[34:37], v[170:173], v[186:189], v[34:37]
	v_mfma_f32_16x16x32_bf16 v[22:25], v[162:165], v[194:197], v[22:25]
	v_mfma_f32_16x16x32_bf16 v[18:21], v[170:173], v[194:197], v[18:21]
	v_mfma_f32_16x16x32_bf16 v[6:9], v[162:165], v[204:207], v[6:9]
	v_mfma_f32_16x16x32_bf16 v[2:5], v[170:173], v[204:207], v[2:5]
	s_setprio 0
	s_barrier
	s_cbranch_scc0 .LBB0_2172
	s_and_b64 vcc, exec, s[10:11]
	s_cbranch_vccnz .LBB0_2160
	v_mov_b32_e32 v2, 0
	s_mov_b32 s45, s57
	s_mov_b32 s17, s58
	s_mov_b64 s[20:21], s[24:25]
	s_mov_b64 s[22:23], s[12:13]
	s_mov_b32 s56, s59
	v_mov_b32_e32 v3, v2
	v_mov_b32_e32 v4, v2
	v_mov_b32_e32 v5, v2
	v_mov_b32_e32 v6, v2
	v_mov_b32_e32 v7, v2
	v_mov_b32_e32 v8, v2
	v_mov_b32_e32 v9, v2
	v_mov_b32_e32 v18, v2
	v_mov_b32_e32 v19, v2
	v_mov_b32_e32 v20, v2
	v_mov_b32_e32 v21, v2
	v_mov_b32_e32 v22, v2
	v_mov_b32_e32 v23, v2
	v_mov_b32_e32 v24, v2
	v_mov_b32_e32 v25, v2
	v_mov_b32_e32 v34, v2
	v_mov_b32_e32 v35, v2
	v_mov_b32_e32 v36, v2
	v_mov_b32_e32 v37, v2
	v_mov_b32_e32 v38, v2
	v_mov_b32_e32 v39, v2
	v_mov_b32_e32 v40, v2
	v_mov_b32_e32 v41, v2
	v_mov_b32_e32 v50, v2
	v_mov_b32_e32 v51, v2
	v_mov_b32_e32 v52, v2
	v_mov_b32_e32 v53, v2
	v_mov_b32_e32 v54, v2
	v_mov_b32_e32 v55, v2
	v_mov_b32_e32 v56, v2
	v_mov_b32_e32 v57, v2
	v_mov_b32_e32 v10, v2
	v_mov_b32_e32 v11, v2
	v_mov_b32_e32 v12, v2
	v_mov_b32_e32 v13, v2
	v_mov_b32_e32 v14, v2
	v_mov_b32_e32 v15, v2
	v_mov_b32_e32 v16, v2
	v_mov_b32_e32 v17, v2
	v_mov_b32_e32 v26, v2
	v_mov_b32_e32 v27, v2
	v_mov_b32_e32 v28, v2
	v_mov_b32_e32 v29, v2
	v_mov_b32_e32 v30, v2
	v_mov_b32_e32 v31, v2
	v_mov_b32_e32 v32, v2
	v_mov_b32_e32 v33, v2
	v_mov_b32_e32 v42, v2
	v_mov_b32_e32 v43, v2
	v_mov_b32_e32 v44, v2
	v_mov_b32_e32 v45, v2
	v_mov_b32_e32 v46, v2
	v_mov_b32_e32 v47, v2
	v_mov_b32_e32 v48, v2
	v_mov_b32_e32 v49, v2
	v_mov_b32_e32 v58, v2
	v_mov_b32_e32 v59, v2
	v_mov_b32_e32 v60, v2
	v_mov_b32_e32 v61, v2
	v_mov_b32_e32 v62, v2
	v_mov_b32_e32 v63, v2
	v_mov_b32_e32 v64, v2
	v_mov_b32_e32 v65, v2
	v_mov_b32_e32 v66, v2
	v_mov_b32_e32 v67, v2
	v_mov_b32_e32 v68, v2
	v_mov_b32_e32 v69, v2
	v_mov_b32_e32 v70, v2
	v_mov_b32_e32 v71, v2
	v_mov_b32_e32 v72, v2
	v_mov_b32_e32 v73, v2
	v_mov_b32_e32 v82, v2
	v_mov_b32_e32 v83, v2
	v_mov_b32_e32 v84, v2
	v_mov_b32_e32 v85, v2
	v_mov_b32_e32 v86, v2
	v_mov_b32_e32 v87, v2
	v_mov_b32_e32 v88, v2
	v_mov_b32_e32 v89, v2
	v_mov_b32_e32 v98, v2
	v_mov_b32_e32 v99, v2
	v_mov_b32_e32 v100, v2
	v_mov_b32_e32 v101, v2
	v_mov_b32_e32 v102, v2
	v_mov_b32_e32 v103, v2
	v_mov_b32_e32 v104, v2
	v_mov_b32_e32 v105, v2
	v_mov_b32_e32 v114, v2
	v_mov_b32_e32 v115, v2
	v_mov_b32_e32 v116, v2
	v_mov_b32_e32 v117, v2
	v_mov_b32_e32 v118, v2
	v_mov_b32_e32 v119, v2
	v_mov_b32_e32 v120, v2
	v_mov_b32_e32 v121, v2
	v_mov_b32_e32 v74, v2
	v_mov_b32_e32 v75, v2
	v_mov_b32_e32 v76, v2
	v_mov_b32_e32 v77, v2
	v_mov_b32_e32 v78, v2
	v_mov_b32_e32 v79, v2
	v_mov_b32_e32 v80, v2
	v_mov_b32_e32 v81, v2
	v_mov_b32_e32 v90, v2
	v_mov_b32_e32 v91, v2
	v_mov_b32_e32 v92, v2
	v_mov_b32_e32 v93, v2
	v_mov_b32_e32 v94, v2
	v_mov_b32_e32 v95, v2
	v_mov_b32_e32 v96, v2
	v_mov_b32_e32 v97, v2
	v_mov_b32_e32 v106, v2
	v_mov_b32_e32 v107, v2
	v_mov_b32_e32 v108, v2
	v_mov_b32_e32 v109, v2
	v_mov_b32_e32 v110, v2
	v_mov_b32_e32 v111, v2
	v_mov_b32_e32 v112, v2
	v_mov_b32_e32 v113, v2
	v_mov_b32_e32 v122, v2
	v_mov_b32_e32 v123, v2
	v_mov_b32_e32 v124, v2
	v_mov_b32_e32 v125, v2
	v_mov_b32_e32 v126, v2
	v_mov_b32_e32 v127, v2
	v_mov_b32_e32 v128, v2
	v_mov_b32_e32 v129, v2
	s_branch .LBB0_2160
